# K-loop heads placed at byte phase 8 mod 64 (dead padding behind the branch that precedes each loop head); cold zero-init stubs moved next to their loops
# speedup vs baseline: 1.0120x; 1.0016x over previous
; #define PG8_STAGE(bufoff, gbase, voff) do { const __amdgpu_buffer_rsrc_t _r = __builtin_amdgcn_make_buffer_rsrc((void*)(gbase), (short)0, 0x7fffffff, 0x00020000); _Pragma("unroll") for (int _i = 0; _i < 2; ++_i) \
;         __builtin_amdgcn_raw_ptr_buffer_load_lds(_r, (LAS unsigned*)(lds + (bufoff) + ldsw + _i * 8192), 16, (int)(voff)[_i], 0, 0, 0); } while (0)
; #define PG8_LDA(dst, b, h) do { _Pragma("unroll") for (int m = 0; m < 4; ++m) _Pragma("unroll") for (int k = 0; k < 2; ++k) dst[m][k] = *(const LAS bf16x8*)(lds + PG8_SA(b, h) + aoff + m * 2048 + k * 1024); } while (0)
; #define PG8_LDB(dst, b, h) do { _Pragma("unroll") for (int n = 0; n < 2; ++n) _Pragma("unroll") for (int k = 0; k < 2; ++k) dst[n][k] = *(const LAS bf16x8*)(lds + PG8_SB(b, h) + boff + n * 2048 + k * 1024); } while (0)
; #define PG8_MMA(ai, bj, At, Bt) do { __builtin_amdgcn_s_setprio(1); _Pragma("unroll") for (int k = 0; k < 2; ++k) _Pragma("unroll") for (int m = 0; m < 4; ++m) _Pragma("unroll") for (int n = 0; n < ((bj) == 1 ? NB1 : 2); ++n) \
;         acc[ai][bj][m][n] = __builtin_amdgcn_mfma_f32_16x16x32_bf16(Bt[n][k], At[m][k], acc[ai][bj][m][n], 0, 0, 0); __builtin_amdgcn_s_setprio(0); } while (0)
; #define PG8_WAIT_V(n) asm volatile("s_waitcnt vmcnt(" #n ")" ::: "memory")
; #define PG8_WAIT_L(n) asm volatile("s_waitcnt lgkmcnt(" #n ")" ::: "memory")
; #define PG8_BAR __builtin_amdgcn_s_barrier()
; #define PG8_SCHED __builtin_amdgcn_sched_barrier(0)
;     ...
;             PG8_LDB(B0, 0, 0); PG8_SCHED; PG8_LDA(At, 0, 0); PG8_STAGE(PG8_SA(1, 1), a1 + hstepA, voffA);
;             PG8_WAIT_L(8); PG8_BAR; PG8_WAIT_L(0); PG8_MMA(0, 0, At, B0); PG8_BAR; PG8_SCHED;
;             PG8_LDB(B1, 0, 1); PG8_STAGE(PG8_SB(0, 0), b2, voffB);
;             PG8_BAR; PG8_WAIT_L(0); PG8_MMA(0, 1, At, B1); PG8_BAR;
;             PG8_LDA(At, 0, 1); PG8_STAGE(PG8_SA(0, 0), a2, voffA);
;             PG8_BAR; PG8_WAIT_L(0); PG8_MMA(1, 0, At, B0); PG8_BAR; PG8_SCHED;
;             PG8_STAGE(PG8_SB(0, 1), b2 + hstepB, voffB);
;             PG8_WAIT_V(6); PG8_BAR; PG8_MMA(1, 1, At, B1); PG8_BAR;
.LBB0_505:
	s_andn2_b64 vcc, exec, s[52:53]
	s_cbranch_vccnz .Lkzero_507
	s_add_u32 s17, s36, 0x100
	s_addc_u32 s22, s37, 0
	s_add_u32 s8, s36, s6
	s_addc_u32 s9, s37, s7
	s_add_u32 s23, s8, 0x80
	s_addc_u32 s24, s9, 0
	s_mov_b32 s26, 0
	s_mov_b64 s[8:9], 0
	s_add_i32 s25, s26, 2
	s_add_u32 s72, s8, 0x100
	s_addc_u32 s73, s9, 0
	s_add_u32 s27, s17, s8
	ds_read_b128 v[76:79], v73
	ds_read_b128 v[80:83], v73 offset:1024
	ds_read_b128 v[84:87], v73 offset:2048
	ds_read_b128 v[88:91], v73 offset:3072
	s_addc_u32 s28, s22, s9
	s_cmp_eq_u32 s93, s26
	s_cselect_b32 s64, s58, s27
	s_cselect_b32 s26, s59, s28
	s_cselect_b32 s27, 0, s73
	s_cselect_b32 s28, 0, s72
	s_add_u32 s36, s64, 0x80
	s_addc_u32 s29, s26, 0
	s_add_u32 s44, s4, s28
	s_addc_u32 s27, s82, s27
	s_add_u32 s8, s23, s8
	s_addc_u32 s9, s24, s9
	s_and_b32 s9, s9, 0xffff
	s_mov_b32 m0, s31
	ds_read_b128 v[92:95], v74
	ds_read_b128 v[96:99], v74 offset:1024
	ds_read_b128 v[100:103], v74 offset:2048
	ds_read_b128 v[104:107], v74 offset:3072
	ds_read_b128 v[108:111], v74 offset:4096
	ds_read_b128 v[112:115], v74 offset:5120
	ds_read_b128 v[116:119], v74 offset:6144
	ds_read_b128 v[120:123], v74 offset:7168
	buffer_load_dwordx4 v67, s[8:11], 0 offen lds
	s_mov_b32 m0, s74
	s_nop 0
	buffer_load_dwordx4 v71, s[8:11], 0 offen lds
	s_waitcnt lgkmcnt(8)
	s_barrier
	s_waitcnt lgkmcnt(0)
	s_setprio 1
	s_waitcnt lgkmcnt(7)
	v_mfma_f32_16x16x32_bf16 v[60:63], v[76:79], v[92:95], 0
	v_mfma_f32_16x16x32_bf16 v[56:59], v[84:87], v[92:95], 0
	s_waitcnt lgkmcnt(5)
	v_mfma_f32_16x16x32_bf16 v[52:55], v[76:79], v[100:103], 0
	v_mfma_f32_16x16x32_bf16 v[48:51], v[84:87], v[100:103], 0
	s_waitcnt lgkmcnt(3)
	v_mfma_f32_16x16x32_bf16 v[44:47], v[76:79], v[108:111], 0
	v_mfma_f32_16x16x32_bf16 v[40:43], v[84:87], v[108:111], 0
	s_waitcnt lgkmcnt(1)
	v_mfma_f32_16x16x32_bf16 v[36:39], v[76:79], v[116:119], 0
	v_mfma_f32_16x16x32_bf16 v[32:35], v[84:87], v[116:119], 0
	v_mfma_f32_16x16x32_bf16 v[60:63], v[80:83], v[96:99], v[60:63]
	v_mfma_f32_16x16x32_bf16 v[56:59], v[88:91], v[96:99], v[56:59]
	v_mfma_f32_16x16x32_bf16 v[52:55], v[80:83], v[104:107], v[52:55]
	v_mfma_f32_16x16x32_bf16 v[48:51], v[88:91], v[104:107], v[48:51]
	v_mfma_f32_16x16x32_bf16 v[44:47], v[80:83], v[112:115], v[44:47]
	v_mfma_f32_16x16x32_bf16 v[40:43], v[88:91], v[112:115], v[40:43]
	s_waitcnt lgkmcnt(0)
	v_mfma_f32_16x16x32_bf16 v[36:39], v[80:83], v[120:123], v[36:39]
	v_mfma_f32_16x16x32_bf16 v[32:35], v[88:91], v[120:123], v[32:35]
	s_setprio 0
	s_barrier
	s_and_b32 s45, s27, 0xffff
	s_mov_b32 s46, s10
	s_mov_b32 s47, s11
	s_mov_b32 m0, s84
	s_nop 0
	buffer_load_dwordx4 v70, s[44:47], 0 offen lds
	s_mov_b32 m0, s86
	s_nop 0
	buffer_load_dwordx4 v72, s[44:47], 0 offen lds
	s_barrier
	s_waitcnt lgkmcnt(0)
	s_setprio 1
	s_setprio 0
	s_and_b32 s65, s26, 0xffff
	s_mov_b32 s66, s10
	s_mov_b32 s67, s11
	s_mov_b32 m0, s75
	s_barrier
	ds_read_b128 v[92:95], v74 offset:16384
	ds_read_b128 v[96:99], v74 offset:17408
	ds_read_b128 v[100:103], v74 offset:18432
	ds_read_b128 v[104:107], v74 offset:19456
	ds_read_b128 v[108:111], v74 offset:20480
	ds_read_b128 v[112:115], v74 offset:21504
	ds_read_b128 v[116:119], v74 offset:22528
	ds_read_b128 v[120:123], v74 offset:23552
	buffer_load_dwordx4 v67, s[64:67], 0 offen lds
	s_mov_b32 m0, s5
	s_nop 0
	buffer_load_dwordx4 v71, s[64:67], 0 offen lds
	s_barrier
	s_waitcnt lgkmcnt(0)
	s_setprio 1
	s_waitcnt lgkmcnt(7)
	v_mfma_f32_16x16x32_bf16 v[28:31], v[76:79], v[92:95], 0
	v_mfma_f32_16x16x32_bf16 v[24:27], v[84:87], v[92:95], 0
	s_waitcnt lgkmcnt(5)
	v_mfma_f32_16x16x32_bf16 v[20:23], v[76:79], v[100:103], 0
	v_mfma_f32_16x16x32_bf16 v[16:19], v[84:87], v[100:103], 0
	s_waitcnt lgkmcnt(3)
	v_mfma_f32_16x16x32_bf16 v[12:15], v[76:79], v[108:111], 0
	v_mfma_f32_16x16x32_bf16 v[8:11], v[84:87], v[108:111], 0
	s_waitcnt lgkmcnt(1)
	v_mfma_f32_16x16x32_bf16 v[4:7], v[76:79], v[116:119], 0
	v_mfma_f32_16x16x32_bf16 v[0:3], v[84:87], v[116:119], 0
	v_mfma_f32_16x16x32_bf16 v[28:31], v[80:83], v[96:99], v[28:31]
	v_mfma_f32_16x16x32_bf16 v[24:27], v[88:91], v[96:99], v[24:27]
	v_mfma_f32_16x16x32_bf16 v[20:23], v[80:83], v[104:107], v[20:23]
	v_mfma_f32_16x16x32_bf16 v[16:19], v[88:91], v[104:107], v[16:19]
	v_mfma_f32_16x16x32_bf16 v[12:15], v[80:83], v[112:115], v[12:15]
	v_mfma_f32_16x16x32_bf16 v[8:11], v[88:91], v[112:115], v[8:11]
	s_waitcnt lgkmcnt(0)
	v_mfma_f32_16x16x32_bf16 v[4:7], v[80:83], v[120:123], v[4:7]
	v_mfma_f32_16x16x32_bf16 v[0:3], v[88:91], v[120:123], v[0:3]
	s_setprio 0
	s_barrier
	s_add_u32 s8, s44, s50
	s_addc_u32 s28, s27, s51
	s_and_b32 s9, s28, 0xffff
	s_mov_b32 m0, s87
	s_nop 0
	buffer_load_dwordx4 v70, s[8:11], 0 offen lds
	s_mov_b32 m0, s89
	s_nop 0
	buffer_load_dwordx4 v72, s[8:11], 0 offen lds
	s_waitcnt vmcnt(6)
	s_barrier
	s_setprio 1
	s_setprio 0
	s_barrier
	s_branch .Lkmid_507
	.p2align 6
	s_nop 0
	s_nop 0

; #define PG8_STAGE(bufoff, gbase, voff) do { const __amdgpu_buffer_rsrc_t _r = __builtin_amdgcn_make_buffer_rsrc((void*)(gbase), (short)0, 0x7fffffff, 0x00020000); _Pragma("unroll") for (int _i = 0; _i < 2; ++_i) \
;         __builtin_amdgcn_raw_ptr_buffer_load_lds(_r, (LAS unsigned*)(lds + (bufoff) + ldsw + _i * 8192), 16, (int)(voff)[_i], 0, 0, 0); } while (0)
; #define PG8_LDA(dst, b, h) do { _Pragma("unroll") for (int m = 0; m < 4; ++m) _Pragma("unroll") for (int k = 0; k < 2; ++k) dst[m][k] = *(const LAS bf16x8*)(lds + PG8_SA(b, h) + aoff + m * 2048 + k * 1024); } while (0)
; #define PG8_LDB(dst, b, h) do { _Pragma("unroll") for (int n = 0; n < 2; ++n) _Pragma("unroll") for (int k = 0; k < 2; ++k) dst[n][k] = *(const LAS bf16x8*)(lds + PG8_SB(b, h) + boff + n * 2048 + k * 1024); } while (0)
; #define PG8_MMA(ai, bj, At, Bt) do { __builtin_amdgcn_s_setprio(1); _Pragma("unroll") for (int k = 0; k < 2; ++k) _Pragma("unroll") for (int m = 0; m < 4; ++m) _Pragma("unroll") for (int n = 0; n < ((bj) == 1 ? NB1 : 2); ++n) \
;         acc[ai][bj][m][n] = __builtin_amdgcn_mfma_f32_16x16x32_bf16(Bt[n][k], At[m][k], acc[ai][bj][m][n], 0, 0, 0); __builtin_amdgcn_s_setprio(0); } while (0)
; #define PG8_WAIT_L(n) asm volatile("s_waitcnt lgkmcnt(" #n ")" ::: "memory")
; #define PG8_BAR __builtin_amdgcn_s_barrier()
; #define PG8_SCHED __builtin_amdgcn_sched_barrier(0)
;     ...
;             PG8_LDB(B0, 0, 0); PG8_SCHED; PG8_LDA(At, 0, 0); PG8_STAGE(PG8_SA(1, 1), a1 + hstepA, voffA);
;             PG8_WAIT_L(8); PG8_BAR; PG8_WAIT_L(0); PG8_MMA(0, 0, At, B0); PG8_BAR; PG8_SCHED;
;             PG8_LDB(B1, 0, 1); PG8_STAGE(PG8_SB(0, 0), b2, voffB);
;             PG8_BAR; PG8_WAIT_L(0); PG8_MMA(0, 1, At, B1); PG8_BAR;
;             PG8_LDA(At, 0, 1); PG8_STAGE(PG8_SA(0, 0), a2, voffA);
;             PG8_BAR; PG8_WAIT_L(0); PG8_MMA(1, 0, At, B0); PG8_BAR; PG8_SCHED;
.LBB0_573:
	s_andn2_b64 vcc, exec, s[20:21]
	s_cbranch_vccnz .Lkzero_575
	s_add_u32 s45, s26, 0x100
	s_addc_u32 s47, s27, 0
	s_add_u32 s51, s24, 0x100
	s_addc_u32 s81, s25, 0
	s_mov_b32 s8, 0
	ds_read_b128 v[96:99], v215
	ds_read_b128 v[100:103], v215 offset:1024
	ds_read_b128 v[136:139], v215 offset:2048
	ds_read_b128 v[140:143], v215 offset:3072
	s_add_i32 s16, s8, 2
	s_cmp_eq_u32 s90, s8
	s_cselect_b32 s36, s42, s45
	s_cselect_b32 s23, s43, s47
	s_cselect_b32 s22, s1, s81
	s_cselect_b32 s28, s0, s51
	s_add_u32 s24, s36, 0x80
	s_addc_u32 s17, s23, 0
	s_add_u32 s8, s45, s6
	s_addc_u32 s9, s47, s7
	s_add_u32 s8, s8, 0xffffff80
	s_addc_u32 s9, s9, -1
	s_and_b32 s9, s9, 0xffff
	s_mov_b32 m0, s76
	ds_read_b128 v[144:147], v216
	ds_read_b128 v[148:151], v216 offset:1024
	ds_read_b128 v[152:155], v216 offset:2048
	ds_read_b128 v[156:159], v216 offset:3072
	ds_read_b128 v[160:163], v216 offset:4096
	ds_read_b128 v[164:167], v216 offset:5120
	ds_read_b128 v[168:171], v216 offset:6144
	ds_read_b128 v[172:175], v216 offset:7168
	buffer_load_dwordx4 v210, s[8:11], 0 offen lds
	s_mov_b32 m0, s77
	s_nop 0
	buffer_load_dwordx4 v212, s[8:11], 0 offen lds
	s_waitcnt lgkmcnt(8)
	s_barrier
	s_waitcnt lgkmcnt(0)
	s_setprio 1
	s_waitcnt lgkmcnt(7)
	v_mfma_f32_16x16x32_bf16 v[132:135], v[96:99], v[144:147], 0
	v_mfma_f32_16x16x32_bf16 v[120:123], v[136:139], v[144:147], 0
	s_waitcnt lgkmcnt(5)
	v_mfma_f32_16x16x32_bf16 v[116:119], v[96:99], v[152:155], 0
	v_mfma_f32_16x16x32_bf16 v[112:115], v[136:139], v[152:155], 0
	s_waitcnt lgkmcnt(3)
	v_mfma_f32_16x16x32_bf16 v[92:95], v[96:99], v[160:163], 0
	v_mfma_f32_16x16x32_bf16 v[88:91], v[136:139], v[160:163], 0
	s_waitcnt lgkmcnt(1)
	v_mfma_f32_16x16x32_bf16 v[76:79], v[96:99], v[168:171], 0
	v_mfma_f32_16x16x32_bf16 v[72:75], v[136:139], v[168:171], 0
	v_mfma_f32_16x16x32_bf16 v[132:135], v[100:103], v[148:151], v[132:135]
	v_mfma_f32_16x16x32_bf16 v[120:123], v[140:143], v[148:151], v[120:123]
	v_mfma_f32_16x16x32_bf16 v[116:119], v[100:103], v[156:159], v[116:119]
	v_mfma_f32_16x16x32_bf16 v[112:115], v[140:143], v[156:159], v[112:115]
	v_mfma_f32_16x16x32_bf16 v[92:95], v[100:103], v[164:167], v[92:95]
	v_mfma_f32_16x16x32_bf16 v[88:91], v[140:143], v[164:167], v[88:91]
	s_waitcnt lgkmcnt(0)
	v_mfma_f32_16x16x32_bf16 v[76:79], v[100:103], v[172:175], v[76:79]
	v_mfma_f32_16x16x32_bf16 v[72:75], v[140:143], v[172:175], v[72:75]
	s_setprio 0
	s_barrier
	s_and_b32 s29, s22, 0xffff
	s_mov_b32 s30, s10
	s_mov_b32 s31, s11
	s_mov_b32 m0, s15
	ds_read_b128 v[176:179], v217
	ds_read_b128 v[194:197], v217 offset:1024
	ds_read_b128 v[198:201], v217 offset:2048
	ds_read_b128 v[202:205], v217 offset:3072
	buffer_load_dwordx4 v211, s[28:31], 0 offen lds
	s_mov_b32 m0, s33
	s_nop 0
	buffer_load_dwordx4 v213, s[28:31], 0 offen lds
	s_barrier
	s_waitcnt lgkmcnt(0)
	s_setprio 1
	s_waitcnt lgkmcnt(3)
	v_mfma_f32_16x16x32_bf16 v[128:131], v[176:179], v[144:147], 0
	s_waitcnt lgkmcnt(1)
	v_mfma_f32_16x16x32_bf16 v[124:127], v[198:201], v[144:147], 0
	v_mfma_f32_16x16x32_bf16 v[108:111], v[176:179], v[152:155], 0
	v_mfma_f32_16x16x32_bf16 v[104:107], v[198:201], v[152:155], 0
	v_mfma_f32_16x16x32_bf16 v[84:87], v[176:179], v[160:163], 0
	v_mfma_f32_16x16x32_bf16 v[80:83], v[198:201], v[160:163], 0
	v_mfma_f32_16x16x32_bf16 v[68:71], v[176:179], v[168:171], 0
	v_mfma_f32_16x16x32_bf16 v[64:67], v[198:201], v[168:171], 0
	v_mfma_f32_16x16x32_bf16 v[128:131], v[194:197], v[148:151], v[128:131]
	s_waitcnt lgkmcnt(0)
	v_mfma_f32_16x16x32_bf16 v[124:127], v[202:205], v[148:151], v[124:127]
	v_mfma_f32_16x16x32_bf16 v[108:111], v[194:197], v[156:159], v[108:111]
	v_mfma_f32_16x16x32_bf16 v[104:107], v[202:205], v[156:159], v[104:107]
	v_mfma_f32_16x16x32_bf16 v[84:87], v[194:197], v[164:167], v[84:87]
	v_mfma_f32_16x16x32_bf16 v[80:83], v[202:205], v[164:167], v[80:83]
	v_mfma_f32_16x16x32_bf16 v[68:71], v[194:197], v[172:175], v[68:71]
	v_mfma_f32_16x16x32_bf16 v[64:67], v[202:205], v[172:175], v[64:67]
	s_setprio 0
	s_and_b32 s37, s23, 0xffff
	s_mov_b32 s38, s10
	s_mov_b32 s39, s11
	s_mov_b32 m0, s14
	s_barrier
; #define PG8_STAGE(bufoff, gbase, voff) do { const __amdgpu_buffer_rsrc_t _r = __builtin_amdgcn_make_buffer_rsrc((void*)(gbase), (short)0, 0x7fffffff, 0x00020000); _Pragma("unroll") for (int _i = 0; _i < 2; ++_i) \
;         __builtin_amdgcn_raw_ptr_buffer_load_lds(_r, (LAS unsigned*)(lds + (bufoff) + ldsw + _i * 8192), 16, (int)(voff)[_i], 0, 0, 0); } while (0)
; #define PG8_LDA(dst, b, h) do { _Pragma("unroll") for (int m = 0; m < 4; ++m) _Pragma("unroll") for (int k = 0; k < 2; ++k) dst[m][k] = *(const LAS bf16x8*)(lds + PG8_SA(b, h) + aoff + m * 2048 + k * 1024); } while (0)
; #define PG8_MMA(ai, bj, At, Bt) do { __builtin_amdgcn_s_setprio(1); _Pragma("unroll") for (int k = 0; k < 2; ++k) _Pragma("unroll") for (int m = 0; m < 4; ++m) _Pragma("unroll") for (int n = 0; n < ((bj) == 1 ? NB1 : 2); ++n) \
;         acc[ai][bj][m][n] = __builtin_amdgcn_mfma_f32_16x16x32_bf16(Bt[n][k], At[m][k], acc[ai][bj][m][n], 0, 0, 0); __builtin_amdgcn_s_setprio(0); } while (0)
; #define PG8_WAIT_V(n) asm volatile("s_waitcnt vmcnt(" #n ")" ::: "memory")
; #define PG8_WAIT_L(n) asm volatile("s_waitcnt lgkmcnt(" #n ")" ::: "memory")
; #define PG8_BAR __builtin_amdgcn_s_barrier()
; #define PG8_SCHED __builtin_amdgcn_sched_barrier(0)
;     ...
;             PG8_LDA(At, 0, 1); PG8_STAGE(PG8_SA(0, 0), a2, voffA);
;             PG8_BAR; PG8_WAIT_L(0); PG8_MMA(1, 0, At, B0); PG8_BAR; PG8_SCHED;
;             PG8_STAGE(PG8_SB(0, 1), b2 + hstepB, voffB);
;             PG8_WAIT_V(6); PG8_BAR; PG8_MMA(1, 1, At, B1); PG8_BAR;
	ds_read_b128 v[144:147], v216 offset:16384
	ds_read_b128 v[148:151], v216 offset:17408
	ds_read_b128 v[152:155], v216 offset:18432
	ds_read_b128 v[156:159], v216 offset:19456
	ds_read_b128 v[160:163], v216 offset:20480
	ds_read_b128 v[164:167], v216 offset:21504
	ds_read_b128 v[168:171], v216 offset:22528
	ds_read_b128 v[172:175], v216 offset:23552
	buffer_load_dwordx4 v210, s[36:39], 0 offen lds
	s_mov_b32 m0, s35
	s_nop 0
	buffer_load_dwordx4 v212, s[36:39], 0 offen lds
	s_barrier
	s_waitcnt lgkmcnt(0)
	s_setprio 1
	s_waitcnt lgkmcnt(7)
	v_mfma_f32_16x16x32_bf16 v[60:63], v[96:99], v[144:147], 0
	v_mfma_f32_16x16x32_bf16 v[56:59], v[136:139], v[144:147], 0
	s_waitcnt lgkmcnt(5)
	v_mfma_f32_16x16x32_bf16 v[44:47], v[96:99], v[152:155], 0
	v_mfma_f32_16x16x32_bf16 v[40:43], v[136:139], v[152:155], 0
	s_waitcnt lgkmcnt(3)
	v_mfma_f32_16x16x32_bf16 v[28:31], v[96:99], v[160:163], 0
	v_mfma_f32_16x16x32_bf16 v[24:27], v[136:139], v[160:163], 0
	s_waitcnt lgkmcnt(1)
	v_mfma_f32_16x16x32_bf16 v[12:15], v[96:99], v[168:171], 0
	v_mfma_f32_16x16x32_bf16 v[8:11], v[136:139], v[168:171], 0
	v_mfma_f32_16x16x32_bf16 v[60:63], v[100:103], v[148:151], v[60:63]
	v_mfma_f32_16x16x32_bf16 v[56:59], v[140:143], v[148:151], v[56:59]
	v_mfma_f32_16x16x32_bf16 v[44:47], v[100:103], v[156:159], v[44:47]
	v_mfma_f32_16x16x32_bf16 v[40:43], v[140:143], v[156:159], v[40:43]
	v_mfma_f32_16x16x32_bf16 v[28:31], v[100:103], v[164:167], v[28:31]
	v_mfma_f32_16x16x32_bf16 v[24:27], v[140:143], v[164:167], v[24:27]
	s_waitcnt lgkmcnt(0)
	v_mfma_f32_16x16x32_bf16 v[12:15], v[100:103], v[172:175], v[12:15]
	v_mfma_f32_16x16x32_bf16 v[8:11], v[140:143], v[172:175], v[8:11]
	s_setprio 0
	s_barrier
	s_add_u32 s8, s28, s18
	s_addc_u32 s82, s22, s19
	s_and_b32 s9, s82, 0xffff
	s_mov_b32 m0, s52
	s_nop 0
	buffer_load_dwordx4 v211, s[8:11], 0 offen lds
	s_mov_b32 m0, s53
	s_nop 0
	buffer_load_dwordx4 v213, s[8:11], 0 offen lds
	s_waitcnt vmcnt(6)
	s_barrier
	s_setprio 1
	v_mfma_f32_16x16x32_bf16 v[52:55], v[176:179], v[144:147], 0
	v_mfma_f32_16x16x32_bf16 v[48:51], v[198:201], v[144:147], 0
	v_mfma_f32_16x16x32_bf16 v[36:39], v[176:179], v[152:155], 0
	v_mfma_f32_16x16x32_bf16 v[32:35], v[198:201], v[152:155], 0
	v_mfma_f32_16x16x32_bf16 v[20:23], v[176:179], v[160:163], 0
	v_mfma_f32_16x16x32_bf16 v[16:19], v[198:201], v[160:163], 0
	v_mfma_f32_16x16x32_bf16 v[4:7], v[176:179], v[168:171], 0
	v_mfma_f32_16x16x32_bf16 v[0:3], v[198:201], v[168:171], 0
	v_mfma_f32_16x16x32_bf16 v[52:55], v[194:197], v[148:151], v[52:55]
	v_mfma_f32_16x16x32_bf16 v[48:51], v[202:205], v[148:151], v[48:51]
	v_mfma_f32_16x16x32_bf16 v[36:39], v[194:197], v[156:159], v[36:39]
	v_mfma_f32_16x16x32_bf16 v[32:35], v[202:205], v[156:159], v[32:35]
	v_mfma_f32_16x16x32_bf16 v[20:23], v[194:197], v[164:167], v[20:23]
	v_mfma_f32_16x16x32_bf16 v[16:19], v[202:205], v[164:167], v[16:19]
	v_mfma_f32_16x16x32_bf16 v[4:7], v[194:197], v[172:175], v[4:7]
	v_mfma_f32_16x16x32_bf16 v[0:3], v[202:205], v[172:175], v[0:3]
	s_setprio 0
	s_barrier
	s_branch .Lkmid_575
	.p2align 6
	s_nop 0
	s_nop 0

; #define PG8_STAGE(bufoff, gbase, voff) do { const __amdgpu_buffer_rsrc_t _r = __builtin_amdgcn_make_buffer_rsrc((void*)(gbase), (short)0, 0x7fffffff, 0x00020000); _Pragma("unroll") for (int _i = 0; _i < 2; ++_i) \
;         __builtin_amdgcn_raw_ptr_buffer_load_lds(_r, (LAS unsigned*)(lds + (bufoff) + ldsw + _i * 8192), 16, (int)(voff)[_i], 0, 0, 0); } while (0)
; #define PG8_LDA(dst, b, h) do { _Pragma("unroll") for (int m = 0; m < 4; ++m) _Pragma("unroll") for (int k = 0; k < 2; ++k) dst[m][k] = *(const LAS bf16x8*)(lds + PG8_SA(b, h) + aoff + m * 2048 + k * 1024); } while (0)
; #define PG8_LDB(dst, b, h) do { _Pragma("unroll") for (int n = 0; n < 2; ++n) _Pragma("unroll") for (int k = 0; k < 2; ++k) dst[n][k] = *(const LAS bf16x8*)(lds + PG8_SB(b, h) + boff + n * 2048 + k * 1024); } while (0)
; #define PG8_MMA(ai, bj, At, Bt) do { __builtin_amdgcn_s_setprio(1); _Pragma("unroll") for (int k = 0; k < 2; ++k) _Pragma("unroll") for (int m = 0; m < 4; ++m) _Pragma("unroll") for (int n = 0; n < ((bj) == 1 ? NB1 : 2); ++n) \
;         acc[ai][bj][m][n] = __builtin_amdgcn_mfma_f32_16x16x32_bf16(Bt[n][k], At[m][k], acc[ai][bj][m][n], 0, 0, 0); __builtin_amdgcn_s_setprio(0); } while (0)
; #define PG8_WAIT_L(n) asm volatile("s_waitcnt lgkmcnt(" #n ")" ::: "memory")
; #define PG8_BAR __builtin_amdgcn_s_barrier()
; #define PG8_SCHED __builtin_amdgcn_sched_barrier(0)
;     ...
;             PG8_LDB(B0, 1, 0); PG8_SCHED; PG8_LDA(At, 1, 0); PG8_STAGE(PG8_SA(0, 1), a2 + hstepA, voffA);
;             PG8_WAIT_L(8); PG8_BAR; PG8_WAIT_L(0); PG8_MMA(0, 0, At, B0); PG8_BAR; PG8_SCHED;
;             PG8_LDB(B1, 1, 1); PG8_STAGE(PG8_SB(1, 0), b3, voffB);
;             PG8_BAR; PG8_WAIT_L(0); PG8_MMA(0, 1, At, B1); PG8_BAR;
;             PG8_LDA(At, 1, 1); PG8_STAGE(PG8_SA(1, 0), a3, voffA);
;             PG8_BAR; PG8_WAIT_L(0); PG8_MMA(1, 0, At, B0); PG8_BAR; PG8_SCHED;
;             PG8_STAGE(PG8_SB(1, 1), b3 + hstepB, voffB);
.Lkmid_575:
	ds_read_b128 v[96:99], v218
	ds_read_b128 v[100:103], v218 offset:1024
	ds_read_b128 v[136:139], v218 offset:2048
	ds_read_b128 v[140:143], v218 offset:3072
	s_add_u32 s36, s36, s6
	s_addc_u32 s9, s23, s7
	s_and_b32 s37, s9, 0xffff
	s_mov_b32 m0, s58
	ds_read_b128 v[144:147], v216 offset:32768
	ds_read_b128 v[148:151], v216 offset:33792
	ds_read_b128 v[152:155], v216 offset:34816
	ds_read_b128 v[156:159], v216 offset:35840
	ds_read_b128 v[160:163], v216 offset:36864
	ds_read_b128 v[164:167], v216 offset:37888
	ds_read_b128 v[168:171], v216 offset:38912
	ds_read_b128 v[172:175], v216 offset:39936
	buffer_load_dwordx4 v210, s[36:39], 0 offen lds
	s_mov_b32 m0, s59
	s_nop 0
	buffer_load_dwordx4 v212, s[36:39], 0 offen lds
	s_waitcnt lgkmcnt(8)
	s_barrier
	s_waitcnt lgkmcnt(0)
	s_setprio 1
	s_waitcnt lgkmcnt(7)
	v_mfma_f32_16x16x32_bf16 v[132:135], v[96:99], v[144:147], v[132:135]
	v_mfma_f32_16x16x32_bf16 v[120:123], v[136:139], v[144:147], v[120:123]
	s_waitcnt lgkmcnt(5)
	v_mfma_f32_16x16x32_bf16 v[116:119], v[96:99], v[152:155], v[116:119]
	v_mfma_f32_16x16x32_bf16 v[112:115], v[136:139], v[152:155], v[112:115]
	s_waitcnt lgkmcnt(3)
	v_mfma_f32_16x16x32_bf16 v[92:95], v[96:99], v[160:163], v[92:95]
	v_mfma_f32_16x16x32_bf16 v[88:91], v[136:139], v[160:163], v[88:91]
	s_waitcnt lgkmcnt(1)
	v_mfma_f32_16x16x32_bf16 v[76:79], v[96:99], v[168:171], v[76:79]
	v_mfma_f32_16x16x32_bf16 v[72:75], v[136:139], v[168:171], v[72:75]
	v_mfma_f32_16x16x32_bf16 v[132:135], v[100:103], v[148:151], v[132:135]
	v_mfma_f32_16x16x32_bf16 v[120:123], v[140:143], v[148:151], v[120:123]
	v_mfma_f32_16x16x32_bf16 v[116:119], v[100:103], v[156:159], v[116:119]
	v_mfma_f32_16x16x32_bf16 v[112:115], v[140:143], v[156:159], v[112:115]
	v_mfma_f32_16x16x32_bf16 v[92:95], v[100:103], v[164:167], v[92:95]
	v_mfma_f32_16x16x32_bf16 v[88:91], v[140:143], v[164:167], v[88:91]
	s_waitcnt lgkmcnt(0)
	v_mfma_f32_16x16x32_bf16 v[76:79], v[100:103], v[172:175], v[76:79]
	v_mfma_f32_16x16x32_bf16 v[72:75], v[140:143], v[172:175], v[72:75]
	s_setprio 0
	s_barrier
	s_add_u32 s28, s28, 0x80
	s_addc_u32 s9, s22, 0
	s_and_b32 s29, s9, 0xffff
	s_mov_b32 m0, s48
	ds_read_b128 v[176:179], v219
	ds_read_b128 v[194:197], v219 offset:1024
	ds_read_b128 v[198:201], v219 offset:2048
	ds_read_b128 v[202:205], v219 offset:3072
	buffer_load_dwordx4 v211, s[28:31], 0 offen lds
	s_mov_b32 m0, s49
	s_nop 0
	buffer_load_dwordx4 v213, s[28:31], 0 offen lds
	s_barrier
	s_waitcnt lgkmcnt(0)
	s_setprio 1
	s_waitcnt lgkmcnt(3)
	v_mfma_f32_16x16x32_bf16 v[128:131], v[176:179], v[144:147], v[128:131]
	s_waitcnt lgkmcnt(1)
	v_mfma_f32_16x16x32_bf16 v[124:127], v[198:201], v[144:147], v[124:127]
	v_mfma_f32_16x16x32_bf16 v[108:111], v[176:179], v[152:155], v[108:111]
	v_mfma_f32_16x16x32_bf16 v[104:107], v[198:201], v[152:155], v[104:107]
	v_mfma_f32_16x16x32_bf16 v[84:87], v[176:179], v[160:163], v[84:87]
	v_mfma_f32_16x16x32_bf16 v[80:83], v[198:201], v[160:163], v[80:83]
	v_mfma_f32_16x16x32_bf16 v[68:71], v[176:179], v[168:171], v[68:71]
	v_mfma_f32_16x16x32_bf16 v[64:67], v[198:201], v[168:171], v[64:67]
	v_mfma_f32_16x16x32_bf16 v[128:131], v[194:197], v[148:151], v[128:131]
	s_waitcnt lgkmcnt(0)
	v_mfma_f32_16x16x32_bf16 v[124:127], v[202:205], v[148:151], v[124:127]
	v_mfma_f32_16x16x32_bf16 v[108:111], v[194:197], v[156:159], v[108:111]
	v_mfma_f32_16x16x32_bf16 v[104:107], v[202:205], v[156:159], v[104:107]
	v_mfma_f32_16x16x32_bf16 v[84:87], v[194:197], v[164:167], v[84:87]
	v_mfma_f32_16x16x32_bf16 v[80:83], v[202:205], v[164:167], v[80:83]
	v_mfma_f32_16x16x32_bf16 v[68:71], v[194:197], v[172:175], v[68:71]
	v_mfma_f32_16x16x32_bf16 v[64:67], v[202:205], v[172:175], v[64:67]
	s_setprio 0
	s_and_b32 s25, s17, 0xffff
	s_mov_b32 s26, s10
	s_mov_b32 s27, s11
	s_mov_b32 m0, s83
	s_barrier
	ds_read_b128 v[144:147], v216 offset:49152
	ds_read_b128 v[148:151], v216 offset:50176
	ds_read_b128 v[152:155], v216 offset:51200
	ds_read_b128 v[156:159], v216 offset:52224
	ds_read_b128 v[160:163], v216 offset:53248
	ds_read_b128 v[164:167], v216 offset:54272
	ds_read_b128 v[168:171], v216 offset:55296
	ds_read_b128 v[172:175], v216 offset:56320
	buffer_load_dwordx4 v210, s[24:27], 0 offen lds
	s_mov_b32 m0, s84
	s_nop 0
	buffer_load_dwordx4 v212, s[24:27], 0 offen lds
	s_barrier
	s_waitcnt lgkmcnt(0)
	s_setprio 1
	s_waitcnt lgkmcnt(7)
	v_mfma_f32_16x16x32_bf16 v[60:63], v[96:99], v[144:147], v[60:63]
	v_mfma_f32_16x16x32_bf16 v[56:59], v[136:139], v[144:147], v[56:59]
	s_waitcnt lgkmcnt(5)
	v_mfma_f32_16x16x32_bf16 v[44:47], v[96:99], v[152:155], v[44:47]
	v_mfma_f32_16x16x32_bf16 v[40:43], v[136:139], v[152:155], v[40:43]
	s_waitcnt lgkmcnt(3)
	v_mfma_f32_16x16x32_bf16 v[28:31], v[96:99], v[160:163], v[28:31]
	v_mfma_f32_16x16x32_bf16 v[24:27], v[136:139], v[160:163], v[24:27]
	s_waitcnt lgkmcnt(1)
	v_mfma_f32_16x16x32_bf16 v[12:15], v[96:99], v[168:171], v[12:15]
	v_mfma_f32_16x16x32_bf16 v[8:11], v[136:139], v[168:171], v[8:11]
	v_mfma_f32_16x16x32_bf16 v[60:63], v[100:103], v[148:151], v[60:63]
	v_mfma_f32_16x16x32_bf16 v[56:59], v[140:143], v[148:151], v[56:59]
	v_mfma_f32_16x16x32_bf16 v[44:47], v[100:103], v[156:159], v[44:47]
	v_mfma_f32_16x16x32_bf16 v[40:43], v[140:143], v[156:159], v[40:43]
	v_mfma_f32_16x16x32_bf16 v[28:31], v[100:103], v[164:167], v[28:31]
	v_mfma_f32_16x16x32_bf16 v[24:27], v[140:143], v[164:167], v[24:27]
	s_waitcnt lgkmcnt(0)
	v_mfma_f32_16x16x32_bf16 v[12:15], v[100:103], v[172:175], v[12:15]
	v_mfma_f32_16x16x32_bf16 v[8:11], v[140:143], v[172:175], v[8:11]
	s_setprio 0
	s_barrier
; #define PG8_STAGE(bufoff, gbase, voff) do { const __amdgpu_buffer_rsrc_t _r = __builtin_amdgcn_make_buffer_rsrc((void*)(gbase), (short)0, 0x7fffffff, 0x00020000); _Pragma("unroll") for (int _i = 0; _i < 2; ++_i) \
;         __builtin_amdgcn_raw_ptr_buffer_load_lds(_r, (LAS unsigned*)(lds + (bufoff) + ldsw + _i * 8192), 16, (int)(voff)[_i], 0, 0, 0); } while (0)
; #define PG8_MMA(ai, bj, At, Bt) do { __builtin_amdgcn_s_setprio(1); _Pragma("unroll") for (int k = 0; k < 2; ++k) _Pragma("unroll") for (int m = 0; m < 4; ++m) _Pragma("unroll") for (int n = 0; n < ((bj) == 1 ? NB1 : 2); ++n) \
;         acc[ai][bj][m][n] = __builtin_amdgcn_mfma_f32_16x16x32_bf16(Bt[n][k], At[m][k], acc[ai][bj][m][n], 0, 0, 0); __builtin_amdgcn_s_setprio(0); } while (0)
; #define PG8_WAIT_V(n) asm volatile("s_waitcnt vmcnt(" #n ")" ::: "memory")
; #define PG8_BAR __builtin_amdgcn_s_barrier()
;     ...
;     f32x4 acc[2][2][4][2];
; #pragma unroll
;     for (int a = 0; a < 2; ++a)
; #pragma unroll
;         for (int b = 0; b < 2; ++b)
; #pragma unroll
;             for (int m = 0; m < 4; ++m)
; #pragma unroll
;                 for (int n = 0; n < 2; ++n) acc[a][b][m][n] = (f32x4){0.f, 0.f, 0.f, 0.f};
;     ...
;             PG8_STAGE(PG8_SB(1, 1), b3 + hstepB, voffB);
;             PG8_WAIT_V(6); PG8_BAR; PG8_MMA(1, 1, At, B1); PG8_BAR;
	s_add_u32 s8, s8, 0x80
	s_addc_u32 s9, s82, 0
	s_and_b32 s9, s9, 0xffff
	s_mov_b32 m0, s85
	s_nop 0
	buffer_load_dwordx4 v211, s[8:11], 0 offen lds
	s_mov_b32 m0, s86
	s_nop 0
	buffer_load_dwordx4 v213, s[8:11], 0 offen lds
	s_waitcnt vmcnt(6)
	s_barrier
	s_setprio 1
	v_mfma_f32_16x16x32_bf16 v[52:55], v[176:179], v[144:147], v[52:55]
	v_mfma_f32_16x16x32_bf16 v[48:51], v[198:201], v[144:147], v[48:51]
	v_mfma_f32_16x16x32_bf16 v[36:39], v[176:179], v[152:155], v[36:39]
	v_mfma_f32_16x16x32_bf16 v[32:35], v[198:201], v[152:155], v[32:35]
	v_mfma_f32_16x16x32_bf16 v[20:23], v[176:179], v[160:163], v[20:23]
	v_mfma_f32_16x16x32_bf16 v[16:19], v[198:201], v[160:163], v[16:19]
	v_mfma_f32_16x16x32_bf16 v[4:7], v[176:179], v[168:171], v[4:7]
	v_mfma_f32_16x16x32_bf16 v[0:3], v[198:201], v[168:171], v[0:3]
	v_mfma_f32_16x16x32_bf16 v[52:55], v[194:197], v[148:151], v[52:55]
	v_mfma_f32_16x16x32_bf16 v[48:51], v[202:205], v[148:151], v[48:51]
	v_mfma_f32_16x16x32_bf16 v[36:39], v[194:197], v[156:159], v[36:39]
	v_mfma_f32_16x16x32_bf16 v[32:35], v[202:205], v[156:159], v[32:35]
	v_mfma_f32_16x16x32_bf16 v[20:23], v[194:197], v[164:167], v[20:23]
	v_mfma_f32_16x16x32_bf16 v[16:19], v[202:205], v[164:167], v[16:19]
	v_mfma_f32_16x16x32_bf16 v[4:7], v[194:197], v[172:175], v[4:7]
	v_mfma_f32_16x16x32_bf16 v[0:3], v[202:205], v[172:175], v[0:3]
	s_setprio 0
	s_add_u32 s45, s45, 0x100
	s_addc_u32 s47, s47, 0
	s_add_u32 s51, s51, 0x100
	s_addc_u32 s81, s81, 0
	s_cmp_ge_i32 s16, s89
	s_mov_b32 s8, s16
	s_barrier
	s_cbranch_scc0 .LBB0_575
	s_branch .LBB0_568
.Lkzero_575:
	v_mov_b32_e32 v135, 0
	v_mov_b32_e32 v134, v135
	v_mov_b32_e32 v133, v135
	v_mov_b32_e32 v132, v135
	v_mov_b32_e32 v123, v135
	v_mov_b32_e32 v122, v135
	v_mov_b32_e32 v121, v135
	v_mov_b32_e32 v120, v135
	v_mov_b32_e32 v119, v135
	v_mov_b32_e32 v118, v135
	v_mov_b32_e32 v117, v135
	v_mov_b32_e32 v116, v135
	v_mov_b32_e32 v115, v135
	v_mov_b32_e32 v114, v135
	v_mov_b32_e32 v113, v135
	v_mov_b32_e32 v112, v135
	v_mov_b32_e32 v95, v135
	v_mov_b32_e32 v94, v135
	v_mov_b32_e32 v93, v135
	v_mov_b32_e32 v92, v135
	v_mov_b32_e32 v91, v135
	v_mov_b32_e32 v90, v135
	v_mov_b32_e32 v89, v135
	v_mov_b32_e32 v88, v135
	v_mov_b32_e32 v79, v135
	v_mov_b32_e32 v78, v135
	v_mov_b32_e32 v77, v135
	v_mov_b32_e32 v76, v135
	v_mov_b32_e32 v75, v135
	v_mov_b32_e32 v74, v135
	v_mov_b32_e32 v73, v135
	v_mov_b32_e32 v72, v135
	v_mov_b32_e32 v131, v135
	v_mov_b32_e32 v130, v135
	v_mov_b32_e32 v129, v135
	v_mov_b32_e32 v128, v135
	v_mov_b32_e32 v127, v135
	v_mov_b32_e32 v126, v135
	v_mov_b32_e32 v125, v135
	v_mov_b32_e32 v124, v135
	v_mov_b32_e32 v111, v135
	v_mov_b32_e32 v110, v135
	v_mov_b32_e32 v109, v135
	v_mov_b32_e32 v108, v135
	v_mov_b32_e32 v107, v135
	v_mov_b32_e32 v106, v135
	v_mov_b32_e32 v105, v135
	v_mov_b32_e32 v104, v135
	v_mov_b32_e32 v87, v135
	v_mov_b32_e32 v86, v135
	v_mov_b32_e32 v85, v135
	v_mov_b32_e32 v84, v135
	v_mov_b32_e32 v83, v135
	v_mov_b32_e32 v82, v135
	v_mov_b32_e32 v81, v135
	v_mov_b32_e32 v80, v135
	v_mov_b32_e32 v71, v135
	v_mov_b32_e32 v70, v135
	v_mov_b32_e32 v69, v135
	v_mov_b32_e32 v68, v135
	v_mov_b32_e32 v67, v135
	v_mov_b32_e32 v66, v135
	v_mov_b32_e32 v65, v135
	v_mov_b32_e32 v64, v135
	v_mov_b32_e32 v63, v135
	v_mov_b32_e32 v62, v135
	v_mov_b32_e32 v61, v135
	v_mov_b32_e32 v60, v135
	v_mov_b32_e32 v59, v135
	v_mov_b32_e32 v58, v135
	v_mov_b32_e32 v57, v135
	v_mov_b32_e32 v56, v135
	v_mov_b32_e32 v47, v135
	v_mov_b32_e32 v46, v135
	v_mov_b32_e32 v45, v135
	v_mov_b32_e32 v44, v135
	v_mov_b32_e32 v43, v135
	v_mov_b32_e32 v42, v135
	v_mov_b32_e32 v41, v135
	v_mov_b32_e32 v40, v135
	v_mov_b32_e32 v31, v135
	v_mov_b32_e32 v30, v135
	v_mov_b32_e32 v29, v135
	v_mov_b32_e32 v28, v135
	v_mov_b32_e32 v27, v135
	v_mov_b32_e32 v26, v135
	v_mov_b32_e32 v25, v135
	v_mov_b32_e32 v24, v135
	v_mov_b32_e32 v15, v135
	v_mov_b32_e32 v14, v135
	v_mov_b32_e32 v13, v135
	v_mov_b32_e32 v12, v135
	v_mov_b32_e32 v11, v135
	v_mov_b32_e32 v10, v135
	v_mov_b32_e32 v9, v135
	v_mov_b32_e32 v8, v135
	v_mov_b32_e32 v55, v135
	v_mov_b32_e32 v54, v135
	v_mov_b32_e32 v53, v135
	v_mov_b32_e32 v52, v135
	v_mov_b32_e32 v51, v135
	v_mov_b32_e32 v50, v135
	v_mov_b32_e32 v49, v135
	v_mov_b32_e32 v48, v135
	v_mov_b32_e32 v39, v135
	v_mov_b32_e32 v38, v135
	v_mov_b32_e32 v37, v135
	v_mov_b32_e32 v36, v135
	v_mov_b32_e32 v35, v135
	v_mov_b32_e32 v34, v135
	v_mov_b32_e32 v33, v135
	v_mov_b32_e32 v32, v135
	v_mov_b32_e32 v23, v135
	v_mov_b32_e32 v22, v135
	v_mov_b32_e32 v21, v135
	v_mov_b32_e32 v20, v135
	v_mov_b32_e32 v19, v135
	v_mov_b32_e32 v18, v135
	v_mov_b32_e32 v17, v135
	v_mov_b32_e32 v16, v135
	v_mov_b32_e32 v7, v135
	v_mov_b32_e32 v6, v135
	v_mov_b32_e32 v5, v135
	v_mov_b32_e32 v4, v135
	v_mov_b32_e32 v3, v135
	v_mov_b32_e32 v2, v135
	v_mov_b32_e32 v1, v135
	v_mov_b32_e32 v0, v135
	s_branch .LBB0_568
.LBB0_576:
	s_waitcnt vmcnt(0)
	s_cmpk_gt_u32 s3, 0xff
	s_cbranch_scc1 .LBB0_578
	s_barrier

;     __device__ __forceinline__ size_t a_off(const Unit& u) const { return (size_t)u.pm * atile; }
;     __device__ __forceinline__ size_t b_off(const Unit& u) const { return (size_t)u.pn * btile; }
;     __device__ __forceinline__ bool next(int i, Unit& u) const { const long L = (long)i * G + c; if (L >= NG * 8) return false; u.g = (int)(L >> 3); u.pm = (int)(L & 7); u.pn = 0; return true; }
;     __device__ __forceinline__ size_t a_off(const Unit& u) const { return ((size_t)u.g * NROW + (size_t)u.pm * BM) * KA * 2; }
;     __device__ __forceinline__ size_t b_off(const Unit& u) const { return (size_t)u.g * btile; }
;     __device__ __forceinline__ bool next(int i, Unit& u) const { if (i >= 2) return false; u.g = g; u.pm = 2 * b + i; u.pn = 0; return true; }
;     __device__ __forceinline__ size_t a_off(const Unit& u) const { return ((size_t)u.g * NROW + (size_t)u.pm * BM) * KA * 2; }
;     __device__ __forceinline__ size_t b_off(const Unit& u) const { return (size_t)u.g * btile; }
; #define PG8_STAGE(bufoff, gbase, voff) do { const __amdgpu_buffer_rsrc_t _r = __builtin_amdgcn_make_buffer_rsrc((void*)(gbase), (short)0, 0x7fffffff, 0x00020000); _Pragma("unroll") for (int _i = 0; _i < 2; ++_i) \
;         __builtin_amdgcn_raw_ptr_buffer_load_lds(_r, (LAS unsigned*)(lds + (bufoff) + ldsw + _i * 8192), 16, (int)(voff)[_i], 0, 0, 0); } while (0)
; #define PG8_LDA(dst, b, h) do { _Pragma("unroll") for (int m = 0; m < 4; ++m) _Pragma("unroll") for (int k = 0; k < 2; ++k) dst[m][k] = *(const LAS bf16x8*)(lds + PG8_SA(b, h) + aoff + m * 2048 + k * 1024); } while (0)
; #define PG8_LDB(dst, b, h) do { _Pragma("unroll") for (int n = 0; n < 2; ++n) _Pragma("unroll") for (int k = 0; k < 2; ++k) dst[n][k] = *(const LAS bf16x8*)(lds + PG8_SB(b, h) + boff + n * 2048 + k * 1024); } while (0)
; #define PG8_BAR __builtin_amdgcn_s_barrier()
;     ...
;         const bool has_next = S.next(ui + 1, nxt);
;         const char* nA = has_next ? (const char*)Ap + S.a_off(nxt) : cA; const char* nB = has_next ? (const char*)Btp + S.b_off(nxt) : cB;
;     ...
;             PG8_LDB(B0, 0, 0); PG8_SCHED; PG8_LDA(At, 0, 0); PG8_STAGE(PG8_SA(1, 1), a1 + hstepA, voffA);
;             PG8_WAIT_L(8); PG8_BAR; PG8_WAIT_L(0); PG8_MMA(0, 0, At, B0); PG8_BAR; PG8_SCHED;
;             PG8_LDB(B1, 0, 1); PG8_STAGE(PG8_SB(0, 0), b2, voffB);
;             PG8_BAR; PG8_WAIT_L(0); PG8_MMA(0, 1, At, B1); PG8_BAR;
.LBB0_625:
	s_ashr_i32 s97, s96, 31
	s_lshl_b64 s[8:9], s[96:97], 19
	s_add_u32 s68, s40, s8
	s_addc_u32 s69, s41, s9
	s_ashr_i32 s95, s94, 31
	s_lshl_b64 s[8:9], s[94:95], 19
	s_add_u32 s12, s3, s8
	v_cmp_lt_i64_e64 s[0:1], s[0:1], v[184:185]
	s_addc_u32 s13, s87, s9
	s_andn2_b64 vcc, exec, s[36:37]
	s_waitcnt lgkmcnt(0)
	s_cbranch_vccnz .Lkzero_627
	s_and_b64 s[0:1], s[0:1], exec
	s_cselect_b32 s0, s69, s27
	s_cselect_b32 s1, s68, s26
	s_cselect_b32 s47, s13, s25
	s_cselect_b32 s51, s12, s24
	s_add_u32 s89, s26, 0x100
	s_addc_u32 s90, s27, 0
	s_add_u32 s91, s24, 0x100
	s_mov_b64 s[44:45], s[36:37]
	s_addc_u32 s92, s25, 0
	s_mov_b32 s8, 0
	ds_read_b128 v[128:131], v212
	ds_read_b128 v[132:135], v212 offset:1024
	ds_read_b128 v[136:139], v212 offset:2048
	ds_read_b128 v[140:143], v212 offset:3072
	s_add_i32 s16, s8, 2
	s_cmp_eq_u32 s82, s8
	s_cselect_b32 s36, s1, s89
	s_cselect_b32 s23, s0, s90
	s_cselect_b32 s22, s47, s92
	s_cselect_b32 s28, s51, s91
	s_add_u32 s24, s36, 0x80
	s_addc_u32 s17, s23, 0
	s_add_u32 s8, s89, s18
	s_addc_u32 s9, s90, s19
	s_add_u32 s8, s8, 0xffffff80
	s_addc_u32 s9, s9, -1
	s_and_b32 s9, s9, 0xffff
	s_mov_b32 m0, s83
	ds_read_b128 v[144:147], v213
	ds_read_b128 v[148:151], v213 offset:1024
	ds_read_b128 v[152:155], v213 offset:2048
	ds_read_b128 v[156:159], v213 offset:3072
	ds_read_b128 v[160:163], v213 offset:4096
	ds_read_b128 v[164:167], v213 offset:5120
	ds_read_b128 v[168:171], v213 offset:6144
	ds_read_b128 v[172:175], v213 offset:7168
	buffer_load_dwordx4 v206, s[8:11], 0 offen lds
	s_mov_b32 m0, s84
	s_nop 0
	buffer_load_dwordx4 v208, s[8:11], 0 offen lds
	s_waitcnt lgkmcnt(8)
	s_barrier
	s_waitcnt lgkmcnt(0)
	s_setprio 1
	s_waitcnt lgkmcnt(7)
	v_mfma_f32_16x16x32_bf16 v[112:115], v[128:131], v[144:147], 0
	v_mfma_f32_16x16x32_bf16 v[116:119], v[136:139], v[144:147], 0
	s_waitcnt lgkmcnt(5)
	v_mfma_f32_16x16x32_bf16 v[100:103], v[128:131], v[152:155], 0
	v_mfma_f32_16x16x32_bf16 v[96:99], v[136:139], v[152:155], 0
	s_waitcnt lgkmcnt(3)
	v_mfma_f32_16x16x32_bf16 v[84:87], v[128:131], v[160:163], 0
	v_mfma_f32_16x16x32_bf16 v[80:83], v[136:139], v[160:163], 0
	s_waitcnt lgkmcnt(1)
	v_mfma_f32_16x16x32_bf16 v[68:71], v[128:131], v[168:171], 0
	v_mfma_f32_16x16x32_bf16 v[64:67], v[136:139], v[168:171], 0
	v_mfma_f32_16x16x32_bf16 v[112:115], v[132:135], v[148:151], v[112:115]
	v_mfma_f32_16x16x32_bf16 v[116:119], v[140:143], v[148:151], v[116:119]
	v_mfma_f32_16x16x32_bf16 v[100:103], v[132:135], v[156:159], v[100:103]
	v_mfma_f32_16x16x32_bf16 v[96:99], v[140:143], v[156:159], v[96:99]
	v_mfma_f32_16x16x32_bf16 v[84:87], v[132:135], v[164:167], v[84:87]
	v_mfma_f32_16x16x32_bf16 v[80:83], v[140:143], v[164:167], v[80:83]
	s_waitcnt lgkmcnt(0)
	v_mfma_f32_16x16x32_bf16 v[68:71], v[132:135], v[172:175], v[68:71]
	v_mfma_f32_16x16x32_bf16 v[64:67], v[140:143], v[172:175], v[64:67]
	s_setprio 0
	s_barrier
	s_and_b32 s29, s22, 0xffff
	s_mov_b32 s30, s10
	s_mov_b32 s31, s11
	s_mov_b32 m0, s15
	ds_read_b128 v[176:179], v214
	ds_read_b128 v[180:183], v214 offset:1024
	ds_read_b128 v[188:191], v214 offset:2048
	ds_read_b128 v[192:195], v214 offset:3072
	buffer_load_dwordx4 v207, s[28:31], 0 offen lds
	s_mov_b32 m0, s33
	s_nop 0
	buffer_load_dwordx4 v209, s[28:31], 0 offen lds
	s_barrier
; #define PG8_STAGE(bufoff, gbase, voff) do { const __amdgpu_buffer_rsrc_t _r = __builtin_amdgcn_make_buffer_rsrc((void*)(gbase), (short)0, 0x7fffffff, 0x00020000); _Pragma("unroll") for (int _i = 0; _i < 2; ++_i) \
;         __builtin_amdgcn_raw_ptr_buffer_load_lds(_r, (LAS unsigned*)(lds + (bufoff) + ldsw + _i * 8192), 16, (int)(voff)[_i], 0, 0, 0); } while (0)
; #define PG8_LDA(dst, b, h) do { _Pragma("unroll") for (int m = 0; m < 4; ++m) _Pragma("unroll") for (int k = 0; k < 2; ++k) dst[m][k] = *(const LAS bf16x8*)(lds + PG8_SA(b, h) + aoff + m * 2048 + k * 1024); } while (0)
; #define PG8_MMA(ai, bj, At, Bt) do { __builtin_amdgcn_s_setprio(1); _Pragma("unroll") for (int k = 0; k < 2; ++k) _Pragma("unroll") for (int m = 0; m < 4; ++m) _Pragma("unroll") for (int n = 0; n < ((bj) == 1 ? NB1 : 2); ++n) \
;         acc[ai][bj][m][n] = __builtin_amdgcn_mfma_f32_16x16x32_bf16(Bt[n][k], At[m][k], acc[ai][bj][m][n], 0, 0, 0); __builtin_amdgcn_s_setprio(0); } while (0)
; #define PG8_WAIT_V(n) asm volatile("s_waitcnt vmcnt(" #n ")" ::: "memory")
; #define PG8_WAIT_L(n) asm volatile("s_waitcnt lgkmcnt(" #n ")" ::: "memory")
; #define PG8_BAR __builtin_amdgcn_s_barrier()
; #define PG8_SCHED __builtin_amdgcn_sched_barrier(0)
;     ...
;             PG8_BAR; PG8_WAIT_L(0); PG8_MMA(0, 1, At, B1); PG8_BAR;
;             PG8_LDA(At, 0, 1); PG8_STAGE(PG8_SA(0, 0), a2, voffA);
;             PG8_BAR; PG8_WAIT_L(0); PG8_MMA(1, 0, At, B0); PG8_BAR; PG8_SCHED;
;             PG8_STAGE(PG8_SB(0, 1), b2 + hstepB, voffB);
;             PG8_WAIT_V(6); PG8_BAR; PG8_MMA(1, 1, At, B1); PG8_BAR;
	s_waitcnt lgkmcnt(0)
	s_setprio 1
	s_waitcnt lgkmcnt(3)
	v_mfma_f32_16x16x32_bf16 v[124:127], v[176:179], v[144:147], 0
	s_waitcnt lgkmcnt(1)
	v_mfma_f32_16x16x32_bf16 v[120:123], v[188:191], v[144:147], 0
	v_mfma_f32_16x16x32_bf16 v[108:111], v[176:179], v[152:155], 0
	v_mfma_f32_16x16x32_bf16 v[104:107], v[188:191], v[152:155], 0
	v_mfma_f32_16x16x32_bf16 v[92:95], v[176:179], v[160:163], 0
	v_mfma_f32_16x16x32_bf16 v[88:91], v[188:191], v[160:163], 0
	v_mfma_f32_16x16x32_bf16 v[76:79], v[176:179], v[168:171], 0
	v_mfma_f32_16x16x32_bf16 v[72:75], v[188:191], v[168:171], 0
	v_mfma_f32_16x16x32_bf16 v[124:127], v[180:183], v[148:151], v[124:127]
	s_waitcnt lgkmcnt(0)
	v_mfma_f32_16x16x32_bf16 v[120:123], v[192:195], v[148:151], v[120:123]
	v_mfma_f32_16x16x32_bf16 v[108:111], v[180:183], v[156:159], v[108:111]
	v_mfma_f32_16x16x32_bf16 v[104:107], v[192:195], v[156:159], v[104:107]
	v_mfma_f32_16x16x32_bf16 v[92:95], v[180:183], v[164:167], v[92:95]
	v_mfma_f32_16x16x32_bf16 v[88:91], v[192:195], v[164:167], v[88:91]
	v_mfma_f32_16x16x32_bf16 v[76:79], v[180:183], v[172:175], v[76:79]
	v_mfma_f32_16x16x32_bf16 v[72:75], v[192:195], v[172:175], v[72:75]
	s_setprio 0
	s_and_b32 s37, s23, 0xffff
	s_mov_b32 s38, s10
	s_mov_b32 s39, s11
	s_mov_b32 m0, s14
	s_barrier
	ds_read_b128 v[144:147], v213 offset:16384
	ds_read_b128 v[148:151], v213 offset:17408
	ds_read_b128 v[152:155], v213 offset:18432
	ds_read_b128 v[156:159], v213 offset:19456
	ds_read_b128 v[160:163], v213 offset:20480
	ds_read_b128 v[164:167], v213 offset:21504
	ds_read_b128 v[168:171], v213 offset:22528
	ds_read_b128 v[172:175], v213 offset:23552
	buffer_load_dwordx4 v206, s[36:39], 0 offen lds
	s_mov_b32 m0, s35
	s_nop 0
	buffer_load_dwordx4 v208, s[36:39], 0 offen lds
	s_barrier
	s_waitcnt lgkmcnt(0)
	s_setprio 1
	s_waitcnt lgkmcnt(7)
	v_mfma_f32_16x16x32_bf16 v[52:55], v[128:131], v[144:147], 0
	v_mfma_f32_16x16x32_bf16 v[48:51], v[136:139], v[144:147], 0
	s_waitcnt lgkmcnt(5)
	v_mfma_f32_16x16x32_bf16 v[36:39], v[128:131], v[152:155], 0
	v_mfma_f32_16x16x32_bf16 v[32:35], v[136:139], v[152:155], 0
	s_waitcnt lgkmcnt(3)
	v_mfma_f32_16x16x32_bf16 v[20:23], v[128:131], v[160:163], 0
	v_mfma_f32_16x16x32_bf16 v[16:19], v[136:139], v[160:163], 0
	s_waitcnt lgkmcnt(1)
	v_mfma_f32_16x16x32_bf16 v[4:7], v[128:131], v[168:171], 0
	v_mfma_f32_16x16x32_bf16 v[0:3], v[136:139], v[168:171], 0
	v_mfma_f32_16x16x32_bf16 v[52:55], v[132:135], v[148:151], v[52:55]
	v_mfma_f32_16x16x32_bf16 v[48:51], v[140:143], v[148:151], v[48:51]
	v_mfma_f32_16x16x32_bf16 v[36:39], v[132:135], v[156:159], v[36:39]
	v_mfma_f32_16x16x32_bf16 v[32:35], v[140:143], v[156:159], v[32:35]
	v_mfma_f32_16x16x32_bf16 v[20:23], v[132:135], v[164:167], v[20:23]
	v_mfma_f32_16x16x32_bf16 v[16:19], v[140:143], v[164:167], v[16:19]
	s_waitcnt lgkmcnt(0)
	v_mfma_f32_16x16x32_bf16 v[4:7], v[132:135], v[172:175], v[4:7]
	v_mfma_f32_16x16x32_bf16 v[0:3], v[140:143], v[172:175], v[0:3]
	s_setprio 0
	s_barrier
	s_add_u32 s8, s28, s42
	s_addc_u32 s93, s22, s43
	s_and_b32 s9, s93, 0xffff
	s_mov_b32 m0, s65
	s_nop 0
	buffer_load_dwordx4 v207, s[8:11], 0 offen lds
	s_mov_b32 m0, s67
	s_nop 0
	buffer_load_dwordx4 v209, s[8:11], 0 offen lds
	s_waitcnt vmcnt(6)
	s_barrier
	s_setprio 1
	v_mfma_f32_16x16x32_bf16 v[60:63], v[176:179], v[144:147], 0
	v_mfma_f32_16x16x32_bf16 v[56:59], v[188:191], v[144:147], 0
	v_mfma_f32_16x16x32_bf16 v[44:47], v[176:179], v[152:155], 0
	v_mfma_f32_16x16x32_bf16 v[40:43], v[188:191], v[152:155], 0
	v_mfma_f32_16x16x32_bf16 v[28:31], v[176:179], v[160:163], 0
	v_mfma_f32_16x16x32_bf16 v[24:27], v[188:191], v[160:163], 0
	v_mfma_f32_16x16x32_bf16 v[12:15], v[176:179], v[168:171], 0
	v_mfma_f32_16x16x32_bf16 v[8:11], v[188:191], v[168:171], 0
	v_mfma_f32_16x16x32_bf16 v[60:63], v[180:183], v[148:151], v[60:63]
	v_mfma_f32_16x16x32_bf16 v[56:59], v[192:195], v[148:151], v[56:59]
	v_mfma_f32_16x16x32_bf16 v[44:47], v[180:183], v[156:159], v[44:47]
	v_mfma_f32_16x16x32_bf16 v[40:43], v[192:195], v[156:159], v[40:43]
	v_mfma_f32_16x16x32_bf16 v[28:31], v[180:183], v[164:167], v[28:31]
	v_mfma_f32_16x16x32_bf16 v[24:27], v[192:195], v[164:167], v[24:27]
	v_mfma_f32_16x16x32_bf16 v[12:15], v[180:183], v[172:175], v[12:15]
	v_mfma_f32_16x16x32_bf16 v[8:11], v[192:195], v[172:175], v[8:11]
	s_setprio 0
	s_barrier
	s_branch .Lkmid_627
	.p2align 6
	s_nop 0
	s_nop 0

; __device__ __forceinline__ float fast_sigmoid(float x) { return __builtin_amdgcn_rcpf(1.0f + __builtin_amdgcn_exp2f(x * -1.44269504f)); }
;     __device__ __forceinline__ void operator()(const Acc& acc, const Unit& u, int wr, int wc, int fr, int fq, LAS unsigned char* lds, f32x4 epar) const {
;     ...
;         for (int ai = 0; ai < 2; ++ai)
; #pragma unroll
;             for (int m = 0; m < 4; ++m) { const int r = u.pm * BM + ai * HALF + wr * 64 + m * 16 + fr; const size_t off = (size_t)r * DM + c0;
;                 xv[ai][m][0] = __builtin_nontemporal_load((const f32x4*)(x + off)); xv[ai][m][1] = __builtin_nontemporal_load((const f32x4*)(x + off + 4)); }
; #pragma unroll
;         for (int ai = 0; ai < 2; ++ai)
; #pragma unroll
;             for (int m = 0; m < 4; ++m) { const int r = u.pm * BM + ai * HALF + wr * 64 + m * 16 + fr; const size_t off = (size_t)r * DM + c0;
;                 f32x4 v0 = xv[ai][m][0], v1 = xv[ai][m][1];
;                 const f32x4 za0 = acc[ai][0][m][0], za1 = acc[ai][0][m][1], zg0 = acc[ai][1][m][0], zg1 = acc[ai][1][m][1];
; #pragma unroll
;                 for (int j = 0; j < 4; ++j) { v0[j] += za0[j] * fast_sigmoid(zg0[j]); v1[j] += za1[j] * fast_sigmoid(zg1[j]); }
.LBB0_629:
	s_mov_b32 s101, 1.0
	s_mov_b32 s100, 0xbfb8aa3b
	v_readlane_b32 s44, v252, 6
	v_readlane_b32 s45, v252, 7
	v_readlane_b32 s46, v252, 8
	v_readlane_b32 s47, v252, 9
	v_readlane_b32 s48, v252, 10
	v_readlane_b32 s49, v252, 11
	v_readlane_b32 s50, v252, 12
	v_readlane_b32 s51, v252, 13
	v_readlane_b32 s52, v252, 14
	v_readlane_b32 s53, v252, 15
	v_readlane_b32 s54, v252, 16
	v_readlane_b32 s55, v252, 17
	v_readlane_b32 s56, v252, 18
	v_readlane_b32 s57, v252, 19
	v_readlane_b32 s58, v252, 20
	v_readlane_b32 s59, v252, 21
	s_mov_b64 s[0:1], exec
	v_lshl_add_u32 v188, s66, 8, v210
	v_lshl_or_b32 v189, s64, 7, v211
	v_lshlrev_b32_e32 v190, 12, v188
	v_lshlrev_b32_e32 v191, 11, v188
	v_lshlrev_b32_e32 v192, 2, v188
	v_lshl_add_u32 v190, v189, 2, v190
	v_lshl_add_u32 v191, v189, 1, v191
	global_load_dwordx4 v[222:225], v190, s[44:45] nt
	global_load_dwordx4 v[218:221], v190, s[44:45] offset:16 nt
	v_add_u32_e32 v193, 0x10000, v190
	global_load_dwordx4 v[180:183], v193, s[44:45] nt
	global_load_dwordx4 v[176:179], v193, s[44:45] offset:16 nt
	v_add_u32_e32 v193, 0x20000, v190
	global_load_dwordx4 v[172:175], v193, s[44:45] nt
	global_load_dwordx4 v[168:171], v193, s[44:45] offset:16 nt
	v_add_u32_e32 v193, 0x30000, v190
	global_load_dwordx4 v[164:167], v193, s[44:45] nt
	global_load_dwordx4 v[160:163], v193, s[44:45] offset:16 nt
	v_add_u32_e32 v193, 0x80000, v190
	global_load_dwordx4 v[156:159], v193, s[44:45] nt
	global_load_dwordx4 v[152:155], v193, s[44:45] offset:16 nt
	v_add_u32_e32 v193, 0x90000, v190
	global_load_dwordx4 v[148:151], v193, s[44:45] nt
	global_load_dwordx4 v[144:147], v193, s[44:45] offset:16 nt
	v_add_u32_e32 v193, 0xa0000, v190
	global_load_dwordx4 v[140:143], v193, s[44:45] nt
	global_load_dwordx4 v[136:139], v193, s[44:45] offset:16 nt
	v_add_u32_e32 v193, 0xb0000, v190
	global_load_dwordx4 v[132:135], v193, s[44:45] nt
	global_load_dwordx4 v[128:131], v193, s[44:45] offset:16 nt
	v_pk_mul_f32 v[124:125], s[100:101], v[124:125] op_sel_hi:[0,1]
	v_pk_mul_f32 v[126:127], s[100:101], v[126:127] op_sel_hi:[0,1]
	v_pk_mul_f32 v[120:121], s[100:101], v[120:121] op_sel_hi:[0,1]
	v_pk_mul_f32 v[122:123], s[100:101], v[122:123] op_sel_hi:[0,1]
	v_exp_f32_e32 v124, v124
	v_exp_f32_e32 v125, v125
	v_exp_f32_e32 v126, v126
	v_exp_f32_e32 v127, v127
	v_exp_f32_e32 v120, v120
	v_exp_f32_e32 v121, v121
	v_exp_f32_e32 v122, v122
	v_exp_f32_e32 v123, v123
	v_pk_add_f32 v[124:125], s[100:101], v[124:125] op_sel:[1,0]
	v_pk_add_f32 v[126:127], s[100:101], v[126:127] op_sel:[1,0]
	v_pk_add_f32 v[120:121], s[100:101], v[120:121] op_sel:[1,0]
	v_pk_add_f32 v[122:123], s[100:101], v[122:123] op_sel:[1,0]
	v_rcp_f32_e32 v124, v124
	v_rcp_f32_e32 v125, v125
	v_rcp_f32_e32 v126, v126
	v_rcp_f32_e32 v127, v127
	v_rcp_f32_e32 v120, v120
	v_rcp_f32_e32 v121, v121
	v_rcp_f32_e32 v122, v122
	v_rcp_f32_e32 v123, v123
	v_pk_mul_f32 v[108:109], s[100:101], v[108:109] op_sel_hi:[0,1]
	v_pk_mul_f32 v[110:111], s[100:101], v[110:111] op_sel_hi:[0,1]
	v_pk_mul_f32 v[104:105], s[100:101], v[104:105] op_sel_hi:[0,1]
	v_pk_mul_f32 v[106:107], s[100:101], v[106:107] op_sel_hi:[0,1]
	v_exp_f32_e32 v108, v108
	v_exp_f32_e32 v109, v109
	v_exp_f32_e32 v110, v110
	v_exp_f32_e32 v111, v111
	v_exp_f32_e32 v104, v104
	v_exp_f32_e32 v105, v105
	v_exp_f32_e32 v106, v106
	v_exp_f32_e32 v107, v107
	v_pk_add_f32 v[108:109], s[100:101], v[108:109] op_sel:[1,0]
	v_pk_add_f32 v[110:111], s[100:101], v[110:111] op_sel:[1,0]
	v_pk_add_f32 v[104:105], s[100:101], v[104:105] op_sel:[1,0]
	v_pk_add_f32 v[106:107], s[100:101], v[106:107] op_sel:[1,0]
	v_rcp_f32_e32 v108, v108
	v_rcp_f32_e32 v109, v109
	v_rcp_f32_e32 v110, v110
	v_rcp_f32_e32 v111, v111
	v_rcp_f32_e32 v104, v104
	v_rcp_f32_e32 v105, v105
	v_rcp_f32_e32 v106, v106
	v_rcp_f32_e32 v107, v107
	v_pk_mul_f32 v[92:93], s[100:101], v[92:93] op_sel_hi:[0,1]
	v_pk_mul_f32 v[94:95], s[100:101], v[94:95] op_sel_hi:[0,1]
	v_pk_mul_f32 v[88:89], s[100:101], v[88:89] op_sel_hi:[0,1]
	v_pk_mul_f32 v[90:91], s[100:101], v[90:91] op_sel_hi:[0,1]
	v_exp_f32_e32 v92, v92
	v_exp_f32_e32 v93, v93
	v_exp_f32_e32 v94, v94
	v_exp_f32_e32 v95, v95
	v_exp_f32_e32 v88, v88
	v_exp_f32_e32 v89, v89
	v_exp_f32_e32 v90, v90
	v_exp_f32_e32 v91, v91
	v_pk_add_f32 v[92:93], s[100:101], v[92:93] op_sel:[1,0]
	v_pk_add_f32 v[94:95], s[100:101], v[94:95] op_sel:[1,0]
	v_pk_add_f32 v[88:89], s[100:101], v[88:89] op_sel:[1,0]
	v_pk_add_f32 v[90:91], s[100:101], v[90:91] op_sel:[1,0]
	v_rcp_f32_e32 v92, v92
	v_rcp_f32_e32 v93, v93
	v_rcp_f32_e32 v94, v94
	v_rcp_f32_e32 v95, v95
	v_rcp_f32_e32 v88, v88
	v_rcp_f32_e32 v89, v89
	v_rcp_f32_e32 v90, v90
	v_rcp_f32_e32 v91, v91
	v_pk_mul_f32 v[76:77], s[100:101], v[76:77] op_sel_hi:[0,1]
	v_pk_mul_f32 v[78:79], s[100:101], v[78:79] op_sel_hi:[0,1]
	v_pk_mul_f32 v[72:73], s[100:101], v[72:73] op_sel_hi:[0,1]
	v_pk_mul_f32 v[74:75], s[100:101], v[74:75] op_sel_hi:[0,1]
	v_exp_f32_e32 v76, v76
	v_exp_f32_e32 v77, v77
	v_exp_f32_e32 v78, v78
	v_exp_f32_e32 v79, v79
	v_exp_f32_e32 v72, v72
	v_exp_f32_e32 v73, v73
	v_exp_f32_e32 v74, v74
	v_exp_f32_e32 v75, v75
	v_pk_add_f32 v[76:77], s[100:101], v[76:77] op_sel:[1,0]
	v_pk_add_f32 v[78:79], s[100:101], v[78:79] op_sel:[1,0]
	v_pk_add_f32 v[72:73], s[100:101], v[72:73] op_sel:[1,0]
	v_pk_add_f32 v[74:75], s[100:101], v[74:75] op_sel:[1,0]
	v_rcp_f32_e32 v76, v76
	v_rcp_f32_e32 v77, v77
	v_rcp_f32_e32 v78, v78
	v_rcp_f32_e32 v79, v79
	v_rcp_f32_e32 v72, v72
	v_rcp_f32_e32 v73, v73
	v_rcp_f32_e32 v74, v74
	v_rcp_f32_e32 v75, v75
	v_pk_mul_f32 v[60:61], s[100:101], v[60:61] op_sel_hi:[0,1]
	v_pk_mul_f32 v[62:63], s[100:101], v[62:63] op_sel_hi:[0,1]
; __device__ __forceinline__ unsigned cvt_pk_bf16(float lo, float hi) { unsigned r; asm volatile("v_cvt_pk_bf16_f32 %0, %1, %2" : "=v"(r) : "v"(lo), "v"(hi)); return r; }
; __device__ __forceinline__ float fast_sigmoid(float x) { return __builtin_amdgcn_rcpf(1.0f + __builtin_amdgcn_exp2f(x * -1.44269504f)); }
;     __device__ __forceinline__ void operator()(const Acc& acc, const Unit& u, int wr, int wc, int fr, int fq, LAS unsigned char* lds, f32x4 epar) const {
;     ...
;                 for (int j = 0; j < 4; ++j) { v0[j] += za0[j] * fast_sigmoid(zg0[j]); v1[j] += za1[j] * fast_sigmoid(zg1[j]); }
;                 u32x4 w; w.x = cvt_pk_bf16(v0[0], v0[1]); w.y = cvt_pk_bf16(v0[2], v0[3]); w.z = cvt_pk_bf16(v1[0], v1[1]); w.w = cvt_pk_bf16(v1[2], v1[3]);
;                 *(u32x4*)(HB + off) = w;
;                 float s = (v0[0] * v0[0] + v0[1] * v0[1]) + (v0[2] * v0[2] + v0[3] * v0[3]) + (v1[0] * v1[0] + v1[1] * v1[1]) + (v1[2] * v1[2] + v1[3] * v1[3]);
;                 s += __shfl_xor(s, 16); s += __shfl_xor(s, 32);
;                 if (fq == 0) unsafeAtomicAdd(ssq + r, s); }
	v_pk_mul_f32 v[56:57], s[100:101], v[56:57] op_sel_hi:[0,1]
	v_pk_mul_f32 v[58:59], s[100:101], v[58:59] op_sel_hi:[0,1]
	v_exp_f32_e32 v60, v60
	v_exp_f32_e32 v61, v61
	v_exp_f32_e32 v62, v62
	v_exp_f32_e32 v63, v63
	v_exp_f32_e32 v56, v56
	v_exp_f32_e32 v57, v57
	v_exp_f32_e32 v58, v58
	v_exp_f32_e32 v59, v59
	v_pk_add_f32 v[60:61], s[100:101], v[60:61] op_sel:[1,0]
	v_pk_add_f32 v[62:63], s[100:101], v[62:63] op_sel:[1,0]
	v_pk_add_f32 v[56:57], s[100:101], v[56:57] op_sel:[1,0]
	v_pk_add_f32 v[58:59], s[100:101], v[58:59] op_sel:[1,0]
	v_rcp_f32_e32 v60, v60
	v_rcp_f32_e32 v61, v61
	v_rcp_f32_e32 v62, v62
	v_rcp_f32_e32 v63, v63
	v_rcp_f32_e32 v56, v56
	v_rcp_f32_e32 v57, v57
	v_rcp_f32_e32 v58, v58
	v_rcp_f32_e32 v59, v59
	v_pk_mul_f32 v[44:45], s[100:101], v[44:45] op_sel_hi:[0,1]
	v_pk_mul_f32 v[46:47], s[100:101], v[46:47] op_sel_hi:[0,1]
	v_pk_mul_f32 v[40:41], s[100:101], v[40:41] op_sel_hi:[0,1]
	v_pk_mul_f32 v[42:43], s[100:101], v[42:43] op_sel_hi:[0,1]
	v_exp_f32_e32 v44, v44
	v_exp_f32_e32 v45, v45
	v_exp_f32_e32 v46, v46
	v_exp_f32_e32 v47, v47
	v_exp_f32_e32 v40, v40
	v_exp_f32_e32 v41, v41
	v_exp_f32_e32 v42, v42
	v_exp_f32_e32 v43, v43
	v_pk_add_f32 v[44:45], s[100:101], v[44:45] op_sel:[1,0]
	v_pk_add_f32 v[46:47], s[100:101], v[46:47] op_sel:[1,0]
	v_pk_add_f32 v[40:41], s[100:101], v[40:41] op_sel:[1,0]
	v_pk_add_f32 v[42:43], s[100:101], v[42:43] op_sel:[1,0]
	v_rcp_f32_e32 v44, v44
	v_rcp_f32_e32 v45, v45
	v_rcp_f32_e32 v46, v46
	v_rcp_f32_e32 v47, v47
	v_rcp_f32_e32 v40, v40
	v_rcp_f32_e32 v41, v41
	v_rcp_f32_e32 v42, v42
	v_rcp_f32_e32 v43, v43
	v_pk_mul_f32 v[28:29], s[100:101], v[28:29] op_sel_hi:[0,1]
	v_pk_mul_f32 v[30:31], s[100:101], v[30:31] op_sel_hi:[0,1]
	v_pk_mul_f32 v[24:25], s[100:101], v[24:25] op_sel_hi:[0,1]
	v_pk_mul_f32 v[26:27], s[100:101], v[26:27] op_sel_hi:[0,1]
	v_exp_f32_e32 v28, v28
	v_exp_f32_e32 v29, v29
	v_exp_f32_e32 v30, v30
	v_exp_f32_e32 v31, v31
	v_exp_f32_e32 v24, v24
	v_exp_f32_e32 v25, v25
	v_exp_f32_e32 v26, v26
	v_exp_f32_e32 v27, v27
	v_pk_add_f32 v[28:29], s[100:101], v[28:29] op_sel:[1,0]
	v_pk_add_f32 v[30:31], s[100:101], v[30:31] op_sel:[1,0]
	v_pk_add_f32 v[24:25], s[100:101], v[24:25] op_sel:[1,0]
	v_pk_add_f32 v[26:27], s[100:101], v[26:27] op_sel:[1,0]
	v_rcp_f32_e32 v28, v28
	v_rcp_f32_e32 v29, v29
	v_rcp_f32_e32 v30, v30
	v_rcp_f32_e32 v31, v31
	v_rcp_f32_e32 v24, v24
	v_rcp_f32_e32 v25, v25
	v_rcp_f32_e32 v26, v26
	v_rcp_f32_e32 v27, v27
	v_pk_mul_f32 v[12:13], s[100:101], v[12:13] op_sel_hi:[0,1]
	v_pk_mul_f32 v[14:15], s[100:101], v[14:15] op_sel_hi:[0,1]
	v_pk_mul_f32 v[8:9], s[100:101], v[8:9] op_sel_hi:[0,1]
	v_pk_mul_f32 v[10:11], s[100:101], v[10:11] op_sel_hi:[0,1]
	v_exp_f32_e32 v12, v12
	v_exp_f32_e32 v13, v13
	v_exp_f32_e32 v14, v14
	v_exp_f32_e32 v15, v15
	v_exp_f32_e32 v8, v8
	v_exp_f32_e32 v9, v9
	v_exp_f32_e32 v10, v10
	v_exp_f32_e32 v11, v11
	v_pk_add_f32 v[12:13], s[100:101], v[12:13] op_sel:[1,0]
	v_pk_add_f32 v[14:15], s[100:101], v[14:15] op_sel:[1,0]
	v_pk_add_f32 v[8:9], s[100:101], v[8:9] op_sel:[1,0]
	v_pk_add_f32 v[10:11], s[100:101], v[10:11] op_sel:[1,0]
	v_rcp_f32_e32 v12, v12
	v_rcp_f32_e32 v13, v13
	v_rcp_f32_e32 v14, v14
	v_rcp_f32_e32 v15, v15
	v_rcp_f32_e32 v8, v8
	v_rcp_f32_e32 v9, v9
	v_rcp_f32_e32 v10, v10
	v_rcp_f32_e32 v11, v11
	s_nop 0
	s_waitcnt vmcnt(14)
	v_pk_fma_f32 v[222:223], v[124:125], v[112:113], v[222:223]
	v_pk_fma_f32 v[224:225], v[126:127], v[114:115], v[224:225]
	v_pk_fma_f32 v[218:219], v[120:121], v[116:117], v[218:219]
	v_pk_fma_f32 v[220:221], v[122:123], v[118:119], v[220:221]
	v_mul_f32_e32 v124, v222, v222
	v_mul_f32_e32 v125, v224, v224
	v_mul_f32_e32 v126, v218, v218
	v_mul_f32_e32 v127, v220, v220
	v_fmac_f32_e32 v124, v223, v223
	v_fmac_f32_e32 v125, v225, v225
	v_fmac_f32_e32 v126, v219, v219
	v_fmac_f32_e32 v127, v221, v221
	v_cvt_pk_bf16_f32 v112, v222, v223
	v_cvt_pk_bf16_f32 v113, v224, v225
	v_cvt_pk_bf16_f32 v114, v218, v219
	v_cvt_pk_bf16_f32 v115, v220, v221
	v_add_f32_e32 v124, v124, v125
	v_add_f32_e32 v126, v126, v127
	v_add_f32_e32 v194, v124, v126
	global_store_dwordx4 v191, v[112:115], s[20:21]
	v_mov_b32_e32 v202, v194
	s_nop 0
	s_nop 0
	v_permlane16_swap_b32_e32 v194, v202
	v_add_f32_e32 v194, v194, v202
	v_mov_b32_e32 v202, v194
	s_nop 1
	v_permlane32_swap_b32_e32 v194, v202
	v_add_f32_e32 v194, v194, v202
	s_and_b64 exec, exec, s[4:5]
	global_atomic_add_f32 v192, v194, s[60:61]
	s_mov_b64 exec, s[0:1]
	s_waitcnt vmcnt(14)
	v_pk_fma_f32 v[180:181], v[108:109], v[100:101], v[180:181]
	v_pk_fma_f32 v[182:183], v[110:111], v[102:103], v[182:183]
	v_pk_fma_f32 v[176:177], v[104:105], v[96:97], v[176:177]
	v_pk_fma_f32 v[178:179], v[106:107], v[98:99], v[178:179]
	v_mul_f32_e32 v108, v180, v180
	v_mul_f32_e32 v109, v182, v182
	v_mul_f32_e32 v110, v176, v176
	v_mul_f32_e32 v111, v178, v178
	v_fmac_f32_e32 v108, v181, v181
	v_fmac_f32_e32 v109, v183, v183
	v_fmac_f32_e32 v110, v177, v177
	v_fmac_f32_e32 v111, v179, v179
	v_cvt_pk_bf16_f32 v100, v180, v181
	v_cvt_pk_bf16_f32 v101, v182, v183
	v_cvt_pk_bf16_f32 v102, v176, v177
	v_cvt_pk_bf16_f32 v103, v178, v179
	v_add_f32_e32 v108, v108, v109
	v_add_f32_e32 v110, v110, v111
	v_add_u32_e32 v193, 0x8000, v191
	v_add_f32_e32 v195, v108, v110
	global_store_dwordx4 v193, v[100:103], s[20:21]
	v_mov_b32_e32 v203, v195
	v_add_u32_e32 v193, 0x40, v192
	s_nop 0
	v_permlane16_swap_b32_e32 v195, v203
	v_add_f32_e32 v195, v195, v203
	v_mov_b32_e32 v203, v195
	s_nop 1
	v_permlane32_swap_b32_e32 v195, v203
	v_add_f32_e32 v195, v195, v203
	s_and_b64 exec, exec, s[4:5]
	global_atomic_add_f32 v193, v195, s[60:61]
	s_mov_b64 exec, s[0:1]
	s_waitcnt vmcnt(14)
; __device__ __forceinline__ unsigned cvt_pk_bf16(float lo, float hi) { unsigned r; asm volatile("v_cvt_pk_bf16_f32 %0, %1, %2" : "=v"(r) : "v"(lo), "v"(hi)); return r; }
; __device__ __forceinline__ float fast_sigmoid(float x) { return __builtin_amdgcn_rcpf(1.0f + __builtin_amdgcn_exp2f(x * -1.44269504f)); }
;     __device__ __forceinline__ void operator()(const Acc& acc, const Unit& u, int wr, int wc, int fr, int fq, LAS unsigned char* lds, f32x4 epar) const {
;     ...
;             for (int m = 0; m < 4; ++m) { const int r = u.pm * BM + ai * HALF + wr * 64 + m * 16 + fr; const size_t off = (size_t)r * DM + c0;
;                 f32x4 v0 = xv[ai][m][0], v1 = xv[ai][m][1];
;                 const f32x4 za0 = acc[ai][0][m][0], za1 = acc[ai][0][m][1], zg0 = acc[ai][1][m][0], zg1 = acc[ai][1][m][1];
; #pragma unroll
;                 for (int j = 0; j < 4; ++j) { v0[j] += za0[j] * fast_sigmoid(zg0[j]); v1[j] += za1[j] * fast_sigmoid(zg1[j]); }
;                 u32x4 w; w.x = cvt_pk_bf16(v0[0], v0[1]); w.y = cvt_pk_bf16(v0[2], v0[3]); w.z = cvt_pk_bf16(v1[0], v1[1]); w.w = cvt_pk_bf16(v1[2], v1[3]);
;                 *(u32x4*)(HB + off) = w;
;                 float s = (v0[0] * v0[0] + v0[1] * v0[1]) + (v0[2] * v0[2] + v0[3] * v0[3]) + (v1[0] * v1[0] + v1[1] * v1[1]) + (v1[2] * v1[2] + v1[3] * v1[3]);
;                 s += __shfl_xor(s, 16); s += __shfl_xor(s, 32);
;                 if (fq == 0) unsafeAtomicAdd(ssq + r, s); }
	v_pk_fma_f32 v[172:173], v[92:93], v[84:85], v[172:173]
	v_pk_fma_f32 v[174:175], v[94:95], v[86:87], v[174:175]
	v_pk_fma_f32 v[168:169], v[88:89], v[80:81], v[168:169]
	v_pk_fma_f32 v[170:171], v[90:91], v[82:83], v[170:171]
	v_mul_f32_e32 v92, v172, v172
	v_mul_f32_e32 v93, v174, v174
	v_mul_f32_e32 v94, v168, v168
	v_mul_f32_e32 v95, v170, v170
	v_fmac_f32_e32 v92, v173, v173
	v_fmac_f32_e32 v93, v175, v175
	v_fmac_f32_e32 v94, v169, v169
	v_fmac_f32_e32 v95, v171, v171
	v_cvt_pk_bf16_f32 v84, v172, v173
	v_cvt_pk_bf16_f32 v85, v174, v175
	v_cvt_pk_bf16_f32 v86, v168, v169
	v_cvt_pk_bf16_f32 v87, v170, v171
	v_add_f32_e32 v92, v92, v93
	v_add_f32_e32 v94, v94, v95
	v_add_u32_e32 v193, 0x10000, v191
	v_add_f32_e32 v196, v92, v94
	global_store_dwordx4 v193, v[84:87], s[20:21]
	v_mov_b32_e32 v204, v196
	v_add_u32_e32 v193, 0x80, v192
	s_nop 0
	v_permlane16_swap_b32_e32 v196, v204
	v_add_f32_e32 v196, v196, v204
	v_mov_b32_e32 v204, v196
	s_nop 1
	v_permlane32_swap_b32_e32 v196, v204
	v_add_f32_e32 v196, v196, v204
	s_and_b64 exec, exec, s[4:5]
	global_atomic_add_f32 v193, v196, s[60:61]
	s_mov_b64 exec, s[0:1]
	s_waitcnt vmcnt(14)
	v_pk_fma_f32 v[164:165], v[76:77], v[68:69], v[164:165]
	v_pk_fma_f32 v[166:167], v[78:79], v[70:71], v[166:167]
	v_pk_fma_f32 v[160:161], v[72:73], v[64:65], v[160:161]
	v_pk_fma_f32 v[162:163], v[74:75], v[66:67], v[162:163]
	v_mul_f32_e32 v76, v164, v164
	v_mul_f32_e32 v77, v166, v166
	v_mul_f32_e32 v78, v160, v160
	v_mul_f32_e32 v79, v162, v162
	v_fmac_f32_e32 v76, v165, v165
	v_fmac_f32_e32 v77, v167, v167
	v_fmac_f32_e32 v78, v161, v161
	v_fmac_f32_e32 v79, v163, v163
	v_cvt_pk_bf16_f32 v68, v164, v165
	v_cvt_pk_bf16_f32 v69, v166, v167
	v_cvt_pk_bf16_f32 v70, v160, v161
	v_cvt_pk_bf16_f32 v71, v162, v163
	v_add_f32_e32 v76, v76, v77
	v_add_f32_e32 v78, v78, v79
	v_add_u32_e32 v193, 0x18000, v191
	v_add_f32_e32 v197, v76, v78
	global_store_dwordx4 v193, v[68:71], s[20:21]
	v_mov_b32_e32 v205, v197
	v_add_u32_e32 v193, 0xc0, v192
	s_nop 0
	v_permlane16_swap_b32_e32 v197, v205
	v_add_f32_e32 v197, v197, v205
	v_mov_b32_e32 v205, v197
	s_nop 1
	v_permlane32_swap_b32_e32 v197, v205
	v_add_f32_e32 v197, v197, v205
	s_and_b64 exec, exec, s[4:5]
	global_atomic_add_f32 v193, v197, s[60:61]
	s_mov_b64 exec, s[0:1]
	s_waitcnt vmcnt(14)
	v_pk_fma_f32 v[156:157], v[60:61], v[52:53], v[156:157]
	v_pk_fma_f32 v[158:159], v[62:63], v[54:55], v[158:159]
	v_pk_fma_f32 v[152:153], v[56:57], v[48:49], v[152:153]
	v_pk_fma_f32 v[154:155], v[58:59], v[50:51], v[154:155]
	v_mul_f32_e32 v60, v156, v156
	v_mul_f32_e32 v61, v158, v158
	v_mul_f32_e32 v62, v152, v152
	v_mul_f32_e32 v63, v154, v154
	v_fmac_f32_e32 v60, v157, v157
	v_fmac_f32_e32 v61, v159, v159
	v_fmac_f32_e32 v62, v153, v153
	v_fmac_f32_e32 v63, v155, v155
	v_cvt_pk_bf16_f32 v52, v156, v157
	v_cvt_pk_bf16_f32 v53, v158, v159
	v_cvt_pk_bf16_f32 v54, v152, v153
	v_cvt_pk_bf16_f32 v55, v154, v155
	v_add_f32_e32 v60, v60, v61
	v_add_f32_e32 v62, v62, v63
	v_add_u32_e32 v193, 0x40000, v191
	v_add_f32_e32 v198, v60, v62
	global_store_dwordx4 v193, v[52:55], s[20:21]
	v_mov_b32_e32 v124, v198
	v_add_u32_e32 v193, 0x200, v192
	s_nop 0
	v_permlane16_swap_b32_e32 v198, v124
	v_add_f32_e32 v198, v198, v124
	v_mov_b32_e32 v124, v198
	s_nop 1
	v_permlane32_swap_b32_e32 v198, v124
	v_add_f32_e32 v198, v198, v124
	s_and_b64 exec, exec, s[4:5]
	global_atomic_add_f32 v193, v198, s[60:61]
	s_mov_b64 exec, s[0:1]
	s_waitcnt vmcnt(14)
	v_pk_fma_f32 v[148:149], v[44:45], v[36:37], v[148:149]
	v_pk_fma_f32 v[150:151], v[46:47], v[38:39], v[150:151]
	v_pk_fma_f32 v[144:145], v[40:41], v[32:33], v[144:145]
	v_pk_fma_f32 v[146:147], v[42:43], v[34:35], v[146:147]
	v_mul_f32_e32 v44, v148, v148
	v_mul_f32_e32 v45, v150, v150
	v_mul_f32_e32 v46, v144, v144
	v_mul_f32_e32 v47, v146, v146
	v_fmac_f32_e32 v44, v149, v149
	v_fmac_f32_e32 v45, v151, v151
	v_fmac_f32_e32 v46, v145, v145
	v_fmac_f32_e32 v47, v147, v147
	v_cvt_pk_bf16_f32 v36, v148, v149
	v_cvt_pk_bf16_f32 v37, v150, v151
	v_cvt_pk_bf16_f32 v38, v144, v145
	v_cvt_pk_bf16_f32 v39, v146, v147
	v_add_f32_e32 v44, v44, v45
	v_add_f32_e32 v46, v46, v47
	v_add_u32_e32 v193, 0x48000, v191
	v_add_f32_e32 v199, v44, v46
	global_store_dwordx4 v193, v[36:39], s[20:21]
	v_mov_b32_e32 v125, v199
	v_add_u32_e32 v193, 0x240, v192
	s_nop 0
	v_permlane16_swap_b32_e32 v199, v125
	v_add_f32_e32 v199, v199, v125
	v_mov_b32_e32 v125, v199
	s_nop 1
	v_permlane32_swap_b32_e32 v199, v125
	v_add_f32_e32 v199, v199, v125
	s_and_b64 exec, exec, s[4:5]
	global_atomic_add_f32 v193, v199, s[60:61]
	s_mov_b64 exec, s[0:1]
	s_waitcnt vmcnt(14)
	v_pk_fma_f32 v[140:141], v[28:29], v[20:21], v[140:141]
	v_pk_fma_f32 v[142:143], v[30:31], v[22:23], v[142:143]
	v_pk_fma_f32 v[136:137], v[24:25], v[16:17], v[136:137]
	v_pk_fma_f32 v[138:139], v[26:27], v[18:19], v[138:139]
	v_mul_f32_e32 v28, v140, v140
	v_mul_f32_e32 v29, v142, v142
	v_mul_f32_e32 v30, v136, v136
	v_mul_f32_e32 v31, v138, v138
	v_fmac_f32_e32 v28, v141, v141
	v_fmac_f32_e32 v29, v143, v143
	v_fmac_f32_e32 v30, v137, v137
	v_fmac_f32_e32 v31, v139, v139
	v_cvt_pk_bf16_f32 v20, v140, v141
	v_cvt_pk_bf16_f32 v21, v142, v143
	v_cvt_pk_bf16_f32 v22, v136, v137
	v_cvt_pk_bf16_f32 v23, v138, v139
	v_add_f32_e32 v28, v28, v29
	v_add_f32_e32 v30, v30, v31
	v_add_u32_e32 v193, 0x50000, v191
	v_add_f32_e32 v200, v28, v30
	global_store_dwordx4 v193, v[20:23], s[20:21]
	v_mov_b32_e32 v126, v200
	v_add_u32_e32 v193, 0x280, v192
	s_nop 0
	v_permlane16_swap_b32_e32 v200, v126
	v_add_f32_e32 v200, v200, v126
	v_mov_b32_e32 v126, v200
	s_nop 1
	v_permlane32_swap_b32_e32 v200, v126
	v_add_f32_e32 v200, v200, v126
	s_and_b64 exec, exec, s[4:5]
	global_atomic_add_f32 v193, v200, s[60:61]
	s_mov_b64 exec, s[0:1]
	s_waitcnt vmcnt(14)
	v_pk_fma_f32 v[132:133], v[12:13], v[4:5], v[132:133]
	v_pk_fma_f32 v[134:135], v[14:15], v[6:7], v[134:135]
	v_pk_fma_f32 v[128:129], v[8:9], v[0:1], v[128:129]
	v_pk_fma_f32 v[130:131], v[10:11], v[2:3], v[130:131]
	v_mul_f32_e32 v12, v132, v132
	v_mul_f32_e32 v13, v134, v134
	v_mul_f32_e32 v14, v128, v128
	v_mul_f32_e32 v15, v130, v130
	v_fmac_f32_e32 v12, v133, v133
	v_fmac_f32_e32 v13, v135, v135
	v_fmac_f32_e32 v14, v129, v129
	v_fmac_f32_e32 v15, v131, v131
	v_cvt_pk_bf16_f32 v4, v132, v133
	v_cvt_pk_bf16_f32 v5, v134, v135
	v_cvt_pk_bf16_f32 v6, v128, v129
	v_cvt_pk_bf16_f32 v7, v130, v131
	v_add_f32_e32 v12, v12, v13
	v_add_f32_e32 v14, v14, v15
	v_add_u32_e32 v193, 0x58000, v191
	v_add_f32_e32 v201, v12, v14
	global_store_dwordx4 v193, v[4:7], s[20:21]
	v_mov_b32_e32 v127, v201
	v_add_u32_e32 v193, 0x2c0, v192
	s_nop 0
	v_permlane16_swap_b32_e32 v201, v127
	v_add_f32_e32 v201, v201, v127
	v_mov_b32_e32 v127, v201
	s_nop 1
	v_permlane32_swap_b32_e32 v201, v127
	v_add_f32_e32 v201, v201, v127
	s_and_b64 exec, exec, s[4:5]
	global_atomic_add_f32 v193, v201, s[60:61]
	s_mov_b64 exec, s[0:1]
	s_branch .LBB0_618
; #define PG8_WAIT_V(n) asm volatile("s_waitcnt vmcnt(" #n ")" ::: "memory")
; #define PG8_BAR __builtin_amdgcn_s_barrier()
;     ...
; #pragma unroll
;         for (int a = 0; a < 2; ++a)
; #pragma unroll
;             for (int b = 0; b < 2; ++b)
; #pragma unroll
;                 for (int m = 0; m < 4; ++m)
; #pragma unroll
;                     for (int n = 0; n < 2; ++n) acc[a][b][m][n] = (f32x4){0.f, 0.f, 0.f, 0.f};
;         cur = nxt; cA = nA; cB = nB; ++ui;
;     }
;     PG8_WAIT_V(0);
;     if (wr == 0) PG8_BAR;
;     PG8_BAR;
.Lkzero_627:
	v_mov_b32_e32 v115, 0
	v_mov_b32_e32 v114, v115
	v_mov_b32_e32 v113, v115
	v_mov_b32_e32 v112, v115
	v_mov_b32_e32 v119, v115
	v_mov_b32_e32 v118, v115
	v_mov_b32_e32 v117, v115
	v_mov_b32_e32 v116, v115
	v_mov_b32_e32 v103, v115
	v_mov_b32_e32 v102, v115
	v_mov_b32_e32 v101, v115
	v_mov_b32_e32 v100, v115
	v_mov_b32_e32 v99, v115
	v_mov_b32_e32 v98, v115
	v_mov_b32_e32 v97, v115
	v_mov_b32_e32 v96, v115
	v_mov_b32_e32 v87, v115
	v_mov_b32_e32 v86, v115
	v_mov_b32_e32 v85, v115
	v_mov_b32_e32 v84, v115
	v_mov_b32_e32 v83, v115
	v_mov_b32_e32 v82, v115
	v_mov_b32_e32 v81, v115
	v_mov_b32_e32 v80, v115
	v_mov_b32_e32 v71, v115
	v_mov_b32_e32 v70, v115
	v_mov_b32_e32 v69, v115
	v_mov_b32_e32 v68, v115
	v_mov_b32_e32 v67, v115
	v_mov_b32_e32 v66, v115
	v_mov_b32_e32 v65, v115
	v_mov_b32_e32 v64, v115
	v_mov_b32_e32 v127, v115
	v_mov_b32_e32 v126, v115
	v_mov_b32_e32 v125, v115
	v_mov_b32_e32 v124, v115
	v_mov_b32_e32 v123, v115
	v_mov_b32_e32 v122, v115
	v_mov_b32_e32 v121, v115
	v_mov_b32_e32 v120, v115
	v_mov_b32_e32 v111, v115
	v_mov_b32_e32 v110, v115
	v_mov_b32_e32 v109, v115
	v_mov_b32_e32 v108, v115
	v_mov_b32_e32 v107, v115
	v_mov_b32_e32 v106, v115
	v_mov_b32_e32 v105, v115
	v_mov_b32_e32 v104, v115
	v_mov_b32_e32 v95, v115
	v_mov_b32_e32 v94, v115
	v_mov_b32_e32 v93, v115
	v_mov_b32_e32 v92, v115
	v_mov_b32_e32 v91, v115
	v_mov_b32_e32 v90, v115
	v_mov_b32_e32 v89, v115
	v_mov_b32_e32 v88, v115
	v_mov_b32_e32 v79, v115
	v_mov_b32_e32 v78, v115
	v_mov_b32_e32 v77, v115
	v_mov_b32_e32 v76, v115
	v_mov_b32_e32 v75, v115
	v_mov_b32_e32 v74, v115
	v_mov_b32_e32 v73, v115
	v_mov_b32_e32 v72, v115
	v_mov_b32_e32 v55, v115
	v_mov_b32_e32 v54, v115
	v_mov_b32_e32 v53, v115
	v_mov_b32_e32 v52, v115
	v_mov_b32_e32 v51, v115
	v_mov_b32_e32 v50, v115
	v_mov_b32_e32 v49, v115
	v_mov_b32_e32 v48, v115
	v_mov_b32_e32 v39, v115
	v_mov_b32_e32 v38, v115
	v_mov_b32_e32 v37, v115
	v_mov_b32_e32 v36, v115
	v_mov_b32_e32 v35, v115
	v_mov_b32_e32 v34, v115
	v_mov_b32_e32 v33, v115
	v_mov_b32_e32 v32, v115
	v_mov_b32_e32 v23, v115
	v_mov_b32_e32 v22, v115
	v_mov_b32_e32 v21, v115
	v_mov_b32_e32 v20, v115
	v_mov_b32_e32 v19, v115
	v_mov_b32_e32 v18, v115
	v_mov_b32_e32 v17, v115
	v_mov_b32_e32 v16, v115
	v_mov_b32_e32 v7, v115
	v_mov_b32_e32 v6, v115
	v_mov_b32_e32 v5, v115
	v_mov_b32_e32 v4, v115
	v_mov_b32_e32 v3, v115
	v_mov_b32_e32 v2, v115
	v_mov_b32_e32 v1, v115
	v_mov_b32_e32 v0, v115
	v_mov_b32_e32 v63, v115
	v_mov_b32_e32 v62, v115
	v_mov_b32_e32 v61, v115
	v_mov_b32_e32 v60, v115
	v_mov_b32_e32 v59, v115
	v_mov_b32_e32 v58, v115
	v_mov_b32_e32 v57, v115
	v_mov_b32_e32 v56, v115
	v_mov_b32_e32 v47, v115
	v_mov_b32_e32 v46, v115
	v_mov_b32_e32 v45, v115
	v_mov_b32_e32 v44, v115
	v_mov_b32_e32 v43, v115
	v_mov_b32_e32 v42, v115
	v_mov_b32_e32 v41, v115
	v_mov_b32_e32 v40, v115
	v_mov_b32_e32 v31, v115
	v_mov_b32_e32 v30, v115
	v_mov_b32_e32 v29, v115
	v_mov_b32_e32 v28, v115
	v_mov_b32_e32 v27, v115
	v_mov_b32_e32 v26, v115
	v_mov_b32_e32 v25, v115
	v_mov_b32_e32 v24, v115
	v_mov_b32_e32 v15, v115
	v_mov_b32_e32 v14, v115
	v_mov_b32_e32 v13, v115
	v_mov_b32_e32 v12, v115
	v_mov_b32_e32 v11, v115
	v_mov_b32_e32 v10, v115
	v_mov_b32_e32 v9, v115
	v_mov_b32_e32 v8, v115
	s_branch .LBB0_629
.LBB0_645:
	s_waitcnt vmcnt(0)
	v_readlane_b32 s0, v252, 54
	v_readlane_b32 s96, v252, 38
	v_readlane_b32 s52, v252, 40
	s_cmpk_gt_u32 s0, 0xff
	v_readlane_b32 s97, v252, 39
	v_readlane_b32 s54, v252, 42
	v_readlane_b32 s55, v252, 43
	v_readlane_b32 s56, v252, 44
	v_readlane_b32 s57, v252, 45
	v_readlane_b32 s53, v252, 41
	v_readlane_b32 s58, v252, 46
	v_readlane_b32 s59, v252, 47
	s_cbranch_scc1 .LBB0_647
	s_barrier

;     __device__ __forceinline__ size_t a_off(const Unit& u) const { return (size_t)u.pm * atile; }
;     __device__ __forceinline__ size_t b_off(const Unit& u) const { return (size_t)u.pn * btile; }
;     __device__ __forceinline__ bool next(int i, Unit& u) const { const long L = (long)i * G + c; if (L >= NG * 8) return false; u.g = (int)(L >> 3); u.pm = (int)(L & 7); u.pn = 0; return true; }
;     __device__ __forceinline__ size_t a_off(const Unit& u) const { return ((size_t)u.g * NROW + (size_t)u.pm * BM) * KA * 2; }
;     __device__ __forceinline__ size_t b_off(const Unit& u) const { return (size_t)u.g * btile; }
;     __device__ __forceinline__ bool next(int i, Unit& u) const { if (i >= 2) return false; u.g = g; u.pm = 2 * b + i; u.pn = 0; return true; }
;     __device__ __forceinline__ size_t a_off(const Unit& u) const { return ((size_t)u.g * NROW + (size_t)u.pm * BM) * KA * 2; }
;     __device__ __forceinline__ size_t b_off(const Unit& u) const { return (size_t)u.g * btile; }
; #define PG8_LDA(dst, b, h) do { _Pragma("unroll") for (int m = 0; m < 4; ++m) _Pragma("unroll") for (int k = 0; k < 2; ++k) dst[m][k] = *(const LAS bf16x8*)(lds + PG8_SA(b, h) + aoff + m * 2048 + k * 1024); } while (0)
; #define PG8_WAIT_L(n) asm volatile("s_waitcnt lgkmcnt(" #n ")" ::: "memory")
; #define PG8_BAR __builtin_amdgcn_s_barrier()
;     ...
;         const bool has_next = S.next(ui + 1, nxt);
;         const char* nA = has_next ? (const char*)Ap + S.a_off(nxt) : cA; const char* nB = has_next ? (const char*)Btp + S.b_off(nxt) : cB;
;         for (int t = 0; t < nt; t += 2) {
;             const bool last = (t == nt - 2);
;             const char* a1 = cA + (size_t)(t + 1) * kstep;
;             const char* a2 = last ? nA : cA + (size_t)(t + 2) * kstep; const char* b2 = last ? nB : cB + (size_t)(t + 2) * kstep;
;             const char* a3 = a2 + kstep; const char* b3 = b2 + kstep;
;             PG8_LDB(B0, 0, 0); PG8_SCHED; PG8_LDA(At, 0, 0); PG8_STAGE(PG8_SA(1, 1), a1 + hstepA, voffA);
;             PG8_WAIT_L(8); PG8_BAR; PG8_WAIT_L(0); PG8_MMA(0, 0, At, B0); PG8_BAR; PG8_SCHED;
;             PG8_LDB(B1, 0, 1); PG8_STAGE(PG8_SB(0, 0), b2, voffB);
;             PG8_BAR; PG8_WAIT_L(0); PG8_MMA(0, 1, At, B1); PG8_BAR;
;             PG8_LDA(At, 0, 1); PG8_STAGE(PG8_SA(0, 0), a2, voffA);
;             PG8_BAR; PG8_WAIT_L(0); PG8_MMA(1, 0, At, B0); PG8_BAR; PG8_SCHED;
.Lnext_done_17625:
.LBB0_688:
	s_ashr_i32 s59, s58, 31
	s_lshl_b64 s[16:17], s[58:59], 19
	s_add_u32 s64, s20, s16
	s_addc_u32 s65, s21, s17
	s_ashr_i32 s53, s52, 31
	s_lshl_b64 s[16:17], s[52:53], 19
	s_add_u32 s66, s76, s16
	v_cmp_lt_i64_e64 s[12:13], s[12:13], v[170:171]
	s_addc_u32 s67, s77, s17
	s_andn2_b64 vcc, exec, s[50:51]
	s_cbranch_vccnz .Lkzero_690
	s_and_b64 s[16:17], s[12:13], exec
	s_cselect_b32 s53, s65, s27
	s_cselect_b32 s59, s64, s26
	s_cselect_b32 s96, s67, s25
	s_cselect_b32 s97, s66, s24
	s_add_u32 vcc_lo, s26, 0x100
	s_addc_u32 vcc_hi, s27, 0
	s_add_u32 s3, s24, 0x100
	s_addc_u32 s46, s25, 0
	s_mov_b32 s16, 0
	ds_read_b128 v[76:79], v193
	ds_read_b128 v[88:91], v193 offset:1024
	ds_read_b128 v[92:95], v193 offset:2048
	ds_read_b128 v[128:131], v193 offset:3072
	s_add_i32 s22, s16, 2
	s_cmp_eq_u32 s91, s16
	s_cselect_b32 s36, s59, vcc_lo
	s_cselect_b32 s26, s53, vcc_hi
	s_cselect_b32 s25, s96, s46
	s_cselect_b32 s28, s97, s3
	s_add_u32 s24, s36, 0x80
	s_addc_u32 s23, s26, 0
	s_add_u32 s16, vcc_lo, s0
	s_addc_u32 s17, vcc_hi, s1
	s_add_u32 s16, s16, 0xffffff80
	s_addc_u32 s17, s17, -1
	s_and_b32 s17, s17, 0xffff
	s_mov_b32 m0, s92
	ds_read_b128 v[132:135], v194
	ds_read_b128 v[136:139], v194 offset:1024
	ds_read_b128 v[140:143], v194 offset:2048
	ds_read_b128 v[174:177], v194 offset:3072
	ds_read_b128 v[178:181], v194 offset:4096
	ds_read_b128 v[182:185], v194 offset:5120
	ds_read_b128 v[202:205], v194 offset:6144
	ds_read_b128 v[206:209], v194 offset:7168
	buffer_load_dwordx4 v186, s[16:19], 0 offen lds
	s_mov_b32 m0, s93
	s_nop 0
	buffer_load_dwordx4 v188, s[16:19], 0 offen lds
	s_waitcnt lgkmcnt(8)
	s_barrier
	s_waitcnt lgkmcnt(0)
	s_setprio 1
	s_waitcnt lgkmcnt(7)
	v_mfma_f32_16x16x32_bf16 v[152:155], v[76:79], v[132:135], 0
	v_mfma_f32_16x16x32_bf16 v[144:147], v[92:95], v[132:135], 0
	s_waitcnt lgkmcnt(5)
	v_mfma_f32_16x16x32_bf16 v[124:127], v[76:79], v[140:143], 0
	v_mfma_f32_16x16x32_bf16 v[120:123], v[92:95], v[140:143], 0
	s_waitcnt lgkmcnt(3)
	v_mfma_f32_16x16x32_bf16 v[108:111], v[76:79], v[178:181], 0
	v_mfma_f32_16x16x32_bf16 v[104:107], v[92:95], v[178:181], 0
	s_waitcnt lgkmcnt(1)
	v_mfma_f32_16x16x32_bf16 v[84:87], v[76:79], v[202:205], 0
	v_mfma_f32_16x16x32_bf16 v[80:83], v[92:95], v[202:205], 0
	v_mfma_f32_16x16x32_bf16 v[152:155], v[88:91], v[136:139], v[152:155]
	v_mfma_f32_16x16x32_bf16 v[144:147], v[128:131], v[136:139], v[144:147]
	v_mfma_f32_16x16x32_bf16 v[124:127], v[88:91], v[174:177], v[124:127]
	v_mfma_f32_16x16x32_bf16 v[120:123], v[128:131], v[174:177], v[120:123]
	v_mfma_f32_16x16x32_bf16 v[108:111], v[88:91], v[182:185], v[108:111]
	v_mfma_f32_16x16x32_bf16 v[104:107], v[128:131], v[182:185], v[104:107]
	s_waitcnt lgkmcnt(0)
	v_mfma_f32_16x16x32_bf16 v[84:87], v[88:91], v[206:209], v[84:87]
	v_mfma_f32_16x16x32_bf16 v[80:83], v[128:131], v[206:209], v[80:83]
	s_setprio 0
	s_barrier
	s_and_b32 s29, s25, 0xffff
	s_mov_b32 s30, s18
	s_mov_b32 s31, s19
	s_mov_b32 m0, s73
	ds_read_b128 v[210:213], v195
	ds_read_b128 v[214:217], v195 offset:1024
	ds_read_b128 v[218:221], v195 offset:2048
	ds_read_b128 v[222:225], v195 offset:3072
	buffer_load_dwordx4 v187, s[28:31], 0 offen lds
	s_mov_b32 m0, s78
	s_nop 0
	buffer_load_dwordx4 v189, s[28:31], 0 offen lds
	s_barrier
; #define PG8_STAGE(bufoff, gbase, voff) do { const __amdgpu_buffer_rsrc_t _r = __builtin_amdgcn_make_buffer_rsrc((void*)(gbase), (short)0, 0x7fffffff, 0x00020000); _Pragma("unroll") for (int _i = 0; _i < 2; ++_i) \
;         __builtin_amdgcn_raw_ptr_buffer_load_lds(_r, (LAS unsigned*)(lds + (bufoff) + ldsw + _i * 8192), 16, (int)(voff)[_i], 0, 0, 0); } while (0)
; #define PG8_LDA(dst, b, h) do { _Pragma("unroll") for (int m = 0; m < 4; ++m) _Pragma("unroll") for (int k = 0; k < 2; ++k) dst[m][k] = *(const LAS bf16x8*)(lds + PG8_SA(b, h) + aoff + m * 2048 + k * 1024); } while (0)
; #define PG8_LDB(dst, b, h) do { _Pragma("unroll") for (int n = 0; n < 2; ++n) _Pragma("unroll") for (int k = 0; k < 2; ++k) dst[n][k] = *(const LAS bf16x8*)(lds + PG8_SB(b, h) + boff + n * 2048 + k * 1024); } while (0)
; #define PG8_MMA(ai, bj, At, Bt) do { __builtin_amdgcn_s_setprio(1); _Pragma("unroll") for (int k = 0; k < 2; ++k) _Pragma("unroll") for (int m = 0; m < 4; ++m) _Pragma("unroll") for (int n = 0; n < ((bj) == 1 ? NB1 : 2); ++n) \
;         acc[ai][bj][m][n] = __builtin_amdgcn_mfma_f32_16x16x32_bf16(Bt[n][k], At[m][k], acc[ai][bj][m][n], 0, 0, 0); __builtin_amdgcn_s_setprio(0); } while (0)
; #define PG8_WAIT_V(n) asm volatile("s_waitcnt vmcnt(" #n ")" ::: "memory")
; #define PG8_WAIT_L(n) asm volatile("s_waitcnt lgkmcnt(" #n ")" ::: "memory")
; #define PG8_BAR __builtin_amdgcn_s_barrier()
; #define PG8_SCHED __builtin_amdgcn_sched_barrier(0)
;     ...
;             PG8_BAR; PG8_WAIT_L(0); PG8_MMA(1, 0, At, B0); PG8_BAR; PG8_SCHED;
;             PG8_STAGE(PG8_SB(0, 1), b2 + hstepB, voffB);
;             PG8_WAIT_V(6); PG8_BAR; PG8_MMA(1, 1, At, B1); PG8_BAR;
;             PG8_LDB(B0, 1, 0); PG8_SCHED; PG8_LDA(At, 1, 0); PG8_STAGE(PG8_SA(0, 1), a2 + hstepA, voffA);
;             PG8_WAIT_L(8); PG8_BAR; PG8_WAIT_L(0); PG8_MMA(0, 0, At, B0); PG8_BAR; PG8_SCHED;
;             PG8_LDB(B1, 1, 1); PG8_STAGE(PG8_SB(1, 0), b3, voffB);
;             PG8_BAR; PG8_WAIT_L(0); PG8_MMA(0, 1, At, B1); PG8_BAR;
;             PG8_LDA(At, 1, 1); PG8_STAGE(PG8_SA(1, 0), a3, voffA);
;             PG8_BAR; PG8_WAIT_L(0); PG8_MMA(1, 0, At, B0); PG8_BAR; PG8_SCHED;
;             PG8_STAGE(PG8_SB(1, 1), b3 + hstepB, voffB);
;             PG8_WAIT_V(6); PG8_BAR; PG8_MMA(1, 1, At, B1); PG8_BAR;
	s_waitcnt lgkmcnt(0)
	s_setprio 1
	s_waitcnt lgkmcnt(3)
	v_mfma_f32_16x16x32_bf16 v[116:119], v[210:213], v[140:143], 0
	s_waitcnt lgkmcnt(1)
	v_mfma_f32_16x16x32_bf16 v[112:115], v[218:221], v[140:143], 0
	v_mfma_f32_16x16x32_bf16 v[100:103], v[210:213], v[178:181], 0
	v_mfma_f32_16x16x32_bf16 v[96:99], v[218:221], v[178:181], 0
	v_mfma_f32_16x16x32_bf16 v[68:71], v[210:213], v[202:205], 0
	v_mfma_f32_16x16x32_bf16 v[64:67], v[218:221], v[202:205], 0
	v_mfma_f32_16x16x32_bf16 v[156:159], v[210:213], v[132:135], 0
	v_mfma_f32_16x16x32_bf16 v[132:135], v[218:221], v[132:135], 0
	v_mfma_f32_16x16x32_bf16 v[116:119], v[214:217], v[174:177], v[116:119]
	s_waitcnt lgkmcnt(0)
	v_mfma_f32_16x16x32_bf16 v[112:115], v[222:225], v[174:177], v[112:115]
	v_mfma_f32_16x16x32_bf16 v[100:103], v[214:217], v[182:185], v[100:103]
	v_mfma_f32_16x16x32_bf16 v[96:99], v[222:225], v[182:185], v[96:99]
	v_mfma_f32_16x16x32_bf16 v[68:71], v[214:217], v[206:209], v[68:71]
	v_mfma_f32_16x16x32_bf16 v[64:67], v[222:225], v[206:209], v[64:67]
	v_mfma_f32_16x16x32_bf16 v[140:143], v[214:217], v[136:139], v[156:159]
	v_mfma_f32_16x16x32_bf16 v[132:135], v[222:225], v[136:139], v[132:135]
	s_setprio 0
	s_and_b32 s37, s26, 0xffff
	s_mov_b32 s38, s18
	s_mov_b32 s39, s19
	s_mov_b32 m0, s71
	s_barrier
	ds_read_b128 v[136:139], v194 offset:16384
	ds_read_b128 v[148:151], v194 offset:17408
	ds_read_b128 v[156:159], v194 offset:18432
	ds_read_b128 v[174:177], v194 offset:19456
	ds_read_b128 v[178:181], v194 offset:20480
	ds_read_b128 v[182:185], v194 offset:21504
	ds_read_b128 v[202:205], v194 offset:22528
	ds_read_b128 v[206:209], v194 offset:23552
	buffer_load_dwordx4 v186, s[36:39], 0 offen lds
	s_mov_b32 m0, s79
	s_nop 0
	buffer_load_dwordx4 v188, s[36:39], 0 offen lds
	s_barrier
	s_waitcnt lgkmcnt(0)
	s_setprio 1
	s_waitcnt lgkmcnt(7)
	v_mfma_f32_16x16x32_bf16 v[60:63], v[76:79], v[136:139], 0
	v_mfma_f32_16x16x32_bf16 v[52:55], v[92:95], v[136:139], 0
	s_waitcnt lgkmcnt(5)
	v_mfma_f32_16x16x32_bf16 v[44:47], v[76:79], v[156:159], 0
	v_mfma_f32_16x16x32_bf16 v[40:43], v[92:95], v[156:159], 0
	s_waitcnt lgkmcnt(3)
	v_mfma_f32_16x16x32_bf16 v[28:31], v[76:79], v[178:181], 0
	v_mfma_f32_16x16x32_bf16 v[24:27], v[92:95], v[178:181], 0
	s_waitcnt lgkmcnt(1)
	v_mfma_f32_16x16x32_bf16 v[12:15], v[76:79], v[202:205], 0
	v_mfma_f32_16x16x32_bf16 v[8:11], v[92:95], v[202:205], 0
	v_mfma_f32_16x16x32_bf16 v[60:63], v[88:91], v[148:151], v[60:63]
	v_mfma_f32_16x16x32_bf16 v[52:55], v[128:131], v[148:151], v[52:55]
	v_mfma_f32_16x16x32_bf16 v[44:47], v[88:91], v[174:177], v[44:47]
	v_mfma_f32_16x16x32_bf16 v[40:43], v[128:131], v[174:177], v[40:43]
	v_mfma_f32_16x16x32_bf16 v[28:31], v[88:91], v[182:185], v[28:31]
	v_mfma_f32_16x16x32_bf16 v[24:27], v[128:131], v[182:185], v[24:27]
	s_waitcnt lgkmcnt(0)
	v_mfma_f32_16x16x32_bf16 v[12:15], v[88:91], v[206:209], v[12:15]
	v_mfma_f32_16x16x32_bf16 v[8:11], v[128:131], v[206:209], v[8:11]
	s_setprio 0
	s_barrier
	s_add_u32 s16, s28, s44
	s_addc_u32 s74, s25, s45
	s_and_b32 s17, s74, 0xffff
	s_mov_b32 m0, s80
	s_nop 0
	buffer_load_dwordx4 v187, s[16:19], 0 offen lds
	s_mov_b32 m0, s81
	s_nop 0
	buffer_load_dwordx4 v189, s[16:19], 0 offen lds
	s_waitcnt vmcnt(6)
	s_barrier
	s_setprio 1
	v_mfma_f32_16x16x32_bf16 v[56:59], v[210:213], v[136:139], 0
	v_mfma_f32_16x16x32_bf16 v[48:51], v[218:221], v[136:139], 0
	v_mfma_f32_16x16x32_bf16 v[36:39], v[210:213], v[156:159], 0
	v_mfma_f32_16x16x32_bf16 v[32:35], v[218:221], v[156:159], 0
	v_mfma_f32_16x16x32_bf16 v[20:23], v[210:213], v[178:181], 0
	v_mfma_f32_16x16x32_bf16 v[16:19], v[218:221], v[178:181], 0
	v_mfma_f32_16x16x32_bf16 v[4:7], v[210:213], v[202:205], 0
	v_mfma_f32_16x16x32_bf16 v[0:3], v[218:221], v[202:205], 0
	v_mfma_f32_16x16x32_bf16 v[56:59], v[214:217], v[148:151], v[56:59]
	v_mfma_f32_16x16x32_bf16 v[48:51], v[222:225], v[148:151], v[48:51]
	v_mfma_f32_16x16x32_bf16 v[36:39], v[214:217], v[174:177], v[36:39]
	v_mfma_f32_16x16x32_bf16 v[32:35], v[222:225], v[174:177], v[32:35]
	v_mfma_f32_16x16x32_bf16 v[20:23], v[214:217], v[182:185], v[20:23]
	v_mfma_f32_16x16x32_bf16 v[16:19], v[222:225], v[182:185], v[16:19]
	v_mfma_f32_16x16x32_bf16 v[4:7], v[214:217], v[206:209], v[4:7]
	v_mfma_f32_16x16x32_bf16 v[0:3], v[222:225], v[206:209], v[0:3]
	s_setprio 0
	s_barrier
	s_branch .Lkmid_690
	.p2align 6
	s_nop 0
	s_nop 0

; #define PG8_WAIT_V(n) asm volatile("s_waitcnt vmcnt(" #n ")" ::: "memory")
; #define PG8_BAR __builtin_amdgcn_s_barrier()
;     __device__ __forceinline__ f32x4 prefetch(const Unit&, int, int, int) const { return (f32x4){0.f, 0.f, 0.f, 0.f}; }
;     __device__ __forceinline__ f32x4 prefetch(const Unit&, int, int, int) const { return (f32x4){0.f, 0.f, 0.f, 0.f}; }
;     __device__ __forceinline__ f32x4 prefetch(const Unit&, int, int, int) const { return (f32x4){0.f, 0.f, 0.f, 0.f}; }
;     __device__ __forceinline__ f32x4 prefetch(const Unit&, int, int, int) const { return (f32x4){0.f, 0.f, 0.f, 0.f}; }
;     ...
;         if (has_next) epar = E.prefetch(nxt, wr, wc, lane);
;         if (!has_next) break;
; #pragma unroll
;         for (int a = 0; a < 2; ++a)
; #pragma unroll
;             for (int b = 0; b < 2; ++b)
; #pragma unroll
;                 for (int m = 0; m < 4; ++m)
; #pragma unroll
;                     for (int n = 0; n < 2; ++n) acc[a][b][m][n] = (f32x4){0.f, 0.f, 0.f, 0.f};
;         cur = nxt; cA = nA; cB = nB; ++ui;
;     }
;     PG8_WAIT_V(0);
;     if (wr == 0) PG8_BAR;
;     PG8_BAR;
;     __device__ __forceinline__ f32x4 prefetch(const Unit& u, int wr, int wc, int lane) const {
;         const float* ptr;
;         if (lane < 32) { const int arr = lane >> 3, j = lane & 7;
;             if (MODE == 0) ptr = (arr < 3 ? cw + arr * C : cb) + u.pn * 128 + wc * 32 + 4 * j;
;             else ptr = cw + (arr < 3 ? arr : 0) * C + u.pn * 64 + wc * 16 + 4 * (j & 3); }
;         else { const int k = lane - 32; ptr = ssq + u.pm * BM + (k >> 4) * HALF + wr * 64 + 4 * (k & 15); }
;         f32x4 v; asm volatile("global_load_dwordx4 %0, %1, off" : "=&v"(v) : "v"(ptr) : "memory"); return v;
.LBB0_704:
	s_or_b64 exec, exec, s[24:25]
	s_mov_b64 s[16:17], -1
	s_and_b64 vcc, exec, s[12:13]
	s_cbranch_vccz .LBB0_685
	s_lshl_b32 s3, s58, 8
	s_lshl_b32 s12, s52, 7
	v_mov_b32_e32 v0, s3
	v_mov_b32_e32 v1, s12
	v_cndmask_b32_e64 v0, v0, v1, s[4:5]
	v_ashrrev_i32_e32 v1, 31, v0
	v_lshl_add_u64 v[0:1], v[0:1], 2, v[168:169]
	v_lshl_add_u64 v[0:1], v[0:1], 0, v[160:161]
	global_load_dwordx4 v[72:75], v[0:1], off
	s_mov_b64 s[16:17], 0
	s_branch .LBB0_685
.Lkzero_690:
	v_mov_b32_e32 v155, 0
	v_mov_b32_e32 v154, v155
	v_mov_b32_e32 v153, v155
	v_mov_b32_e32 v152, v155
	v_mov_b32_e32 v147, v155
	v_mov_b32_e32 v146, v155
	v_mov_b32_e32 v145, v155
	v_mov_b32_e32 v144, v155
	v_mov_b32_e32 v127, v155
	v_mov_b32_e32 v126, v155
	v_mov_b32_e32 v125, v155
	v_mov_b32_e32 v124, v155
	v_mov_b32_e32 v123, v155
	v_mov_b32_e32 v122, v155
	v_mov_b32_e32 v121, v155
	v_mov_b32_e32 v120, v155
	v_mov_b32_e32 v111, v155
	v_mov_b32_e32 v110, v155
	v_mov_b32_e32 v109, v155
	v_mov_b32_e32 v108, v155
	v_mov_b32_e32 v107, v155
	v_mov_b32_e32 v106, v155
	v_mov_b32_e32 v105, v155
	v_mov_b32_e32 v104, v155
	v_mov_b32_e32 v87, v155
	v_mov_b32_e32 v86, v155
	v_mov_b32_e32 v85, v155
	v_mov_b32_e32 v84, v155
	v_mov_b32_e32 v83, v155
	v_mov_b32_e32 v82, v155
	v_mov_b32_e32 v81, v155
	v_mov_b32_e32 v80, v155
	v_mov_b32_e32 v159, v155
	v_mov_b32_e32 v158, v155
	v_mov_b32_e32 v157, v155
	v_mov_b32_e32 v156, v155
	v_mov_b32_e32 v151, v155
	v_mov_b32_e32 v150, v155
	v_mov_b32_e32 v149, v155
	v_mov_b32_e32 v148, v155
	v_mov_b32_e32 v119, v155
	v_mov_b32_e32 v118, v155
	v_mov_b32_e32 v117, v155
	v_mov_b32_e32 v116, v155
	v_mov_b32_e32 v115, v155
	v_mov_b32_e32 v114, v155
	v_mov_b32_e32 v113, v155
	v_mov_b32_e32 v112, v155
	v_mov_b32_e32 v103, v155
	v_mov_b32_e32 v102, v155
	v_mov_b32_e32 v101, v155
	v_mov_b32_e32 v100, v155
	v_mov_b32_e32 v99, v155
	v_mov_b32_e32 v98, v155
	v_mov_b32_e32 v97, v155
	v_mov_b32_e32 v96, v155
	v_mov_b32_e32 v71, v155
	v_mov_b32_e32 v70, v155
	v_mov_b32_e32 v69, v155
	v_mov_b32_e32 v68, v155
	v_mov_b32_e32 v67, v155
	v_mov_b32_e32 v66, v155
	v_mov_b32_e32 v65, v155
	v_mov_b32_e32 v64, v155
	v_mov_b32_e32 v63, v155
	v_mov_b32_e32 v62, v155
	v_mov_b32_e32 v61, v155
	v_mov_b32_e32 v60, v155
	v_mov_b32_e32 v55, v155
	v_mov_b32_e32 v54, v155
	v_mov_b32_e32 v53, v155
	v_mov_b32_e32 v52, v155
	v_mov_b32_e32 v47, v155
	v_mov_b32_e32 v46, v155
	v_mov_b32_e32 v45, v155
	v_mov_b32_e32 v44, v155
	v_mov_b32_e32 v43, v155
	v_mov_b32_e32 v42, v155
	v_mov_b32_e32 v41, v155
	v_mov_b32_e32 v40, v155
	v_mov_b32_e32 v31, v155
	v_mov_b32_e32 v30, v155
	v_mov_b32_e32 v29, v155
	v_mov_b32_e32 v28, v155
	v_mov_b32_e32 v27, v155
	v_mov_b32_e32 v26, v155
	v_mov_b32_e32 v25, v155
	v_mov_b32_e32 v24, v155
	v_mov_b32_e32 v15, v155
	v_mov_b32_e32 v14, v155
	v_mov_b32_e32 v13, v155
	v_mov_b32_e32 v12, v155
	v_mov_b32_e32 v11, v155
	v_mov_b32_e32 v10, v155
	v_mov_b32_e32 v9, v155
	v_mov_b32_e32 v8, v155
	v_mov_b32_e32 v59, v155
	v_mov_b32_e32 v58, v155
	v_mov_b32_e32 v57, v155
	v_mov_b32_e32 v56, v155
	v_mov_b32_e32 v51, v155
	v_mov_b32_e32 v50, v155
	v_mov_b32_e32 v49, v155
	v_mov_b32_e32 v48, v155
	v_mov_b32_e32 v39, v155
	v_mov_b32_e32 v38, v155
	v_mov_b32_e32 v37, v155
	v_mov_b32_e32 v36, v155
	v_mov_b32_e32 v35, v155
	v_mov_b32_e32 v34, v155
	v_mov_b32_e32 v33, v155
	v_mov_b32_e32 v32, v155
	v_mov_b32_e32 v23, v155
	v_mov_b32_e32 v22, v155
	v_mov_b32_e32 v21, v155
	v_mov_b32_e32 v20, v155
	v_mov_b32_e32 v19, v155
	v_mov_b32_e32 v18, v155
	v_mov_b32_e32 v17, v155
	v_mov_b32_e32 v16, v155
	v_mov_b32_e32 v7, v155
	v_mov_b32_e32 v6, v155
	v_mov_b32_e32 v5, v155
	v_mov_b32_e32 v4, v155
	v_mov_b32_e32 v3, v155
	v_mov_b32_e32 v2, v155
	v_mov_b32_e32 v1, v155
	v_mov_b32_e32 v0, v155
	s_branch .LBB0_692
.LBB0_706:
	s_waitcnt vmcnt(0)
	s_cmpk_gt_u32 s48, 0xff
	s_cbranch_scc1 .LBB0_708
	s_barrier

; #define PG8_STAGE(bufoff, gbase, voff) do { const __amdgpu_buffer_rsrc_t _r = __builtin_amdgcn_make_buffer_rsrc((void*)(gbase), (short)0, 0x7fffffff, 0x00020000); _Pragma("unroll") for (int _i = 0; _i < 2; ++_i) \
;         __builtin_amdgcn_raw_ptr_buffer_load_lds(_r, (LAS unsigned*)(lds + (bufoff) + ldsw + _i * 8192), 16, (int)(voff)[_i], 0, 0, 0); } while (0)
; #define PG8_LDA(dst, b, h) do { _Pragma("unroll") for (int m = 0; m < 4; ++m) _Pragma("unroll") for (int k = 0; k < 2; ++k) dst[m][k] = *(const LAS bf16x8*)(lds + PG8_SA(b, h) + aoff + m * 2048 + k * 1024); } while (0)
; #define PG8_LDB(dst, b, h) do { _Pragma("unroll") for (int n = 0; n < 2; ++n) _Pragma("unroll") for (int k = 0; k < 2; ++k) dst[n][k] = *(const LAS bf16x8*)(lds + PG8_SB(b, h) + boff + n * 2048 + k * 1024); } while (0)
; #define PG8_MMA(ai, bj, At, Bt) do { __builtin_amdgcn_s_setprio(1); _Pragma("unroll") for (int k = 0; k < 2; ++k) _Pragma("unroll") for (int m = 0; m < 4; ++m) _Pragma("unroll") for (int n = 0; n < ((bj) == 1 ? NB1 : 2); ++n) \
;         acc[ai][bj][m][n] = __builtin_amdgcn_mfma_f32_16x16x32_bf16(Bt[n][k], At[m][k], acc[ai][bj][m][n], 0, 0, 0); __builtin_amdgcn_s_setprio(0); } while (0)
; #define PG8_WAIT_V(n) asm volatile("s_waitcnt vmcnt(" #n ")" ::: "memory")
; #define PG8_WAIT_L(n) asm volatile("s_waitcnt lgkmcnt(" #n ")" ::: "memory")
; #define PG8_BAR __builtin_amdgcn_s_barrier()
;     ...
;         for (int t = 0; t < nt; t += 2) {
;             const bool last = (t == nt - 2);
;             const char* a1 = cA + (size_t)(t + 1) * kstep;
;             const char* a2 = last ? nA : cA + (size_t)(t + 2) * kstep; const char* b2 = last ? nB : cB + (size_t)(t + 2) * kstep;
;             const char* a3 = a2 + kstep; const char* b3 = b2 + kstep;
;             PG8_LDB(B0, 0, 0); PG8_SCHED; PG8_LDA(At, 0, 0); PG8_STAGE(PG8_SA(1, 1), a1 + hstepA, voffA);
;             PG8_WAIT_L(8); PG8_BAR; PG8_WAIT_L(0); PG8_MMA(0, 0, At, B0); PG8_BAR; PG8_SCHED;
;             PG8_LDB(B1, 0, 1); PG8_STAGE(PG8_SB(0, 0), b2, voffB);
;             PG8_BAR; PG8_WAIT_L(0); PG8_MMA(0, 1, At, B1); PG8_BAR;
;             PG8_LDA(At, 0, 1); PG8_STAGE(PG8_SA(0, 0), a2, voffA);
;             PG8_BAR; PG8_WAIT_L(0); PG8_MMA(1, 0, At, B0); PG8_BAR; PG8_SCHED;
;             PG8_STAGE(PG8_SB(0, 1), b2 + hstepB, voffB);
;             PG8_WAIT_V(6); PG8_BAR; PG8_MMA(1, 1, At, B1); PG8_BAR;
.LBB0_770:
	s_andn2_b64 vcc, exec, s[46:47]
	s_waitcnt lgkmcnt(0)
	s_cbranch_vccnz .Lkzero_772
	s_add_u32 s89, s18, 0x100
	s_addc_u32 s90, s19, 0
	s_add_u32 s91, s16, 0x100
	s_addc_u32 s92, s17, 0
	s_mov_b32 s8, 0
	ds_read_b128 v[128:131], v227
	ds_read_b128 v[132:135], v227 offset:1024
	ds_read_b128 v[136:139], v227 offset:2048
	ds_read_b128 v[140:143], v227 offset:3072
	s_add_i32 s22, s8, 2
	s_cmp_eq_u32 s81, s8
	s_cselect_b32 s28, s0, s89
	s_cselect_b32 s19, s1, s90
	s_cselect_b32 s18, s51, s92
	s_cselect_b32 s24, s50, s91
	s_add_u32 s16, s28, 0x80
	s_addc_u32 s17, s19, 0
	s_add_u32 s8, s89, s36
	s_addc_u32 s9, s90, s37
	s_add_u32 s8, s8, 0xffffff80
	s_addc_u32 s9, s9, -1
	s_and_b32 s9, s9, 0xffff
	s_mov_b32 m0, s82
	ds_read_b128 v[144:147], v228
	ds_read_b128 v[148:151], v228 offset:1024
	ds_read_b128 v[152:155], v228 offset:2048
	ds_read_b128 v[156:159], v228 offset:3072
	ds_read_b128 v[160:163], v228 offset:4096
	ds_read_b128 v[164:167], v228 offset:5120
	ds_read_b128 v[168:171], v228 offset:6144
	ds_read_b128 v[172:175], v228 offset:7168
	buffer_load_dwordx4 v222, s[8:11], 0 offen lds
	s_mov_b32 m0, s83
	s_nop 0
	buffer_load_dwordx4 v224, s[8:11], 0 offen lds
	s_waitcnt lgkmcnt(8)
	s_barrier
	s_waitcnt lgkmcnt(0)
	s_setprio 1
	s_waitcnt lgkmcnt(7)
	v_mfma_f32_16x16x32_bf16 v[120:123], v[128:131], v[144:147], 0
	v_mfma_f32_16x16x32_bf16 v[124:127], v[136:139], v[144:147], 0
	s_waitcnt lgkmcnt(5)
	v_mfma_f32_16x16x32_bf16 v[108:111], v[128:131], v[152:155], 0
	v_mfma_f32_16x16x32_bf16 v[104:107], v[136:139], v[152:155], 0
	s_waitcnt lgkmcnt(3)
	v_mfma_f32_16x16x32_bf16 v[92:95], v[128:131], v[160:163], 0
	v_mfma_f32_16x16x32_bf16 v[88:91], v[136:139], v[160:163], 0
	s_waitcnt lgkmcnt(1)
	v_mfma_f32_16x16x32_bf16 v[76:79], v[128:131], v[168:171], 0
	v_mfma_f32_16x16x32_bf16 v[72:75], v[136:139], v[168:171], 0
	v_mfma_f32_16x16x32_bf16 v[120:123], v[132:135], v[148:151], v[120:123]
	v_mfma_f32_16x16x32_bf16 v[124:127], v[140:143], v[148:151], v[124:127]
	v_mfma_f32_16x16x32_bf16 v[108:111], v[132:135], v[156:159], v[108:111]
	v_mfma_f32_16x16x32_bf16 v[104:107], v[140:143], v[156:159], v[104:107]
	v_mfma_f32_16x16x32_bf16 v[92:95], v[132:135], v[164:167], v[92:95]
	v_mfma_f32_16x16x32_bf16 v[88:91], v[140:143], v[164:167], v[88:91]
	s_waitcnt lgkmcnt(0)
	v_mfma_f32_16x16x32_bf16 v[76:79], v[132:135], v[172:175], v[76:79]
	v_mfma_f32_16x16x32_bf16 v[72:75], v[140:143], v[172:175], v[72:75]
	s_setprio 0
	s_barrier
	s_and_b32 s25, s18, 0xffff
	s_mov_b32 s26, s10
	s_mov_b32 s27, s11
	s_mov_b32 m0, s64
	ds_read_b128 v[176:179], v229
	ds_read_b128 v[180:183], v229 offset:1024
	ds_read_b128 v[192:195], v229 offset:2048
	ds_read_b128 v[196:199], v229 offset:3072
	buffer_load_dwordx4 v223, s[24:27], 0 offen lds
	s_mov_b32 m0, s65
	s_nop 0
	buffer_load_dwordx4 v225, s[24:27], 0 offen lds
	s_barrier
	s_waitcnt lgkmcnt(0)
	s_setprio 1
	s_waitcnt lgkmcnt(3)
	v_mfma_f32_16x16x32_bf16 v[116:119], v[176:179], v[144:147], 0
	s_waitcnt lgkmcnt(1)
	v_mfma_f32_16x16x32_bf16 v[112:115], v[192:195], v[144:147], 0
	v_mfma_f32_16x16x32_bf16 v[100:103], v[176:179], v[152:155], 0
	v_mfma_f32_16x16x32_bf16 v[96:99], v[192:195], v[152:155], 0
	v_mfma_f32_16x16x32_bf16 v[84:87], v[176:179], v[160:163], 0
	v_mfma_f32_16x16x32_bf16 v[80:83], v[192:195], v[160:163], 0
	v_mfma_f32_16x16x32_bf16 v[68:71], v[176:179], v[168:171], 0
	v_mfma_f32_16x16x32_bf16 v[64:67], v[192:195], v[168:171], 0
	v_mfma_f32_16x16x32_bf16 v[116:119], v[180:183], v[148:151], v[116:119]
	s_waitcnt lgkmcnt(0)
	v_mfma_f32_16x16x32_bf16 v[112:115], v[196:199], v[148:151], v[112:115]
	v_mfma_f32_16x16x32_bf16 v[100:103], v[180:183], v[156:159], v[100:103]
	v_mfma_f32_16x16x32_bf16 v[96:99], v[196:199], v[156:159], v[96:99]
	v_mfma_f32_16x16x32_bf16 v[84:87], v[180:183], v[164:167], v[84:87]
	v_mfma_f32_16x16x32_bf16 v[80:83], v[196:199], v[164:167], v[80:83]
	v_mfma_f32_16x16x32_bf16 v[68:71], v[180:183], v[172:175], v[68:71]
	v_mfma_f32_16x16x32_bf16 v[64:67], v[196:199], v[172:175], v[64:67]
	s_setprio 0
	s_and_b32 s29, s19, 0xffff
	s_mov_b32 s30, s10
	s_mov_b32 s31, s11
	s_mov_b32 m0, s59
	s_barrier
; #define PG8_STAGE(bufoff, gbase, voff) do { const __amdgpu_buffer_rsrc_t _r = __builtin_amdgcn_make_buffer_rsrc((void*)(gbase), (short)0, 0x7fffffff, 0x00020000); _Pragma("unroll") for (int _i = 0; _i < 2; ++_i) \
;         __builtin_amdgcn_raw_ptr_buffer_load_lds(_r, (LAS unsigned*)(lds + (bufoff) + ldsw + _i * 8192), 16, (int)(voff)[_i], 0, 0, 0); } while (0)
; #define PG8_LDA(dst, b, h) do { _Pragma("unroll") for (int m = 0; m < 4; ++m) _Pragma("unroll") for (int k = 0; k < 2; ++k) dst[m][k] = *(const LAS bf16x8*)(lds + PG8_SA(b, h) + aoff + m * 2048 + k * 1024); } while (0)
; #define PG8_LDB(dst, b, h) do { _Pragma("unroll") for (int n = 0; n < 2; ++n) _Pragma("unroll") for (int k = 0; k < 2; ++k) dst[n][k] = *(const LAS bf16x8*)(lds + PG8_SB(b, h) + boff + n * 2048 + k * 1024); } while (0)
; #define PG8_MMA(ai, bj, At, Bt) do { __builtin_amdgcn_s_setprio(1); _Pragma("unroll") for (int k = 0; k < 2; ++k) _Pragma("unroll") for (int m = 0; m < 4; ++m) _Pragma("unroll") for (int n = 0; n < ((bj) == 1 ? NB1 : 2); ++n) \
;         acc[ai][bj][m][n] = __builtin_amdgcn_mfma_f32_16x16x32_bf16(Bt[n][k], At[m][k], acc[ai][bj][m][n], 0, 0, 0); __builtin_amdgcn_s_setprio(0); } while (0)
; #define PG8_WAIT_V(n) asm volatile("s_waitcnt vmcnt(" #n ")" ::: "memory")
; #define PG8_WAIT_L(n) asm volatile("s_waitcnt lgkmcnt(" #n ")" ::: "memory")
; #define PG8_BAR __builtin_amdgcn_s_barrier()
; #define PG8_SCHED __builtin_amdgcn_sched_barrier(0)
;     ...
;             PG8_WAIT_V(6); PG8_BAR; PG8_MMA(1, 1, At, B1); PG8_BAR;
;             PG8_LDB(B0, 1, 0); PG8_SCHED; PG8_LDA(At, 1, 0); PG8_STAGE(PG8_SA(0, 1), a2 + hstepA, voffA);
;             PG8_WAIT_L(8); PG8_BAR; PG8_WAIT_L(0); PG8_MMA(0, 0, At, B0); PG8_BAR; PG8_SCHED;
;             PG8_LDB(B1, 1, 1); PG8_STAGE(PG8_SB(1, 0), b3, voffB);
;             PG8_BAR; PG8_WAIT_L(0); PG8_MMA(0, 1, At, B1); PG8_BAR;
;             PG8_LDA(At, 1, 1); PG8_STAGE(PG8_SA(1, 0), a3, voffA);
;             PG8_BAR; PG8_WAIT_L(0); PG8_MMA(1, 0, At, B0); PG8_BAR; PG8_SCHED;
;             PG8_STAGE(PG8_SB(1, 1), b3 + hstepB, voffB);
;             PG8_WAIT_V(6); PG8_BAR; PG8_MMA(1, 1, At, B1); PG8_BAR;
	ds_read_b128 v[144:147], v228 offset:16384
	ds_read_b128 v[148:151], v228 offset:17408
	ds_read_b128 v[152:155], v228 offset:18432
	ds_read_b128 v[156:159], v228 offset:19456
	ds_read_b128 v[160:163], v228 offset:20480
	ds_read_b128 v[164:167], v228 offset:21504
	ds_read_b128 v[168:171], v228 offset:22528
	ds_read_b128 v[172:175], v228 offset:23552
	buffer_load_dwordx4 v222, s[28:31], 0 offen lds
	s_mov_b32 m0, s67
	s_nop 0
	buffer_load_dwordx4 v224, s[28:31], 0 offen lds
	s_barrier
	s_waitcnt lgkmcnt(0)
	s_setprio 1
	s_waitcnt lgkmcnt(7)
	v_mfma_f32_16x16x32_bf16 v[60:63], v[128:131], v[144:147], 0
	v_mfma_f32_16x16x32_bf16 v[56:59], v[136:139], v[144:147], 0
	s_waitcnt lgkmcnt(5)
	v_mfma_f32_16x16x32_bf16 v[44:47], v[128:131], v[152:155], 0
	v_mfma_f32_16x16x32_bf16 v[40:43], v[136:139], v[152:155], 0
	s_waitcnt lgkmcnt(3)
	v_mfma_f32_16x16x32_bf16 v[28:31], v[128:131], v[160:163], 0
	v_mfma_f32_16x16x32_bf16 v[24:27], v[136:139], v[160:163], 0
	s_waitcnt lgkmcnt(1)
	v_mfma_f32_16x16x32_bf16 v[12:15], v[128:131], v[168:171], 0
	v_mfma_f32_16x16x32_bf16 v[8:11], v[136:139], v[168:171], 0
	v_mfma_f32_16x16x32_bf16 v[60:63], v[132:135], v[148:151], v[60:63]
	v_mfma_f32_16x16x32_bf16 v[56:59], v[140:143], v[148:151], v[56:59]
	v_mfma_f32_16x16x32_bf16 v[44:47], v[132:135], v[156:159], v[44:47]
	v_mfma_f32_16x16x32_bf16 v[40:43], v[140:143], v[156:159], v[40:43]
	v_mfma_f32_16x16x32_bf16 v[28:31], v[132:135], v[164:167], v[28:31]
	v_mfma_f32_16x16x32_bf16 v[24:27], v[140:143], v[164:167], v[24:27]
	s_waitcnt lgkmcnt(0)
	v_mfma_f32_16x16x32_bf16 v[12:15], v[132:135], v[172:175], v[12:15]
	v_mfma_f32_16x16x32_bf16 v[8:11], v[140:143], v[172:175], v[8:11]
	s_setprio 0
	s_barrier
	s_add_u32 s8, s24, s38
	s_addc_u32 s23, s18, s39
	s_and_b32 s9, s23, 0xffff
	s_mov_b32 m0, s70
	s_nop 0
	buffer_load_dwordx4 v223, s[8:11], 0 offen lds
	s_mov_b32 m0, s71
	s_nop 0
	buffer_load_dwordx4 v225, s[8:11], 0 offen lds
	s_waitcnt vmcnt(6)
	s_barrier
	s_setprio 1
	v_mfma_f32_16x16x32_bf16 v[52:55], v[176:179], v[144:147], 0
	v_mfma_f32_16x16x32_bf16 v[48:51], v[192:195], v[144:147], 0
	v_mfma_f32_16x16x32_bf16 v[36:39], v[176:179], v[152:155], 0
	v_mfma_f32_16x16x32_bf16 v[32:35], v[192:195], v[152:155], 0
	v_mfma_f32_16x16x32_bf16 v[20:23], v[176:179], v[160:163], 0
	v_mfma_f32_16x16x32_bf16 v[16:19], v[192:195], v[160:163], 0
	v_mfma_f32_16x16x32_bf16 v[4:7], v[176:179], v[168:171], 0
	v_mfma_f32_16x16x32_bf16 v[0:3], v[192:195], v[168:171], 0
	v_mfma_f32_16x16x32_bf16 v[52:55], v[180:183], v[148:151], v[52:55]
	v_mfma_f32_16x16x32_bf16 v[48:51], v[196:199], v[148:151], v[48:51]
	v_mfma_f32_16x16x32_bf16 v[36:39], v[180:183], v[156:159], v[36:39]
	v_mfma_f32_16x16x32_bf16 v[32:35], v[196:199], v[156:159], v[32:35]
	v_mfma_f32_16x16x32_bf16 v[20:23], v[180:183], v[164:167], v[20:23]
	v_mfma_f32_16x16x32_bf16 v[16:19], v[196:199], v[164:167], v[16:19]
	v_mfma_f32_16x16x32_bf16 v[4:7], v[180:183], v[172:175], v[4:7]
	v_mfma_f32_16x16x32_bf16 v[0:3], v[196:199], v[172:175], v[0:3]
	s_setprio 0
	s_barrier
	s_branch .Lkmid_772
	.p2align 6
	s_nop 0
	s_nop 0

; __device__ __forceinline__ unsigned cvt_pk_bf16(float lo, float hi) { unsigned r; asm volatile("v_cvt_pk_bf16_f32 %0, %1, %2" : "=v"(r) : "v"(lo), "v"(hi)); return r; }
; __device__ __forceinline__ float bf_lo(unsigned w) { return __uint_as_float(w << 16); }
; __device__ __forceinline__ float bf_hi(unsigned w) { return __uint_as_float(w & 0xffff0000u); }
; #define PG8_WAIT_V(n) asm volatile("s_waitcnt vmcnt(" #n ")" ::: "memory")
; #define PG8_BAR __builtin_amdgcn_s_barrier()
;     ...
; #pragma unroll
;         for (int a = 0; a < 2; ++a)
; #pragma unroll
;             for (int b = 0; b < 2; ++b)
; #pragma unroll
;                 for (int m = 0; m < 4; ++m)
; #pragma unroll
;                     for (int n = 0; n < 2; ++n) acc[a][b][m][n] = (f32x4){0.f, 0.f, 0.f, 0.f};
;         cur = nxt; cA = nA; cB = nB; ++ui;
;     }
;     PG8_WAIT_V(0);
;     if (wr == 0) PG8_BAR;
;     PG8_BAR;
;     __device__ __forceinline__ void operator()(const Acc& acc, const Unit& u, int wr, int wc, int fr, int fq, LAS unsigned char* lds, f32x4 epar) const {
;     ...
;             for (int m = 0; m < 4; ++m) { const int r = u.pm * BM + ai * HALF + wr * 64 + m * 16 + fr; float s = 0.f;
; #pragma unroll
;                 for (int bj = 0; bj < 2; ++bj) { const size_t off = (size_t)r * DM + u.pn * 256 + bj * 128 + wc * 32 + 8 * fq;
;                     const u32x4 q = hv[ai][m][bj];
;                     f32x4 v0 = (f32x4){bf_lo(q.x), bf_hi(q.x), bf_lo(q.y), bf_hi(q.y)}, v1 = (f32x4){bf_lo(q.z), bf_hi(q.z), bf_lo(q.w), bf_hi(q.w)};
;                     v0 += acc[ai][bj][m][0]; v1 += acc[ai][bj][m][1];
;                     u32x4 w; w.x = cvt_pk_bf16(v0[0], v0[1]); w.y = cvt_pk_bf16(v0[2], v0[3]); w.z = cvt_pk_bf16(v1[0], v1[1]); w.w = cvt_pk_bf16(v1[2], v1[3]);
;                     *(u32x4*)(HB + off) = w;
;                     s += (v0[0] * v0[0] + v0[1] * v0[1]) + (v0[2] * v0[2] + v0[3] * v0[3]) + (v1[0] * v1[0] + v1[1] * v1[1]) + (v1[2] * v1[2] + v1[3] * v1[3]); }
;                 s += __shfl_xor(s, 16); s += __shfl_xor(s, 32);
;                 if (fq == 0) unsafeAtomicAdd(ssq + r, s); }
.LBB0_787:
	s_or_b64 exec, exec, s[16:17]
	s_waitcnt vmcnt(15)
	v_lshlrev_b32_e32 v16, 16, v132
	s_waitcnt lgkmcnt(0)
	v_and_b32_e32 v17, 0xffff0000, v132
	v_lshlrev_b32_e32 v18, 16, v133
	v_and_b32_e32 v19, 0xffff0000, v133
	v_lshlrev_b32_e32 v20, 16, v134
	v_and_b32_e32 v21, 0xffff0000, v134
	v_pk_add_f32 v[12:13], v[12:13], v[16:17]
	v_pk_add_f32 v[14:15], v[14:15], v[18:19]
	v_pk_add_f32 v[18:19], v[8:9], v[20:21]
	v_cvt_pk_bf16_f32 v8, v12, v13
	v_mul_f32_e32 v13, v13, v13
	v_fmac_f32_e32 v13, v12, v12
	v_mul_f32_e32 v12, v15, v15
	v_fmac_f32_e32 v12, v14, v14
	v_lshlrev_b32_e32 v22, 16, v135
	v_and_b32_e32 v23, 0xffff0000, v135
	v_add_f32_e32 v12, v13, v12
	v_mul_f32_e32 v13, v19, v19
	v_pk_add_f32 v[16:17], v[10:11], v[22:23]
	v_fmac_f32_e32 v13, v18, v18
	v_add_f32_e32 v12, v13, v12
	v_mul_f32_e32 v13, v17, v17
	v_fmac_f32_e32 v13, v16, v16
	v_cvt_pk_bf16_f32 v9, v14, v15
	v_add_f32_e32 v22, v13, v12
	s_waitcnt vmcnt(14)
	v_lshlrev_b32_e32 v12, 16, v128
	v_and_b32_e32 v13, 0xffff0000, v128
	v_lshlrev_b32_e32 v14, 16, v129
	v_and_b32_e32 v15, 0xffff0000, v129
	v_cvt_pk_bf16_f32 v10, v18, v19
	v_cvt_pk_bf16_f32 v11, v16, v17
	v_lshlrev_b32_e32 v16, 16, v130
	v_and_b32_e32 v17, 0xffff0000, v130
	v_pk_add_f32 v[6:7], v[6:7], v[14:15]
	v_pk_add_f32 v[4:5], v[4:5], v[12:13]
	v_pk_add_f32 v[14:15], v[0:1], v[16:17]
	v_mul_f32_e32 v0, v5, v5
	v_mul_f32_e32 v1, v7, v7
	v_fmac_f32_e32 v0, v4, v4
	v_fmac_f32_e32 v1, v6, v6
	v_lshlrev_b32_e32 v18, 16, v131
	v_and_b32_e32 v19, 0xffff0000, v131
	v_add_f32_e32 v0, v0, v1
	v_mul_f32_e32 v1, v15, v15
	v_pk_add_f32 v[12:13], v[2:3], v[18:19]
	v_fmac_f32_e32 v1, v14, v14
	v_add_f32_e32 v0, v1, v0
	v_mul_f32_e32 v1, v13, v13
	v_fmac_f32_e32 v1, v12, v12
	v_add_f32_e32 v0, v1, v0
	v_add_f32_e32 v3, v22, v0
	ds_bpermute_b32 v18, v112, v3
	v_lshl_add_u64 v[20:21], s[20:21], 0, v[194:195]
	v_lshl_add_u64 v[20:21], s[8:9], 1, v[20:21]
	v_lshl_add_u64 v[0:1], v[20:21], 0, s[44:45]
	v_lshl_add_u64 v[16:17], v[0:1], 0, v[184:185]
	s_waitcnt lgkmcnt(0)
	v_add_f32_e32 v0, v3, v18
	ds_bpermute_b32 v1, v113, v0
	global_store_dwordx4 v[16:17], v[8:11], off
	v_cvt_pk_bf16_f32 v2, v4, v5
	v_cvt_pk_bf16_f32 v3, v6, v7
	v_cvt_pk_bf16_f32 v4, v14, v15
	v_cvt_pk_bf16_f32 v5, v12, v13
	global_store_dwordx4 v[16:17], v[2:5], off offset:256
	s_and_saveexec_b64 s[8:9], s[4:5]
	s_cbranch_execz .LBB0_759
	s_waitcnt lgkmcnt(0)
	v_add_f32_e32 v2, v0, v1
	v_lshl_add_u64 v[0:1], v[192:193], 2, s[12:13]
	global_atomic_add_f32 v[0:1], v2, off
	s_branch .LBB0_759
.Lkzero_772:
	v_mov_b32_e32 v123, 0
	v_mov_b32_e32 v122, v123
	v_mov_b32_e32 v121, v123
	v_mov_b32_e32 v120, v123
	v_mov_b32_e32 v127, v123
	v_mov_b32_e32 v126, v123
	v_mov_b32_e32 v125, v123
	v_mov_b32_e32 v124, v123
	v_mov_b32_e32 v111, v123
	v_mov_b32_e32 v110, v123
	v_mov_b32_e32 v109, v123
	v_mov_b32_e32 v108, v123
	v_mov_b32_e32 v107, v123
	v_mov_b32_e32 v106, v123
	v_mov_b32_e32 v105, v123
	v_mov_b32_e32 v104, v123
	v_mov_b32_e32 v95, v123
	v_mov_b32_e32 v94, v123
	v_mov_b32_e32 v93, v123
	v_mov_b32_e32 v92, v123
	v_mov_b32_e32 v91, v123
	v_mov_b32_e32 v90, v123
	v_mov_b32_e32 v89, v123
	v_mov_b32_e32 v88, v123
	v_mov_b32_e32 v79, v123
	v_mov_b32_e32 v78, v123
	v_mov_b32_e32 v77, v123
	v_mov_b32_e32 v76, v123
	v_mov_b32_e32 v75, v123
	v_mov_b32_e32 v74, v123
	v_mov_b32_e32 v73, v123
	v_mov_b32_e32 v72, v123
	v_mov_b32_e32 v119, v123
	v_mov_b32_e32 v118, v123
	v_mov_b32_e32 v117, v123
	v_mov_b32_e32 v116, v123
	v_mov_b32_e32 v115, v123
	v_mov_b32_e32 v114, v123
	v_mov_b32_e32 v113, v123
	v_mov_b32_e32 v112, v123
	v_mov_b32_e32 v103, v123
	v_mov_b32_e32 v102, v123
	v_mov_b32_e32 v101, v123
	v_mov_b32_e32 v100, v123
	v_mov_b32_e32 v99, v123
	v_mov_b32_e32 v98, v123
	v_mov_b32_e32 v97, v123
	v_mov_b32_e32 v96, v123
	v_mov_b32_e32 v87, v123
	v_mov_b32_e32 v86, v123
	v_mov_b32_e32 v85, v123
	v_mov_b32_e32 v84, v123
	v_mov_b32_e32 v83, v123
	v_mov_b32_e32 v82, v123
	v_mov_b32_e32 v81, v123
	v_mov_b32_e32 v80, v123
	v_mov_b32_e32 v71, v123
	v_mov_b32_e32 v70, v123
	v_mov_b32_e32 v69, v123
	v_mov_b32_e32 v68, v123
	v_mov_b32_e32 v67, v123
	v_mov_b32_e32 v66, v123
	v_mov_b32_e32 v65, v123
	v_mov_b32_e32 v64, v123
	v_mov_b32_e32 v63, v123
	v_mov_b32_e32 v62, v123
	v_mov_b32_e32 v61, v123
	v_mov_b32_e32 v60, v123
	v_mov_b32_e32 v59, v123
	v_mov_b32_e32 v58, v123
	v_mov_b32_e32 v57, v123
	v_mov_b32_e32 v56, v123
	v_mov_b32_e32 v47, v123
	v_mov_b32_e32 v46, v123
	v_mov_b32_e32 v45, v123
	v_mov_b32_e32 v44, v123
	v_mov_b32_e32 v43, v123
	v_mov_b32_e32 v42, v123
	v_mov_b32_e32 v41, v123
	v_mov_b32_e32 v40, v123
	v_mov_b32_e32 v31, v123
	v_mov_b32_e32 v30, v123
	v_mov_b32_e32 v29, v123
	v_mov_b32_e32 v28, v123
	v_mov_b32_e32 v27, v123
	v_mov_b32_e32 v26, v123
	v_mov_b32_e32 v25, v123
	v_mov_b32_e32 v24, v123
	v_mov_b32_e32 v15, v123
	v_mov_b32_e32 v14, v123
	v_mov_b32_e32 v13, v123
	v_mov_b32_e32 v12, v123
	v_mov_b32_e32 v11, v123
	v_mov_b32_e32 v10, v123
	v_mov_b32_e32 v9, v123
	v_mov_b32_e32 v8, v123
	v_mov_b32_e32 v55, v123
	v_mov_b32_e32 v54, v123
	v_mov_b32_e32 v53, v123
	v_mov_b32_e32 v52, v123
	v_mov_b32_e32 v51, v123
	v_mov_b32_e32 v50, v123
	v_mov_b32_e32 v49, v123
	v_mov_b32_e32 v48, v123
	v_mov_b32_e32 v39, v123
	v_mov_b32_e32 v38, v123
	v_mov_b32_e32 v37, v123
	v_mov_b32_e32 v36, v123
	v_mov_b32_e32 v35, v123
	v_mov_b32_e32 v34, v123
	v_mov_b32_e32 v33, v123
	v_mov_b32_e32 v32, v123
	v_mov_b32_e32 v23, v123
	v_mov_b32_e32 v22, v123
	v_mov_b32_e32 v21, v123
	v_mov_b32_e32 v20, v123
	v_mov_b32_e32 v19, v123
	v_mov_b32_e32 v18, v123
	v_mov_b32_e32 v17, v123
	v_mov_b32_e32 v16, v123
	v_mov_b32_e32 v7, v123
	v_mov_b32_e32 v6, v123
	v_mov_b32_e32 v5, v123
	v_mov_b32_e32 v4, v123
	v_mov_b32_e32 v3, v123
	v_mov_b32_e32 v2, v123
	v_mov_b32_e32 v1, v123
	v_mov_b32_e32 v0, v123
	s_branch .LBB0_773
.LBB0_789:
	s_waitcnt vmcnt(0)
	s_cmpk_gt_u32 s52, 0xff
	s_cbranch_scc1 .LBB0_791
	s_barrier

;     __device__ __forceinline__ size_t a_off(const Unit& u) const { return (size_t)u.pm * atile; }
;     __device__ __forceinline__ size_t b_off(const Unit& u) const { return (size_t)u.pn * btile; }
;     __device__ __forceinline__ bool next(int i, Unit& u) const { const long L = (long)i * G + c; if (L >= NG * 8) return false; u.g = (int)(L >> 3); u.pm = (int)(L & 7); u.pn = 0; return true; }
;     __device__ __forceinline__ size_t a_off(const Unit& u) const { return ((size_t)u.g * NROW + (size_t)u.pm * BM) * KA * 2; }
; #define PG8_WAIT_V(n) asm volatile("s_waitcnt vmcnt(" #n ")" ::: "memory")
;     ...
;         const bool has_next = S.next(ui + 1, nxt);
;         const char* nA = has_next ? (const char*)Ap + S.a_off(nxt) : cA; const char* nB = has_next ? (const char*)Btp + S.b_off(nxt) : cB;
;         for (int t = 0; t < nt; t += 2) {
;             const bool last = (t == nt - 2);
;             const char* a1 = cA + (size_t)(t + 1) * kstep;
;             const char* a2 = last ? nA : cA + (size_t)(t + 2) * kstep; const char* b2 = last ? nB : cB + (size_t)(t + 2) * kstep;
;             const char* a3 = a2 + kstep; const char* b3 = b2 + kstep;
;             PG8_LDB(B0, 0, 0); PG8_SCHED; PG8_LDA(At, 0, 0); PG8_STAGE(PG8_SA(1, 1), a1 + hstepA, voffA);
;             PG8_WAIT_L(8); PG8_BAR; PG8_WAIT_L(0); PG8_MMA(0, 0, At, B0); PG8_BAR; PG8_SCHED;
;             PG8_LDB(B1, 0, 1); PG8_STAGE(PG8_SB(0, 0), b2, voffB);
;             PG8_BAR; PG8_WAIT_L(0); PG8_MMA(0, 1, At, B1); PG8_BAR;
;             PG8_LDA(At, 0, 1); PG8_STAGE(PG8_SA(0, 0), a2, voffA);
;             PG8_BAR; PG8_WAIT_L(0); PG8_MMA(1, 0, At, B0); PG8_BAR; PG8_SCHED;
;             PG8_STAGE(PG8_SB(0, 1), b2 + hstepB, voffB);
;             PG8_WAIT_V(6); PG8_BAR; PG8_MMA(1, 1, At, B1); PG8_BAR;
;             PG8_LDB(B0, 1, 0); PG8_SCHED; PG8_LDA(At, 1, 0); PG8_STAGE(PG8_SA(0, 1), a2 + hstepA, voffA);
;             PG8_WAIT_L(8); PG8_BAR; PG8_WAIT_L(0); PG8_MMA(0, 0, At, B0); PG8_BAR; PG8_SCHED;
;             PG8_LDB(B1, 1, 1); PG8_STAGE(PG8_SB(1, 0), b3, voffB);
;             PG8_BAR; PG8_WAIT_L(0); PG8_MMA(0, 1, At, B1); PG8_BAR;
;             PG8_LDA(At, 1, 1); PG8_STAGE(PG8_SA(1, 0), a3, voffA);
;             PG8_BAR; PG8_WAIT_L(0); PG8_MMA(1, 0, At, B0); PG8_BAR; PG8_SCHED;
;             PG8_STAGE(PG8_SB(1, 1), b3 + hstepB, voffB);
;             PG8_WAIT_V(6); PG8_BAR; PG8_MMA(1, 1, At, B1); PG8_BAR;
.Lnext_done_23079:
.LBB0_842:
	s_ashr_i32 s59, s58, 31
	s_lshl_b64 s[16:17], s[58:59], 19
	s_add_u32 s64, s20, s16
	s_addc_u32 s65, s21, s17
	s_ashr_i32 s53, s52, 31
	s_lshl_b64 s[16:17], s[52:53], 19
	s_add_u32 s66, s33, s16
	v_cmp_lt_i64_e64 s[12:13], s[12:13], v[118:119]
	s_addc_u32 s67, s35, s17
	s_andn2_b64 vcc, exec, s[68:69]
	s_cbranch_vccnz .Lkzero_844
	s_and_b64 s[16:17], s[12:13], exec
	s_cselect_b32 s22, s65, s27
	s_cselect_b32 s23, s64, s26
	s_cselect_b32 s53, s67, s25
	s_cselect_b32 s59, s66, s24
	s_add_u32 s94, s26, 0x100
	s_addc_u32 s95, s27, 0
	s_add_u32 s96, s24, 0x100
	s_addc_u32 s97, s25, 0
	s_mov_b32 s16, 0
	ds_read_b128 v[100:103], v141
	ds_read_b128 v[104:107], v141 offset:1024
	ds_read_b128 v[122:125], v141 offset:2048
	ds_read_b128 v[126:129], v141 offset:3072
	s_add_i32 vcc_lo, s16, 2
	s_cmp_eq_u32 s87, s16
	s_cselect_b32 s36, s23, s94
	s_cselect_b32 s26, s22, s95
	s_cselect_b32 s27, s53, s97
	s_cselect_b32 s28, s59, s96
	s_add_u32 s24, s36, 0x80
	s_addc_u32 s25, s26, 0
	s_add_u32 s16, s94, s0
	s_addc_u32 s17, s95, s1
	s_add_u32 s16, s16, 0xffffff80
	s_addc_u32 s17, s17, -1
	s_and_b32 s17, s17, 0xffff
	s_mov_b32 m0, s88
	ds_read_b128 v[130:133], v142
	ds_read_b128 v[150:153], v142 offset:1024
	ds_read_b128 v[154:157], v142 offset:2048
	ds_read_b128 v[158:161], v142 offset:3072
	ds_read_b128 v[162:165], v142 offset:4096
	ds_read_b128 v[166:169], v142 offset:5120
	ds_read_b128 v[170:173], v142 offset:6144
	ds_read_b128 v[174:177], v142 offset:7168
	buffer_load_dwordx4 v134, s[16:19], 0 offen lds
	s_mov_b32 m0, s89
	s_nop 0
	buffer_load_dwordx4 v136, s[16:19], 0 offen lds
	s_waitcnt lgkmcnt(8)
	s_barrier
	s_waitcnt lgkmcnt(0)
	s_setprio 1
	s_waitcnt lgkmcnt(7)
	v_mfma_f32_16x16x32_bf16 v[88:91], v[100:103], v[130:133], 0
	v_mfma_f32_16x16x32_bf16 v[96:99], v[122:125], v[130:133], 0
	s_waitcnt lgkmcnt(5)
	v_mfma_f32_16x16x32_bf16 v[76:79], v[100:103], v[154:157], 0
	v_mfma_f32_16x16x32_bf16 v[84:87], v[122:125], v[154:157], 0
	s_waitcnt lgkmcnt(3)
	v_mfma_f32_16x16x32_bf16 v[64:67], v[100:103], v[162:165], 0
	v_mfma_f32_16x16x32_bf16 v[72:75], v[122:125], v[162:165], 0
	s_waitcnt lgkmcnt(1)
	v_mfma_f32_16x16x32_bf16 v[52:55], v[100:103], v[170:173], 0
	v_mfma_f32_16x16x32_bf16 v[60:63], v[122:125], v[170:173], 0
	v_mfma_f32_16x16x32_bf16 v[88:91], v[104:107], v[150:153], v[88:91]
	v_mfma_f32_16x16x32_bf16 v[96:99], v[126:129], v[150:153], v[96:99]
	v_mfma_f32_16x16x32_bf16 v[76:79], v[104:107], v[158:161], v[76:79]
	v_mfma_f32_16x16x32_bf16 v[84:87], v[126:129], v[158:161], v[84:87]
	v_mfma_f32_16x16x32_bf16 v[64:67], v[104:107], v[166:169], v[64:67]
	v_mfma_f32_16x16x32_bf16 v[72:75], v[126:129], v[166:169], v[72:75]
	s_waitcnt lgkmcnt(0)
	v_mfma_f32_16x16x32_bf16 v[52:55], v[104:107], v[174:177], v[52:55]
	v_mfma_f32_16x16x32_bf16 v[60:63], v[126:129], v[174:177], v[60:63]
	s_setprio 0
	s_barrier
	s_and_b32 s29, s27, 0xffff
	s_mov_b32 s30, s18
	s_mov_b32 s31, s19
	s_mov_b32 m0, s73
	ds_read_b128 v[178:181], v143
	ds_read_b128 v[182:185], v143 offset:1024
	buffer_load_dwordx4 v135, s[28:31], 0 offen lds
	s_mov_b32 m0, s74
	s_nop 0
	buffer_load_dwordx4 v137, s[28:31], 0 offen lds
	s_barrier
	s_waitcnt lgkmcnt(0)
	s_setprio 1
	s_waitcnt lgkmcnt(1)
	v_mfma_f32_16x16x32_bf16 v[92:95], v[178:181], v[130:133], 0
	v_mfma_f32_16x16x32_bf16 v[80:83], v[178:181], v[154:157], 0
	v_mfma_f32_16x16x32_bf16 v[68:71], v[178:181], v[162:165], 0
	v_mfma_f32_16x16x32_bf16 v[56:59], v[178:181], v[170:173], 0
	s_waitcnt lgkmcnt(0)
	v_mfma_f32_16x16x32_bf16 v[92:95], v[182:185], v[150:153], v[92:95]
	v_mfma_f32_16x16x32_bf16 v[80:83], v[182:185], v[158:161], v[80:83]
	v_mfma_f32_16x16x32_bf16 v[68:71], v[182:185], v[166:169], v[68:71]
	v_mfma_f32_16x16x32_bf16 v[56:59], v[182:185], v[174:177], v[56:59]
	s_setprio 0
	s_and_b32 s37, s26, 0xffff
	s_mov_b32 s38, s18
	s_mov_b32 s39, s19
	s_mov_b32 m0, s71
	s_barrier
	ds_read_b128 v[130:133], v142 offset:16384
	ds_read_b128 v[150:153], v142 offset:17408
	ds_read_b128 v[154:157], v142 offset:18432
	ds_read_b128 v[158:161], v142 offset:19456
	ds_read_b128 v[162:165], v142 offset:20480
	ds_read_b128 v[166:169], v142 offset:21504
	ds_read_b128 v[170:173], v142 offset:22528
	ds_read_b128 v[174:177], v142 offset:23552
	buffer_load_dwordx4 v134, s[36:39], 0 offen lds
	s_mov_b32 m0, s75
	s_nop 0
	buffer_load_dwordx4 v136, s[36:39], 0 offen lds
	s_barrier
	s_waitcnt lgkmcnt(0)
	s_setprio 1
	s_waitcnt lgkmcnt(7)
	v_mfma_f32_16x16x32_bf16 v[44:47], v[100:103], v[130:133], 0
	v_mfma_f32_16x16x32_bf16 v[48:51], v[122:125], v[130:133], 0
	s_waitcnt lgkmcnt(5)
	v_mfma_f32_16x16x32_bf16 v[28:31], v[100:103], v[154:157], 0
	v_mfma_f32_16x16x32_bf16 v[36:39], v[122:125], v[154:157], 0
	s_waitcnt lgkmcnt(3)
	v_mfma_f32_16x16x32_bf16 v[12:15], v[100:103], v[162:165], 0
	v_mfma_f32_16x16x32_bf16 v[20:23], v[122:125], v[162:165], 0
	s_waitcnt lgkmcnt(1)
	v_mfma_f32_16x16x32_bf16 v[0:3], v[100:103], v[170:173], 0
	v_mfma_f32_16x16x32_bf16 v[8:11], v[122:125], v[170:173], 0
	v_mfma_f32_16x16x32_bf16 v[44:47], v[104:107], v[150:153], v[44:47]
	v_mfma_f32_16x16x32_bf16 v[48:51], v[126:129], v[150:153], v[48:51]
	v_mfma_f32_16x16x32_bf16 v[28:31], v[104:107], v[158:161], v[28:31]
	v_mfma_f32_16x16x32_bf16 v[36:39], v[126:129], v[158:161], v[36:39]
	v_mfma_f32_16x16x32_bf16 v[12:15], v[104:107], v[166:169], v[12:15]
	v_mfma_f32_16x16x32_bf16 v[20:23], v[126:129], v[166:169], v[20:23]
	s_waitcnt lgkmcnt(0)
	v_mfma_f32_16x16x32_bf16 v[0:3], v[104:107], v[174:177], v[0:3]
	v_mfma_f32_16x16x32_bf16 v[8:11], v[126:129], v[174:177], v[8:11]
	s_setprio 0
	s_barrier
	s_add_u32 s16, s28, s44
	s_addc_u32 vcc_hi, s27, s45
	s_and_b32 s17, vcc_hi, 0xffff
	s_mov_b32 m0, s76
	s_nop 0
	buffer_load_dwordx4 v135, s[16:19], 0 offen lds
	s_mov_b32 m0, s77
	s_nop 0
	buffer_load_dwordx4 v137, s[16:19], 0 offen lds
	s_waitcnt vmcnt(6)
	s_barrier
	s_setprio 1
	v_mfma_f32_16x16x32_bf16 v[40:43], v[178:181], v[130:133], 0
	v_mfma_f32_16x16x32_bf16 v[32:35], v[178:181], v[154:157], 0
	v_mfma_f32_16x16x32_bf16 v[16:19], v[178:181], v[162:165], 0
	v_mfma_f32_16x16x32_bf16 v[4:7], v[178:181], v[170:173], 0
	v_mfma_f32_16x16x32_bf16 v[40:43], v[182:185], v[150:153], v[40:43]
	v_mfma_f32_16x16x32_bf16 v[32:35], v[182:185], v[158:161], v[32:35]
	v_mfma_f32_16x16x32_bf16 v[16:19], v[182:185], v[166:169], v[16:19]
	v_mfma_f32_16x16x32_bf16 v[4:7], v[182:185], v[174:177], v[4:7]
	s_setprio 0
	s_barrier
	s_branch .Lkmid_844
	.p2align 6
	s_nop 0
	s_nop 0

; #define PG8_WAIT_V(n) asm volatile("s_waitcnt vmcnt(" #n ")" ::: "memory")
; #define PG8_BAR __builtin_amdgcn_s_barrier()
;     __device__ __forceinline__ f32x4 prefetch(const Unit&, int, int, int) const { return (f32x4){0.f, 0.f, 0.f, 0.f}; }
;     __device__ __forceinline__ f32x4 prefetch(const Unit&, int, int, int) const { return (f32x4){0.f, 0.f, 0.f, 0.f}; }
;     __device__ __forceinline__ f32x4 prefetch(const Unit&, int, int, int) const { return (f32x4){0.f, 0.f, 0.f, 0.f}; }
;     __device__ __forceinline__ f32x4 prefetch(const Unit&, int, int, int) const { return (f32x4){0.f, 0.f, 0.f, 0.f}; }
;     ...
;         if (has_next) epar = E.prefetch(nxt, wr, wc, lane);
;         if (!has_next) break;
; #pragma unroll
;         for (int a = 0; a < 2; ++a)
; #pragma unroll
;             for (int b = 0; b < 2; ++b)
; #pragma unroll
;                 for (int m = 0; m < 4; ++m)
; #pragma unroll
;                     for (int n = 0; n < 2; ++n) acc[a][b][m][n] = (f32x4){0.f, 0.f, 0.f, 0.f};
;         cur = nxt; cA = nA; cB = nB; ++ui;
;     }
;     PG8_WAIT_V(0);
;     if (wr == 0) PG8_BAR;
;     PG8_BAR;
;     __device__ __forceinline__ f32x4 prefetch(const Unit& u, int wr, int wc, int lane) const {
;         const float* ptr;
;         if (lane < 32) { const int arr = lane >> 3, j = lane & 7;
;             if (MODE == 0) ptr = (arr < 3 ? cw + arr * C : cb) + u.pn * 128 + wc * 32 + 4 * j;
;             else ptr = cw + (arr < 3 ? arr : 0) * C + u.pn * 64 + wc * 16 + 4 * (j & 3); }
;         else { const int k = lane - 32; ptr = ssq + u.pm * BM + (k >> 4) * HALF + wr * 64 + 4 * (k & 15); }
;         f32x4 v; asm volatile("global_load_dwordx4 %0, %1, off" : "=&v"(v) : "v"(ptr) : "memory"); return v;
.LBB0_858:
	s_or_b64 exec, exec, s[24:25]
	s_mov_b64 s[16:17], -1
	s_and_b64 vcc, exec, s[12:13]
	s_cbranch_vccz .LBB0_835
	s_lshl_b32 s12, s58, 8
	s_lshl_b32 s13, s52, 6
	v_mov_b32_e32 v0, s12
	v_mov_b32_e32 v1, s13
	v_cndmask_b32_e64 v0, v0, v1, s[4:5]
	v_ashrrev_i32_e32 v1, 31, v0
	v_lshl_add_u64 v[0:1], v[0:1], 2, v[116:117]
	v_lshl_add_u64 v[0:1], v[0:1], 0, v[108:109]
	global_load_dwordx4 v[24:27], v[0:1], off
	s_mov_b64 s[16:17], 0
	s_branch .LBB0_835
.Lkzero_844:
	v_mov_b32_e32 v91, 0
	v_mov_b32_e32 v90, v91
	v_mov_b32_e32 v89, v91
	v_mov_b32_e32 v88, v91
	v_mov_b32_e32 v99, v91
	v_mov_b32_e32 v98, v91
	v_mov_b32_e32 v97, v91
	v_mov_b32_e32 v96, v91
	v_mov_b32_e32 v79, v91
	v_mov_b32_e32 v78, v91
	v_mov_b32_e32 v77, v91
	v_mov_b32_e32 v76, v91
	v_mov_b32_e32 v87, v91
	v_mov_b32_e32 v86, v91
	v_mov_b32_e32 v85, v91
	v_mov_b32_e32 v84, v91
	v_mov_b32_e32 v67, v91
	v_mov_b32_e32 v66, v91
	v_mov_b32_e32 v65, v91
	v_mov_b32_e32 v64, v91
	v_mov_b32_e32 v75, v91
	v_mov_b32_e32 v74, v91
	v_mov_b32_e32 v73, v91
	v_mov_b32_e32 v72, v91
	v_mov_b32_e32 v55, v91
	v_mov_b32_e32 v54, v91
	v_mov_b32_e32 v53, v91
	v_mov_b32_e32 v52, v91
	v_mov_b32_e32 v63, v91
	v_mov_b32_e32 v62, v91
	v_mov_b32_e32 v61, v91
	v_mov_b32_e32 v60, v91
	v_mov_b32_e32 v95, v91
	v_mov_b32_e32 v94, v91
	v_mov_b32_e32 v93, v91
	v_mov_b32_e32 v92, v91
	v_mov_b32_e32 v83, v91
	v_mov_b32_e32 v82, v91
	v_mov_b32_e32 v81, v91
	v_mov_b32_e32 v80, v91
	v_mov_b32_e32 v71, v91
	v_mov_b32_e32 v70, v91
	v_mov_b32_e32 v69, v91
	v_mov_b32_e32 v68, v91
	v_mov_b32_e32 v59, v91
	v_mov_b32_e32 v58, v91
	v_mov_b32_e32 v57, v91
	v_mov_b32_e32 v56, v91
	v_mov_b32_e32 v47, v91
	v_mov_b32_e32 v46, v91
	v_mov_b32_e32 v45, v91
	v_mov_b32_e32 v44, v91
	v_mov_b32_e32 v51, v91
	v_mov_b32_e32 v50, v91
	v_mov_b32_e32 v49, v91
	v_mov_b32_e32 v48, v91
	v_mov_b32_e32 v31, v91
	v_mov_b32_e32 v30, v91
	v_mov_b32_e32 v29, v91
	v_mov_b32_e32 v28, v91
	v_mov_b32_e32 v39, v91
	v_mov_b32_e32 v38, v91
	v_mov_b32_e32 v37, v91
	v_mov_b32_e32 v36, v91
	v_mov_b32_e32 v15, v91
	v_mov_b32_e32 v14, v91
	v_mov_b32_e32 v13, v91
	v_mov_b32_e32 v12, v91
	v_mov_b32_e32 v23, v91
	v_mov_b32_e32 v22, v91
	v_mov_b32_e32 v21, v91
	v_mov_b32_e32 v20, v91
	v_mov_b32_e32 v3, v91
	v_mov_b32_e32 v2, v91
	v_mov_b32_e32 v1, v91
	v_mov_b32_e32 v0, v91
	v_mov_b32_e32 v11, v91
	v_mov_b32_e32 v10, v91
	v_mov_b32_e32 v9, v91
	v_mov_b32_e32 v8, v91
	v_mov_b32_e32 v43, v91
	v_mov_b32_e32 v42, v91
	v_mov_b32_e32 v41, v91
	v_mov_b32_e32 v40, v91
	v_mov_b32_e32 v35, v91
	v_mov_b32_e32 v34, v91
	v_mov_b32_e32 v33, v91
	v_mov_b32_e32 v32, v91
	v_mov_b32_e32 v19, v91
	v_mov_b32_e32 v18, v91
	v_mov_b32_e32 v17, v91
	v_mov_b32_e32 v16, v91
	v_mov_b32_e32 v7, v91
	v_mov_b32_e32 v6, v91
	v_mov_b32_e32 v5, v91
	v_mov_b32_e32 v4, v91
	s_branch .LBB0_846
.LBB0_860:
	s_waitcnt vmcnt(0)
	s_cmpk_gt_u32 s14, 0xff
	s_cbranch_scc1 .LBB0_862
	s_barrier

;     __device__ __forceinline__ size_t a_off(const Unit& u) const { return (size_t)u.pm * atile; }
;     __device__ __forceinline__ size_t b_off(const Unit& u) const { return (size_t)u.pn * btile; }
;     __device__ __forceinline__ bool next(int i, Unit& u) const { const long L = (long)i * G + c; if (L >= NG * 8) return false; u.g = (int)(L >> 3); u.pm = (int)(L & 7); u.pn = 0; return true; }
;     __device__ __forceinline__ size_t a_off(const Unit& u) const { return ((size_t)u.g * NROW + (size_t)u.pm * BM) * KA * 2; }
;     __device__ __forceinline__ size_t b_off(const Unit& u) const { return (size_t)u.g * btile; }
;     __device__ __forceinline__ bool next(int i, Unit& u) const { if (i >= 2) return false; u.g = g; u.pm = 2 * b + i; u.pn = 0; return true; }
;     __device__ __forceinline__ size_t a_off(const Unit& u) const { return ((size_t)u.g * NROW + (size_t)u.pm * BM) * KA * 2; }
;     __device__ __forceinline__ size_t b_off(const Unit& u) const { return (size_t)u.g * btile; }
; #define PG8_LDA(dst, b, h) do { _Pragma("unroll") for (int m = 0; m < 4; ++m) _Pragma("unroll") for (int k = 0; k < 2; ++k) dst[m][k] = *(const LAS bf16x8*)(lds + PG8_SA(b, h) + aoff + m * 2048 + k * 1024); } while (0)
; #define PG8_WAIT_L(n) asm volatile("s_waitcnt lgkmcnt(" #n ")" ::: "memory")
; #define PG8_BAR __builtin_amdgcn_s_barrier()
;     ...
;         const bool has_next = S.next(ui + 1, nxt);
;         const char* nA = has_next ? (const char*)Ap + S.a_off(nxt) : cA; const char* nB = has_next ? (const char*)Btp + S.b_off(nxt) : cB;
;         for (int t = 0; t < nt; t += 2) {
;             const bool last = (t == nt - 2);
;             const char* a1 = cA + (size_t)(t + 1) * kstep;
;             const char* a2 = last ? nA : cA + (size_t)(t + 2) * kstep; const char* b2 = last ? nB : cB + (size_t)(t + 2) * kstep;
;             const char* a3 = a2 + kstep; const char* b3 = b2 + kstep;
;             PG8_LDB(B0, 0, 0); PG8_SCHED; PG8_LDA(At, 0, 0); PG8_STAGE(PG8_SA(1, 1), a1 + hstepA, voffA);
;             PG8_WAIT_L(8); PG8_BAR; PG8_WAIT_L(0); PG8_MMA(0, 0, At, B0); PG8_BAR; PG8_SCHED;
;             PG8_LDB(B1, 0, 1); PG8_STAGE(PG8_SB(0, 0), b2, voffB);
;             PG8_BAR; PG8_WAIT_L(0); PG8_MMA(0, 1, At, B1); PG8_BAR;
;             PG8_LDA(At, 0, 1); PG8_STAGE(PG8_SA(0, 0), a2, voffA);
;             PG8_BAR; PG8_WAIT_L(0); PG8_MMA(1, 0, At, B0); PG8_BAR; PG8_SCHED;
.LBB0_920:
	s_ashr_i32 s51, s50, 31
	s_lshl_b64 s[8:9], s[50:51], 19
	s_add_u32 s52, s40, s8
	s_addc_u32 s53, s41, s9
	s_ashr_i32 s49, s48, 31
	s_lshl_b64 s[8:9], s[48:49], 19
	s_add_u32 s58, s72, s8
	v_cmp_lt_i64_e64 s[0:1], s[0:1], v[188:189]
	s_addc_u32 s59, s73, s9
	s_andn2_b64 vcc, exec, s[46:47]
	s_waitcnt lgkmcnt(0)
	s_cbranch_vccnz .Lkzero_922
	s_and_b64 s[0:1], s[0:1], exec
	s_cselect_b32 s0, s53, s19
	s_cselect_b32 s1, s52, s18
	s_cselect_b32 s49, s59, s17
	s_cselect_b32 s51, s58, s16
	s_add_u32 s91, s18, 0x100
	s_addc_u32 s92, s19, 0
	s_add_u32 s93, s16, 0x100
	s_addc_u32 s94, s17, 0
	s_mov_b32 s8, 0
	ds_read_b128 v[128:131], v227
	ds_read_b128 v[132:135], v227 offset:1024
	ds_read_b128 v[136:139], v227 offset:2048
	ds_read_b128 v[140:143], v227 offset:3072
	s_add_i32 s22, s8, 2
	s_cmp_eq_u32 s87, s8
	s_cselect_b32 s28, s1, s91
	s_cselect_b32 s19, s0, s92
	s_cselect_b32 s18, s49, s94
	s_cselect_b32 s24, s51, s93
	s_add_u32 s16, s28, 0x80
	s_addc_u32 s17, s19, 0
	s_add_u32 s8, s91, s36
	s_addc_u32 s9, s92, s37
	s_add_u32 s8, s8, 0xffffff80
	s_addc_u32 s9, s9, -1
	s_and_b32 s9, s9, 0xffff
	s_mov_b32 m0, s88
	ds_read_b128 v[144:147], v228
	ds_read_b128 v[148:151], v228 offset:1024
	ds_read_b128 v[152:155], v228 offset:2048
	ds_read_b128 v[156:159], v228 offset:3072
	ds_read_b128 v[160:163], v228 offset:4096
	ds_read_b128 v[164:167], v228 offset:5120
	ds_read_b128 v[168:171], v228 offset:6144
	ds_read_b128 v[172:175], v228 offset:7168
	buffer_load_dwordx4 v222, s[8:11], 0 offen lds
	s_mov_b32 m0, s89
	s_nop 0
	buffer_load_dwordx4 v224, s[8:11], 0 offen lds
	s_waitcnt lgkmcnt(8)
	s_barrier
	s_waitcnt lgkmcnt(0)
	s_setprio 1
	s_waitcnt lgkmcnt(7)
	v_mfma_f32_16x16x32_bf16 v[120:123], v[128:131], v[144:147], 0
	v_mfma_f32_16x16x32_bf16 v[124:127], v[136:139], v[144:147], 0
	s_waitcnt lgkmcnt(5)
	v_mfma_f32_16x16x32_bf16 v[108:111], v[128:131], v[152:155], 0
	v_mfma_f32_16x16x32_bf16 v[104:107], v[136:139], v[152:155], 0
	s_waitcnt lgkmcnt(3)
	v_mfma_f32_16x16x32_bf16 v[92:95], v[128:131], v[160:163], 0
	v_mfma_f32_16x16x32_bf16 v[88:91], v[136:139], v[160:163], 0
	s_waitcnt lgkmcnt(1)
	v_mfma_f32_16x16x32_bf16 v[76:79], v[128:131], v[168:171], 0
	v_mfma_f32_16x16x32_bf16 v[72:75], v[136:139], v[168:171], 0
	v_mfma_f32_16x16x32_bf16 v[120:123], v[132:135], v[148:151], v[120:123]
	v_mfma_f32_16x16x32_bf16 v[124:127], v[140:143], v[148:151], v[124:127]
	v_mfma_f32_16x16x32_bf16 v[108:111], v[132:135], v[156:159], v[108:111]
	v_mfma_f32_16x16x32_bf16 v[104:107], v[140:143], v[156:159], v[104:107]
	v_mfma_f32_16x16x32_bf16 v[92:95], v[132:135], v[164:167], v[92:95]
	v_mfma_f32_16x16x32_bf16 v[88:91], v[140:143], v[164:167], v[88:91]
	s_waitcnt lgkmcnt(0)
	v_mfma_f32_16x16x32_bf16 v[76:79], v[132:135], v[172:175], v[76:79]
	v_mfma_f32_16x16x32_bf16 v[72:75], v[140:143], v[172:175], v[72:75]
	s_setprio 0
	s_barrier
	s_and_b32 s25, s18, 0xffff
	s_mov_b32 s26, s10
	s_mov_b32 s27, s11
	s_mov_b32 m0, s67
	ds_read_b128 v[176:179], v229
	ds_read_b128 v[180:183], v229 offset:1024
	ds_read_b128 v[192:195], v229 offset:2048
	ds_read_b128 v[196:199], v229 offset:3072
	buffer_load_dwordx4 v223, s[24:27], 0 offen lds
	s_mov_b32 m0, s74
	s_nop 0
	buffer_load_dwordx4 v225, s[24:27], 0 offen lds
	s_barrier
; #define PG8_STAGE(bufoff, gbase, voff) do { const __amdgpu_buffer_rsrc_t _r = __builtin_amdgcn_make_buffer_rsrc((void*)(gbase), (short)0, 0x7fffffff, 0x00020000); _Pragma("unroll") for (int _i = 0; _i < 2; ++_i) \
;         __builtin_amdgcn_raw_ptr_buffer_load_lds(_r, (LAS unsigned*)(lds + (bufoff) + ldsw + _i * 8192), 16, (int)(voff)[_i], 0, 0, 0); } while (0)
; #define PG8_LDA(dst, b, h) do { _Pragma("unroll") for (int m = 0; m < 4; ++m) _Pragma("unroll") for (int k = 0; k < 2; ++k) dst[m][k] = *(const LAS bf16x8*)(lds + PG8_SA(b, h) + aoff + m * 2048 + k * 1024); } while (0)
; #define PG8_LDB(dst, b, h) do { _Pragma("unroll") for (int n = 0; n < 2; ++n) _Pragma("unroll") for (int k = 0; k < 2; ++k) dst[n][k] = *(const LAS bf16x8*)(lds + PG8_SB(b, h) + boff + n * 2048 + k * 1024); } while (0)
; #define PG8_MMA(ai, bj, At, Bt) do { __builtin_amdgcn_s_setprio(1); _Pragma("unroll") for (int k = 0; k < 2; ++k) _Pragma("unroll") for (int m = 0; m < 4; ++m) _Pragma("unroll") for (int n = 0; n < ((bj) == 1 ? NB1 : 2); ++n) \
;         acc[ai][bj][m][n] = __builtin_amdgcn_mfma_f32_16x16x32_bf16(Bt[n][k], At[m][k], acc[ai][bj][m][n], 0, 0, 0); __builtin_amdgcn_s_setprio(0); } while (0)
; #define PG8_WAIT_V(n) asm volatile("s_waitcnt vmcnt(" #n ")" ::: "memory")
; #define PG8_WAIT_L(n) asm volatile("s_waitcnt lgkmcnt(" #n ")" ::: "memory")
; #define PG8_BAR __builtin_amdgcn_s_barrier()
; #define PG8_SCHED __builtin_amdgcn_sched_barrier(0)
;     ...
;             PG8_BAR; PG8_WAIT_L(0); PG8_MMA(1, 0, At, B0); PG8_BAR; PG8_SCHED;
;             PG8_STAGE(PG8_SB(0, 1), b2 + hstepB, voffB);
;             PG8_WAIT_V(6); PG8_BAR; PG8_MMA(1, 1, At, B1); PG8_BAR;
;             PG8_LDB(B0, 1, 0); PG8_SCHED; PG8_LDA(At, 1, 0); PG8_STAGE(PG8_SA(0, 1), a2 + hstepA, voffA);
;             PG8_WAIT_L(8); PG8_BAR; PG8_WAIT_L(0); PG8_MMA(0, 0, At, B0); PG8_BAR; PG8_SCHED;
;             PG8_LDB(B1, 1, 1); PG8_STAGE(PG8_SB(1, 0), b3, voffB);
;             PG8_BAR; PG8_WAIT_L(0); PG8_MMA(0, 1, At, B1); PG8_BAR;
;             PG8_LDA(At, 1, 1); PG8_STAGE(PG8_SA(1, 0), a3, voffA);
;             PG8_BAR; PG8_WAIT_L(0); PG8_MMA(1, 0, At, B0); PG8_BAR; PG8_SCHED;
;             PG8_STAGE(PG8_SB(1, 1), b3 + hstepB, voffB);
;             PG8_WAIT_V(6); PG8_BAR; PG8_MMA(1, 1, At, B1); PG8_BAR;
	s_waitcnt lgkmcnt(0)
	s_setprio 1
	s_waitcnt lgkmcnt(3)
	v_mfma_f32_16x16x32_bf16 v[116:119], v[176:179], v[144:147], 0
	s_waitcnt lgkmcnt(1)
	v_mfma_f32_16x16x32_bf16 v[112:115], v[192:195], v[144:147], 0
	v_mfma_f32_16x16x32_bf16 v[100:103], v[176:179], v[152:155], 0
	v_mfma_f32_16x16x32_bf16 v[96:99], v[192:195], v[152:155], 0
	v_mfma_f32_16x16x32_bf16 v[84:87], v[176:179], v[160:163], 0
	v_mfma_f32_16x16x32_bf16 v[80:83], v[192:195], v[160:163], 0
	v_mfma_f32_16x16x32_bf16 v[68:71], v[176:179], v[168:171], 0
	v_mfma_f32_16x16x32_bf16 v[64:67], v[192:195], v[168:171], 0
	v_mfma_f32_16x16x32_bf16 v[116:119], v[180:183], v[148:151], v[116:119]
	s_waitcnt lgkmcnt(0)
	v_mfma_f32_16x16x32_bf16 v[112:115], v[196:199], v[148:151], v[112:115]
	v_mfma_f32_16x16x32_bf16 v[100:103], v[180:183], v[156:159], v[100:103]
	v_mfma_f32_16x16x32_bf16 v[96:99], v[196:199], v[156:159], v[96:99]
	v_mfma_f32_16x16x32_bf16 v[84:87], v[180:183], v[164:167], v[84:87]
	v_mfma_f32_16x16x32_bf16 v[80:83], v[196:199], v[164:167], v[80:83]
	v_mfma_f32_16x16x32_bf16 v[68:71], v[180:183], v[172:175], v[68:71]
	v_mfma_f32_16x16x32_bf16 v[64:67], v[196:199], v[172:175], v[64:67]
	s_setprio 0
	s_and_b32 s29, s19, 0xffff
	s_mov_b32 s30, s10
	s_mov_b32 s31, s11
	s_mov_b32 m0, s65
	s_barrier
	ds_read_b128 v[144:147], v228 offset:16384
	ds_read_b128 v[148:151], v228 offset:17408
	ds_read_b128 v[152:155], v228 offset:18432
	ds_read_b128 v[156:159], v228 offset:19456
	ds_read_b128 v[160:163], v228 offset:20480
	ds_read_b128 v[164:167], v228 offset:21504
	ds_read_b128 v[168:171], v228 offset:22528
	ds_read_b128 v[172:175], v228 offset:23552
	buffer_load_dwordx4 v222, s[28:31], 0 offen lds
	s_mov_b32 m0, s75
	s_nop 0
	buffer_load_dwordx4 v224, s[28:31], 0 offen lds
	s_barrier
	s_waitcnt lgkmcnt(0)
	s_setprio 1
	s_waitcnt lgkmcnt(7)
	v_mfma_f32_16x16x32_bf16 v[60:63], v[128:131], v[144:147], 0
	v_mfma_f32_16x16x32_bf16 v[56:59], v[136:139], v[144:147], 0
	s_waitcnt lgkmcnt(5)
	v_mfma_f32_16x16x32_bf16 v[44:47], v[128:131], v[152:155], 0
	v_mfma_f32_16x16x32_bf16 v[40:43], v[136:139], v[152:155], 0
	s_waitcnt lgkmcnt(3)
	v_mfma_f32_16x16x32_bf16 v[28:31], v[128:131], v[160:163], 0
	v_mfma_f32_16x16x32_bf16 v[24:27], v[136:139], v[160:163], 0
	s_waitcnt lgkmcnt(1)
	v_mfma_f32_16x16x32_bf16 v[12:15], v[128:131], v[168:171], 0
	v_mfma_f32_16x16x32_bf16 v[8:11], v[136:139], v[168:171], 0
	v_mfma_f32_16x16x32_bf16 v[60:63], v[132:135], v[148:151], v[60:63]
	v_mfma_f32_16x16x32_bf16 v[56:59], v[140:143], v[148:151], v[56:59]
	v_mfma_f32_16x16x32_bf16 v[44:47], v[132:135], v[156:159], v[44:47]
	v_mfma_f32_16x16x32_bf16 v[40:43], v[140:143], v[156:159], v[40:43]
	v_mfma_f32_16x16x32_bf16 v[28:31], v[132:135], v[164:167], v[28:31]
	v_mfma_f32_16x16x32_bf16 v[24:27], v[140:143], v[164:167], v[24:27]
	s_waitcnt lgkmcnt(0)
	v_mfma_f32_16x16x32_bf16 v[12:15], v[132:135], v[172:175], v[12:15]
	v_mfma_f32_16x16x32_bf16 v[8:11], v[140:143], v[172:175], v[8:11]
	s_setprio 0
	s_barrier
	s_add_u32 s8, s24, s38
	s_addc_u32 s23, s18, s39
	s_and_b32 s9, s23, 0xffff
	s_mov_b32 m0, s76
	s_nop 0
	buffer_load_dwordx4 v223, s[8:11], 0 offen lds
	s_mov_b32 m0, s77
	s_nop 0
	buffer_load_dwordx4 v225, s[8:11], 0 offen lds
	s_waitcnt vmcnt(6)
	s_barrier
	s_setprio 1
	v_mfma_f32_16x16x32_bf16 v[52:55], v[176:179], v[144:147], 0
	v_mfma_f32_16x16x32_bf16 v[48:51], v[192:195], v[144:147], 0
	v_mfma_f32_16x16x32_bf16 v[36:39], v[176:179], v[152:155], 0
	v_mfma_f32_16x16x32_bf16 v[32:35], v[192:195], v[152:155], 0
	v_mfma_f32_16x16x32_bf16 v[20:23], v[176:179], v[160:163], 0
	v_mfma_f32_16x16x32_bf16 v[16:19], v[192:195], v[160:163], 0
	v_mfma_f32_16x16x32_bf16 v[4:7], v[176:179], v[168:171], 0
	v_mfma_f32_16x16x32_bf16 v[0:3], v[192:195], v[168:171], 0
	v_mfma_f32_16x16x32_bf16 v[52:55], v[180:183], v[148:151], v[52:55]
	v_mfma_f32_16x16x32_bf16 v[48:51], v[196:199], v[148:151], v[48:51]
	v_mfma_f32_16x16x32_bf16 v[36:39], v[180:183], v[156:159], v[36:39]
	v_mfma_f32_16x16x32_bf16 v[32:35], v[196:199], v[156:159], v[32:35]
	v_mfma_f32_16x16x32_bf16 v[20:23], v[180:183], v[164:167], v[20:23]
	v_mfma_f32_16x16x32_bf16 v[16:19], v[196:199], v[164:167], v[16:19]
	v_mfma_f32_16x16x32_bf16 v[4:7], v[180:183], v[172:175], v[4:7]
	v_mfma_f32_16x16x32_bf16 v[0:3], v[196:199], v[172:175], v[0:3]
	s_setprio 0
	s_barrier
	s_branch .Lkmid_922
	.p2align 6
	s_nop 0
	s_nop 0

; __device__ __forceinline__ unsigned cvt_pk_bf16(float lo, float hi) { unsigned r; asm volatile("v_cvt_pk_bf16_f32 %0, %1, %2" : "=v"(r) : "v"(lo), "v"(hi)); return r; }
; __device__ __forceinline__ float bf_lo(unsigned w) { return __uint_as_float(w << 16); }
; __device__ __forceinline__ float bf_hi(unsigned w) { return __uint_as_float(w & 0xffff0000u); }
; #define PG8_WAIT_V(n) asm volatile("s_waitcnt vmcnt(" #n ")" ::: "memory")
; #define PG8_BAR __builtin_amdgcn_s_barrier()
;     ...
; #pragma unroll
;         for (int a = 0; a < 2; ++a)
; #pragma unroll
;             for (int b = 0; b < 2; ++b)
; #pragma unroll
;                 for (int m = 0; m < 4; ++m)
; #pragma unroll
;                     for (int n = 0; n < 2; ++n) acc[a][b][m][n] = (f32x4){0.f, 0.f, 0.f, 0.f};
;         cur = nxt; cA = nA; cB = nB; ++ui;
;     }
;     PG8_WAIT_V(0);
;     if (wr == 0) PG8_BAR;
;     PG8_BAR;
;     __device__ __forceinline__ void operator()(const Acc& acc, const Unit& u, int wr, int wc, int fr, int fq, LAS unsigned char* lds, f32x4 epar) const {
;     ...
;             for (int m = 0; m < 4; ++m) { const int r = u.pm * BM + ai * HALF + wr * 64 + m * 16 + fr; float s = 0.f;
; #pragma unroll
;                 for (int bj = 0; bj < 2; ++bj) { const size_t off = (size_t)r * DM + u.pn * 256 + bj * 128 + wc * 32 + 8 * fq;
;                     const u32x4 q = hv[ai][m][bj];
;                     f32x4 v0 = (f32x4){bf_lo(q.x), bf_hi(q.x), bf_lo(q.y), bf_hi(q.y)}, v1 = (f32x4){bf_lo(q.z), bf_hi(q.z), bf_lo(q.w), bf_hi(q.w)};
;                     v0 += acc[ai][bj][m][0]; v1 += acc[ai][bj][m][1];
;                     u32x4 w; w.x = cvt_pk_bf16(v0[0], v0[1]); w.y = cvt_pk_bf16(v0[2], v0[3]); w.z = cvt_pk_bf16(v1[0], v1[1]); w.w = cvt_pk_bf16(v1[2], v1[3]);
;                     *(u32x4*)(HB + off) = w;
;                     s += (v0[0] * v0[0] + v0[1] * v0[1]) + (v0[2] * v0[2] + v0[3] * v0[3]) + (v1[0] * v1[0] + v1[1] * v1[1]) + (v1[2] * v1[2] + v1[3] * v1[3]); }
;                 s += __shfl_xor(s, 16); s += __shfl_xor(s, 32);
;                 if (fq == 0) unsafeAtomicAdd(ssq + r, s); }
.LBB0_937:
	s_or_b64 exec, exec, s[8:9]
	s_waitcnt vmcnt(15)
	v_lshlrev_b32_e32 v16, 16, v132
	s_waitcnt lgkmcnt(0)
	v_and_b32_e32 v17, 0xffff0000, v132
	v_lshlrev_b32_e32 v18, 16, v133
	v_and_b32_e32 v19, 0xffff0000, v133
	v_lshlrev_b32_e32 v20, 16, v134
	v_and_b32_e32 v21, 0xffff0000, v134
	v_pk_add_f32 v[12:13], v[12:13], v[16:17]
	v_pk_add_f32 v[14:15], v[14:15], v[18:19]
	v_pk_add_f32 v[18:19], v[8:9], v[20:21]
	v_cvt_pk_bf16_f32 v8, v12, v13
	v_mul_f32_e32 v13, v13, v13
	v_fmac_f32_e32 v13, v12, v12
	v_mul_f32_e32 v12, v15, v15
	v_fmac_f32_e32 v12, v14, v14
	v_lshlrev_b32_e32 v22, 16, v135
	v_and_b32_e32 v23, 0xffff0000, v135
	v_add_f32_e32 v12, v13, v12
	v_mul_f32_e32 v13, v19, v19
	v_pk_add_f32 v[16:17], v[10:11], v[22:23]
	v_fmac_f32_e32 v13, v18, v18
	v_add_f32_e32 v12, v13, v12
	v_mul_f32_e32 v13, v17, v17
	v_fmac_f32_e32 v13, v16, v16
	v_cvt_pk_bf16_f32 v9, v14, v15
	v_add_f32_e32 v22, v13, v12
	s_waitcnt vmcnt(14)
	v_lshlrev_b32_e32 v12, 16, v128
	v_and_b32_e32 v13, 0xffff0000, v128
	v_lshlrev_b32_e32 v14, 16, v129
	v_and_b32_e32 v15, 0xffff0000, v129
	v_cvt_pk_bf16_f32 v10, v18, v19
	v_cvt_pk_bf16_f32 v11, v16, v17
	v_lshlrev_b32_e32 v16, 16, v130
	v_and_b32_e32 v17, 0xffff0000, v130
	v_pk_add_f32 v[6:7], v[6:7], v[14:15]
	v_pk_add_f32 v[4:5], v[4:5], v[12:13]
	v_pk_add_f32 v[14:15], v[0:1], v[16:17]
	v_mul_f32_e32 v0, v5, v5
	v_mul_f32_e32 v1, v7, v7
	v_fmac_f32_e32 v0, v4, v4
	v_fmac_f32_e32 v1, v6, v6
	v_lshlrev_b32_e32 v18, 16, v131
	v_and_b32_e32 v19, 0xffff0000, v131
	v_add_f32_e32 v0, v0, v1
	v_mul_f32_e32 v1, v15, v15
	v_pk_add_f32 v[12:13], v[2:3], v[18:19]
	v_fmac_f32_e32 v1, v14, v14
	v_add_f32_e32 v0, v1, v0
	v_mul_f32_e32 v1, v13, v13
	v_fmac_f32_e32 v1, v12, v12
	v_add_f32_e32 v0, v1, v0
	v_add_f32_e32 v3, v22, v0
	ds_bpermute_b32 v18, v112, v3
	v_lshl_add_u64 v[20:21], s[20:21], 0, v[194:195]
	v_lshl_add_u64 v[20:21], s[0:1], 1, v[20:21]
	v_lshl_add_u64 v[0:1], v[20:21], 0, s[44:45]
	v_lshl_add_u64 v[16:17], v[0:1], 0, v[184:185]
	s_waitcnt lgkmcnt(0)
	v_add_f32_e32 v0, v3, v18
	ds_bpermute_b32 v1, v113, v0
	global_store_dwordx4 v[16:17], v[8:11], off
	v_cvt_pk_bf16_f32 v2, v4, v5
	v_cvt_pk_bf16_f32 v3, v6, v7
	v_cvt_pk_bf16_f32 v4, v14, v15
	v_cvt_pk_bf16_f32 v5, v12, v13
	global_store_dwordx4 v[16:17], v[2:5], off offset:256
	s_and_saveexec_b64 s[0:1], s[4:5]
	s_cbranch_execz .LBB0_913
	s_waitcnt lgkmcnt(0)
	v_add_f32_e32 v2, v0, v1
	v_lshl_add_u64 v[0:1], v[192:193], 2, s[12:13]
	global_atomic_add_f32 v[0:1], v2, off
	s_branch .LBB0_913
.Lkzero_922:
	v_mov_b32_e32 v123, 0
	v_mov_b32_e32 v122, v123
	v_mov_b32_e32 v121, v123
	v_mov_b32_e32 v120, v123
	v_mov_b32_e32 v127, v123
	v_mov_b32_e32 v126, v123
	v_mov_b32_e32 v125, v123
	v_mov_b32_e32 v124, v123
	v_mov_b32_e32 v111, v123
	v_mov_b32_e32 v110, v123
	v_mov_b32_e32 v109, v123
	v_mov_b32_e32 v108, v123
	v_mov_b32_e32 v107, v123
	v_mov_b32_e32 v106, v123
	v_mov_b32_e32 v105, v123
	v_mov_b32_e32 v104, v123
	v_mov_b32_e32 v95, v123
	v_mov_b32_e32 v94, v123
	v_mov_b32_e32 v93, v123
	v_mov_b32_e32 v92, v123
	v_mov_b32_e32 v91, v123
	v_mov_b32_e32 v90, v123
	v_mov_b32_e32 v89, v123
	v_mov_b32_e32 v88, v123
	v_mov_b32_e32 v79, v123
	v_mov_b32_e32 v78, v123
	v_mov_b32_e32 v77, v123
	v_mov_b32_e32 v76, v123
	v_mov_b32_e32 v75, v123
	v_mov_b32_e32 v74, v123
	v_mov_b32_e32 v73, v123
	v_mov_b32_e32 v72, v123
	v_mov_b32_e32 v119, v123
	v_mov_b32_e32 v118, v123
	v_mov_b32_e32 v117, v123
	v_mov_b32_e32 v116, v123
	v_mov_b32_e32 v115, v123
	v_mov_b32_e32 v114, v123
	v_mov_b32_e32 v113, v123
	v_mov_b32_e32 v112, v123
	v_mov_b32_e32 v103, v123
	v_mov_b32_e32 v102, v123
	v_mov_b32_e32 v101, v123
	v_mov_b32_e32 v100, v123
	v_mov_b32_e32 v99, v123
	v_mov_b32_e32 v98, v123
	v_mov_b32_e32 v97, v123
	v_mov_b32_e32 v96, v123
	v_mov_b32_e32 v87, v123
	v_mov_b32_e32 v86, v123
	v_mov_b32_e32 v85, v123
	v_mov_b32_e32 v84, v123
	v_mov_b32_e32 v83, v123
	v_mov_b32_e32 v82, v123
	v_mov_b32_e32 v81, v123
	v_mov_b32_e32 v80, v123
	v_mov_b32_e32 v71, v123
	v_mov_b32_e32 v70, v123
	v_mov_b32_e32 v69, v123
	v_mov_b32_e32 v68, v123
	v_mov_b32_e32 v67, v123
	v_mov_b32_e32 v66, v123
	v_mov_b32_e32 v65, v123
	v_mov_b32_e32 v64, v123
	v_mov_b32_e32 v63, v123
	v_mov_b32_e32 v62, v123
	v_mov_b32_e32 v61, v123
	v_mov_b32_e32 v60, v123
	v_mov_b32_e32 v59, v123
	v_mov_b32_e32 v58, v123
	v_mov_b32_e32 v57, v123
	v_mov_b32_e32 v56, v123
	v_mov_b32_e32 v47, v123
	v_mov_b32_e32 v46, v123
	v_mov_b32_e32 v45, v123
	v_mov_b32_e32 v44, v123
	v_mov_b32_e32 v43, v123
	v_mov_b32_e32 v42, v123
	v_mov_b32_e32 v41, v123
	v_mov_b32_e32 v40, v123
	v_mov_b32_e32 v31, v123
	v_mov_b32_e32 v30, v123
	v_mov_b32_e32 v29, v123
	v_mov_b32_e32 v28, v123
	v_mov_b32_e32 v27, v123
	v_mov_b32_e32 v26, v123
	v_mov_b32_e32 v25, v123
	v_mov_b32_e32 v24, v123
	v_mov_b32_e32 v15, v123
	v_mov_b32_e32 v14, v123
	v_mov_b32_e32 v13, v123
	v_mov_b32_e32 v12, v123
	v_mov_b32_e32 v11, v123
	v_mov_b32_e32 v10, v123
	v_mov_b32_e32 v9, v123
	v_mov_b32_e32 v8, v123
	v_mov_b32_e32 v55, v123
	v_mov_b32_e32 v54, v123
	v_mov_b32_e32 v53, v123
	v_mov_b32_e32 v52, v123
	v_mov_b32_e32 v51, v123
	v_mov_b32_e32 v50, v123
	v_mov_b32_e32 v49, v123
	v_mov_b32_e32 v48, v123
	v_mov_b32_e32 v39, v123
	v_mov_b32_e32 v38, v123
	v_mov_b32_e32 v37, v123
	v_mov_b32_e32 v36, v123
	v_mov_b32_e32 v35, v123
	v_mov_b32_e32 v34, v123
	v_mov_b32_e32 v33, v123
	v_mov_b32_e32 v32, v123
	v_mov_b32_e32 v23, v123
	v_mov_b32_e32 v22, v123
	v_mov_b32_e32 v21, v123
	v_mov_b32_e32 v20, v123
	v_mov_b32_e32 v19, v123
	v_mov_b32_e32 v18, v123
	v_mov_b32_e32 v17, v123
	v_mov_b32_e32 v16, v123
	v_mov_b32_e32 v7, v123
	v_mov_b32_e32 v6, v123
	v_mov_b32_e32 v5, v123
	v_mov_b32_e32 v4, v123
	v_mov_b32_e32 v3, v123
	v_mov_b32_e32 v2, v123
	v_mov_b32_e32 v1, v123
	v_mov_b32_e32 v0, v123
	s_branch .LBB0_923
.LBB0_939:
	s_waitcnt vmcnt(0)
	v_readlane_b32 s52, v252, 40
	s_cmpk_gt_u32 s71, 0xff
	v_readlane_b32 s54, v252, 42
	v_readlane_b32 s55, v252, 43
	v_readlane_b32 s56, v252, 44
	v_readlane_b32 s57, v252, 45
	v_readlane_b32 s53, v252, 41
	v_readlane_b32 s58, v252, 46
	v_readlane_b32 s59, v252, 47
	s_cbranch_scc1 .LBB0_941
	s_barrier

;     __device__ __forceinline__ size_t a_off(const Unit& u) const { return (size_t)u.pm * atile; }
;     __device__ __forceinline__ size_t b_off(const Unit& u) const { return (size_t)u.pn * btile; }
;     __device__ __forceinline__ bool next(int i, Unit& u) const { const long L = (long)i * G + c; if (L >= NG * 8) return false; u.g = (int)(L >> 3); u.pm = (int)(L & 7); u.pn = 0; return true; }
;     __device__ __forceinline__ size_t a_off(const Unit& u) const { return ((size_t)u.g * NROW + (size_t)u.pm * BM) * KA * 2; }
;     __device__ __forceinline__ size_t b_off(const Unit& u) const { return (size_t)u.g * btile; }
;     __device__ __forceinline__ bool next(int i, Unit& u) const { if (i >= 2) return false; u.g = g; u.pm = 2 * b + i; u.pn = 0; return true; }
;     __device__ __forceinline__ size_t a_off(const Unit& u) const { return ((size_t)u.g * NROW + (size_t)u.pm * BM) * KA * 2; }
;     __device__ __forceinline__ size_t b_off(const Unit& u) const { return (size_t)u.g * btile; }
; #define PG8_LDA(dst, b, h) do { _Pragma("unroll") for (int m = 0; m < 4; ++m) _Pragma("unroll") for (int k = 0; k < 2; ++k) dst[m][k] = *(const LAS bf16x8*)(lds + PG8_SA(b, h) + aoff + m * 2048 + k * 1024); } while (0)
; #define PG8_WAIT_L(n) asm volatile("s_waitcnt lgkmcnt(" #n ")" ::: "memory")
; #define PG8_BAR __builtin_amdgcn_s_barrier()
;     ...
;         const bool has_next = S.next(ui + 1, nxt);
;         const char* nA = has_next ? (const char*)Ap + S.a_off(nxt) : cA; const char* nB = has_next ? (const char*)Btp + S.b_off(nxt) : cB;
;         for (int t = 0; t < nt; t += 2) {
;             const bool last = (t == nt - 2);
;             const char* a1 = cA + (size_t)(t + 1) * kstep;
;             const char* a2 = last ? nA : cA + (size_t)(t + 2) * kstep; const char* b2 = last ? nB : cB + (size_t)(t + 2) * kstep;
;             const char* a3 = a2 + kstep; const char* b3 = b2 + kstep;
;             PG8_LDB(B0, 0, 0); PG8_SCHED; PG8_LDA(At, 0, 0); PG8_STAGE(PG8_SA(1, 1), a1 + hstepA, voffA);
;             PG8_WAIT_L(8); PG8_BAR; PG8_WAIT_L(0); PG8_MMA(0, 0, At, B0); PG8_BAR; PG8_SCHED;
;             PG8_LDB(B1, 0, 1); PG8_STAGE(PG8_SB(0, 0), b2, voffB);
;             PG8_BAR; PG8_WAIT_L(0); PG8_MMA(0, 1, At, B1); PG8_BAR;
;             PG8_LDA(At, 0, 1); PG8_STAGE(PG8_SA(0, 0), a2, voffA);
;             PG8_BAR; PG8_WAIT_L(0); PG8_MMA(1, 0, At, B0); PG8_BAR; PG8_SCHED;
.Lnext_done_28037:
.LBB0_982:
	s_ashr_i32 s57, s56, 31
	s_lshl_b64 s[16:17], s[56:57], 19
	s_add_u32 s58, s20, s16
	s_addc_u32 s59, s21, s17
	s_ashr_i32 s53, s52, 31
	s_lshl_b64 s[16:17], s[52:53], 19
	s_add_u32 s64, s75, s16
	v_cmp_lt_i64_e64 s[12:13], s[12:13], v[170:171]
	s_addc_u32 s65, s76, s17
	s_andn2_b64 vcc, exec, s[50:51]
	s_cbranch_vccnz .Lkzero_984
	s_and_b64 s[16:17], s[12:13], exec
	s_cselect_b32 s53, s59, s27
	s_cselect_b32 s57, s58, s26
	s_cselect_b32 s94, s65, s25
	s_cselect_b32 s95, s64, s24
	s_add_u32 s96, s26, 0x100
	s_addc_u32 s97, s27, 0
	s_add_u32 vcc_lo, s24, 0x100
	s_addc_u32 vcc_hi, s25, 0
	s_mov_b32 s16, 0
	ds_read_b128 v[76:79], v193
	ds_read_b128 v[88:91], v193 offset:1024
	ds_read_b128 v[92:95], v193 offset:2048
	ds_read_b128 v[128:131], v193 offset:3072
	s_add_i32 s22, s16, 2
	s_cmp_eq_u32 s90, s16
	s_cselect_b32 s36, s57, s96
	s_cselect_b32 s26, s53, s97
	s_cselect_b32 s25, s94, vcc_hi
	s_cselect_b32 s28, s95, vcc_lo
	s_add_u32 s24, s36, 0x80
	s_addc_u32 s23, s26, 0
	s_add_u32 s16, s96, s44
	s_addc_u32 s17, s97, s45
	s_add_u32 s16, s16, 0xffffff80
	s_addc_u32 s17, s17, -1
	s_and_b32 s17, s17, 0xffff
	s_mov_b32 m0, s91
	ds_read_b128 v[132:135], v194
	ds_read_b128 v[136:139], v194 offset:1024
	ds_read_b128 v[140:143], v194 offset:2048
	ds_read_b128 v[174:177], v194 offset:3072
	ds_read_b128 v[178:181], v194 offset:4096
	ds_read_b128 v[182:185], v194 offset:5120
	ds_read_b128 v[202:205], v194 offset:6144
	ds_read_b128 v[206:209], v194 offset:7168
	buffer_load_dwordx4 v186, s[16:19], 0 offen lds
	s_mov_b32 m0, s92
	s_nop 0
	buffer_load_dwordx4 v188, s[16:19], 0 offen lds
	s_waitcnt lgkmcnt(8)
	s_barrier
	s_waitcnt lgkmcnt(0)
	s_setprio 1
	s_waitcnt lgkmcnt(7)
	v_mfma_f32_16x16x32_bf16 v[152:155], v[76:79], v[132:135], 0
	v_mfma_f32_16x16x32_bf16 v[144:147], v[92:95], v[132:135], 0
	s_waitcnt lgkmcnt(5)
	v_mfma_f32_16x16x32_bf16 v[124:127], v[76:79], v[140:143], 0
	v_mfma_f32_16x16x32_bf16 v[120:123], v[92:95], v[140:143], 0
	s_waitcnt lgkmcnt(3)
	v_mfma_f32_16x16x32_bf16 v[108:111], v[76:79], v[178:181], 0
	v_mfma_f32_16x16x32_bf16 v[104:107], v[92:95], v[178:181], 0
	s_waitcnt lgkmcnt(1)
	v_mfma_f32_16x16x32_bf16 v[84:87], v[76:79], v[202:205], 0
	v_mfma_f32_16x16x32_bf16 v[80:83], v[92:95], v[202:205], 0
	v_mfma_f32_16x16x32_bf16 v[152:155], v[88:91], v[136:139], v[152:155]
	v_mfma_f32_16x16x32_bf16 v[144:147], v[128:131], v[136:139], v[144:147]
	v_mfma_f32_16x16x32_bf16 v[124:127], v[88:91], v[174:177], v[124:127]
	v_mfma_f32_16x16x32_bf16 v[120:123], v[128:131], v[174:177], v[120:123]
	v_mfma_f32_16x16x32_bf16 v[108:111], v[88:91], v[182:185], v[108:111]
	v_mfma_f32_16x16x32_bf16 v[104:107], v[128:131], v[182:185], v[104:107]
	s_waitcnt lgkmcnt(0)
	v_mfma_f32_16x16x32_bf16 v[84:87], v[88:91], v[206:209], v[84:87]
	v_mfma_f32_16x16x32_bf16 v[80:83], v[128:131], v[206:209], v[80:83]
	s_setprio 0
	s_barrier
	s_and_b32 s29, s25, 0xffff
	s_mov_b32 s30, s18
	s_mov_b32 s31, s19
	s_mov_b32 m0, s71
	ds_read_b128 v[210:213], v195
	ds_read_b128 v[214:217], v195 offset:1024
	ds_read_b128 v[218:221], v195 offset:2048
	ds_read_b128 v[222:225], v195 offset:3072
	buffer_load_dwordx4 v187, s[28:31], 0 offen lds
	s_mov_b32 m0, s77
	s_nop 0
	buffer_load_dwordx4 v189, s[28:31], 0 offen lds
	s_barrier
; #define PG8_STAGE(bufoff, gbase, voff) do { const __amdgpu_buffer_rsrc_t _r = __builtin_amdgcn_make_buffer_rsrc((void*)(gbase), (short)0, 0x7fffffff, 0x00020000); _Pragma("unroll") for (int _i = 0; _i < 2; ++_i) \
;         __builtin_amdgcn_raw_ptr_buffer_load_lds(_r, (LAS unsigned*)(lds + (bufoff) + ldsw + _i * 8192), 16, (int)(voff)[_i], 0, 0, 0); } while (0)
; #define PG8_LDA(dst, b, h) do { _Pragma("unroll") for (int m = 0; m < 4; ++m) _Pragma("unroll") for (int k = 0; k < 2; ++k) dst[m][k] = *(const LAS bf16x8*)(lds + PG8_SA(b, h) + aoff + m * 2048 + k * 1024); } while (0)
; #define PG8_LDB(dst, b, h) do { _Pragma("unroll") for (int n = 0; n < 2; ++n) _Pragma("unroll") for (int k = 0; k < 2; ++k) dst[n][k] = *(const LAS bf16x8*)(lds + PG8_SB(b, h) + boff + n * 2048 + k * 1024); } while (0)
; #define PG8_MMA(ai, bj, At, Bt) do { __builtin_amdgcn_s_setprio(1); _Pragma("unroll") for (int k = 0; k < 2; ++k) _Pragma("unroll") for (int m = 0; m < 4; ++m) _Pragma("unroll") for (int n = 0; n < ((bj) == 1 ? NB1 : 2); ++n) \
;         acc[ai][bj][m][n] = __builtin_amdgcn_mfma_f32_16x16x32_bf16(Bt[n][k], At[m][k], acc[ai][bj][m][n], 0, 0, 0); __builtin_amdgcn_s_setprio(0); } while (0)
; #define PG8_WAIT_V(n) asm volatile("s_waitcnt vmcnt(" #n ")" ::: "memory")
; #define PG8_WAIT_L(n) asm volatile("s_waitcnt lgkmcnt(" #n ")" ::: "memory")
; #define PG8_BAR __builtin_amdgcn_s_barrier()
; #define PG8_SCHED __builtin_amdgcn_sched_barrier(0)
;     ...
;             PG8_BAR; PG8_WAIT_L(0); PG8_MMA(1, 0, At, B0); PG8_BAR; PG8_SCHED;
;             PG8_STAGE(PG8_SB(0, 1), b2 + hstepB, voffB);
;             PG8_WAIT_V(6); PG8_BAR; PG8_MMA(1, 1, At, B1); PG8_BAR;
;             PG8_LDB(B0, 1, 0); PG8_SCHED; PG8_LDA(At, 1, 0); PG8_STAGE(PG8_SA(0, 1), a2 + hstepA, voffA);
;             PG8_WAIT_L(8); PG8_BAR; PG8_WAIT_L(0); PG8_MMA(0, 0, At, B0); PG8_BAR; PG8_SCHED;
;             PG8_LDB(B1, 1, 1); PG8_STAGE(PG8_SB(1, 0), b3, voffB);
;             PG8_BAR; PG8_WAIT_L(0); PG8_MMA(0, 1, At, B1); PG8_BAR;
;             PG8_LDA(At, 1, 1); PG8_STAGE(PG8_SA(1, 0), a3, voffA);
;             PG8_BAR; PG8_WAIT_L(0); PG8_MMA(1, 0, At, B0); PG8_BAR; PG8_SCHED;
;             PG8_STAGE(PG8_SB(1, 1), b3 + hstepB, voffB);
;             PG8_WAIT_V(6); PG8_BAR; PG8_MMA(1, 1, At, B1); PG8_BAR;
	s_waitcnt lgkmcnt(0)
	s_setprio 1
	s_waitcnt lgkmcnt(3)
	v_mfma_f32_16x16x32_bf16 v[116:119], v[210:213], v[140:143], 0
	s_waitcnt lgkmcnt(1)
	v_mfma_f32_16x16x32_bf16 v[112:115], v[218:221], v[140:143], 0
	v_mfma_f32_16x16x32_bf16 v[100:103], v[210:213], v[178:181], 0
	v_mfma_f32_16x16x32_bf16 v[96:99], v[218:221], v[178:181], 0
	v_mfma_f32_16x16x32_bf16 v[68:71], v[210:213], v[202:205], 0
	v_mfma_f32_16x16x32_bf16 v[64:67], v[218:221], v[202:205], 0
	v_mfma_f32_16x16x32_bf16 v[156:159], v[210:213], v[132:135], 0
	v_mfma_f32_16x16x32_bf16 v[132:135], v[218:221], v[132:135], 0
	v_mfma_f32_16x16x32_bf16 v[116:119], v[214:217], v[174:177], v[116:119]
	s_waitcnt lgkmcnt(0)
	v_mfma_f32_16x16x32_bf16 v[112:115], v[222:225], v[174:177], v[112:115]
	v_mfma_f32_16x16x32_bf16 v[100:103], v[214:217], v[182:185], v[100:103]
	v_mfma_f32_16x16x32_bf16 v[96:99], v[222:225], v[182:185], v[96:99]
	v_mfma_f32_16x16x32_bf16 v[68:71], v[214:217], v[206:209], v[68:71]
	v_mfma_f32_16x16x32_bf16 v[64:67], v[222:225], v[206:209], v[64:67]
	v_mfma_f32_16x16x32_bf16 v[140:143], v[214:217], v[136:139], v[156:159]
	v_mfma_f32_16x16x32_bf16 v[132:135], v[222:225], v[136:139], v[132:135]
	s_setprio 0
	s_and_b32 s37, s26, 0xffff
	s_mov_b32 s38, s18
	s_mov_b32 s39, s19
	s_mov_b32 m0, s67
	s_barrier
	ds_read_b128 v[136:139], v194 offset:16384
	ds_read_b128 v[148:151], v194 offset:17408
	ds_read_b128 v[156:159], v194 offset:18432
	ds_read_b128 v[174:177], v194 offset:19456
	ds_read_b128 v[178:181], v194 offset:20480
	ds_read_b128 v[182:185], v194 offset:21504
	ds_read_b128 v[202:205], v194 offset:22528
	ds_read_b128 v[206:209], v194 offset:23552
	buffer_load_dwordx4 v186, s[36:39], 0 offen lds
	s_mov_b32 m0, s78
	s_nop 0
	buffer_load_dwordx4 v188, s[36:39], 0 offen lds
	s_barrier
	s_waitcnt lgkmcnt(0)
	s_setprio 1
	s_waitcnt lgkmcnt(7)
	v_mfma_f32_16x16x32_bf16 v[60:63], v[76:79], v[136:139], 0
	v_mfma_f32_16x16x32_bf16 v[52:55], v[92:95], v[136:139], 0
	s_waitcnt lgkmcnt(5)
	v_mfma_f32_16x16x32_bf16 v[44:47], v[76:79], v[156:159], 0
	v_mfma_f32_16x16x32_bf16 v[40:43], v[92:95], v[156:159], 0
	s_waitcnt lgkmcnt(3)
	v_mfma_f32_16x16x32_bf16 v[28:31], v[76:79], v[178:181], 0
	v_mfma_f32_16x16x32_bf16 v[24:27], v[92:95], v[178:181], 0
	s_waitcnt lgkmcnt(1)
	v_mfma_f32_16x16x32_bf16 v[12:15], v[76:79], v[202:205], 0
	v_mfma_f32_16x16x32_bf16 v[8:11], v[92:95], v[202:205], 0
	v_mfma_f32_16x16x32_bf16 v[60:63], v[88:91], v[148:151], v[60:63]
	v_mfma_f32_16x16x32_bf16 v[52:55], v[128:131], v[148:151], v[52:55]
	v_mfma_f32_16x16x32_bf16 v[44:47], v[88:91], v[174:177], v[44:47]
	v_mfma_f32_16x16x32_bf16 v[40:43], v[128:131], v[174:177], v[40:43]
	v_mfma_f32_16x16x32_bf16 v[28:31], v[88:91], v[182:185], v[28:31]
	v_mfma_f32_16x16x32_bf16 v[24:27], v[128:131], v[182:185], v[24:27]
	s_waitcnt lgkmcnt(0)
	v_mfma_f32_16x16x32_bf16 v[12:15], v[88:91], v[206:209], v[12:15]
	v_mfma_f32_16x16x32_bf16 v[8:11], v[128:131], v[206:209], v[8:11]
	s_setprio 0
	s_barrier
	s_add_u32 s16, s28, s46
	s_addc_u32 s14, s25, s47
	s_and_b32 s17, s14, 0xffff
	s_mov_b32 m0, s79
	s_nop 0
	buffer_load_dwordx4 v187, s[16:19], 0 offen lds
	s_mov_b32 m0, s80
	s_nop 0
	buffer_load_dwordx4 v189, s[16:19], 0 offen lds
	s_waitcnt vmcnt(6)
	s_barrier
	s_setprio 1
	v_mfma_f32_16x16x32_bf16 v[56:59], v[210:213], v[136:139], 0
	v_mfma_f32_16x16x32_bf16 v[48:51], v[218:221], v[136:139], 0
	v_mfma_f32_16x16x32_bf16 v[36:39], v[210:213], v[156:159], 0
	v_mfma_f32_16x16x32_bf16 v[32:35], v[218:221], v[156:159], 0
	v_mfma_f32_16x16x32_bf16 v[20:23], v[210:213], v[178:181], 0
	v_mfma_f32_16x16x32_bf16 v[16:19], v[218:221], v[178:181], 0
	v_mfma_f32_16x16x32_bf16 v[4:7], v[210:213], v[202:205], 0
	v_mfma_f32_16x16x32_bf16 v[0:3], v[218:221], v[202:205], 0
	v_mfma_f32_16x16x32_bf16 v[56:59], v[214:217], v[148:151], v[56:59]
	v_mfma_f32_16x16x32_bf16 v[48:51], v[222:225], v[148:151], v[48:51]
	v_mfma_f32_16x16x32_bf16 v[36:39], v[214:217], v[174:177], v[36:39]
	v_mfma_f32_16x16x32_bf16 v[32:35], v[222:225], v[174:177], v[32:35]
	v_mfma_f32_16x16x32_bf16 v[20:23], v[214:217], v[182:185], v[20:23]
	v_mfma_f32_16x16x32_bf16 v[16:19], v[222:225], v[182:185], v[16:19]
	v_mfma_f32_16x16x32_bf16 v[4:7], v[214:217], v[206:209], v[4:7]
	v_mfma_f32_16x16x32_bf16 v[0:3], v[222:225], v[206:209], v[0:3]
	s_setprio 0
	s_barrier
	s_branch .Lkmid_984
	.p2align 6
	s_nop 0
	s_nop 0

; #define PG8_WAIT_V(n) asm volatile("s_waitcnt vmcnt(" #n ")" ::: "memory")
; #define PG8_BAR __builtin_amdgcn_s_barrier()
;     __device__ __forceinline__ f32x4 prefetch(const Unit&, int, int, int) const { return (f32x4){0.f, 0.f, 0.f, 0.f}; }
;     __device__ __forceinline__ f32x4 prefetch(const Unit&, int, int, int) const { return (f32x4){0.f, 0.f, 0.f, 0.f}; }
;     __device__ __forceinline__ f32x4 prefetch(const Unit&, int, int, int) const { return (f32x4){0.f, 0.f, 0.f, 0.f}; }
;     __device__ __forceinline__ f32x4 prefetch(const Unit&, int, int, int) const { return (f32x4){0.f, 0.f, 0.f, 0.f}; }
;     ...
;         if (has_next) epar = E.prefetch(nxt, wr, wc, lane);
;         if (!has_next) break;
; #pragma unroll
;         for (int a = 0; a < 2; ++a)
; #pragma unroll
;             for (int b = 0; b < 2; ++b)
; #pragma unroll
;                 for (int m = 0; m < 4; ++m)
; #pragma unroll
;                     for (int n = 0; n < 2; ++n) acc[a][b][m][n] = (f32x4){0.f, 0.f, 0.f, 0.f};
;         cur = nxt; cA = nA; cB = nB; ++ui;
;     }
;     PG8_WAIT_V(0);
;     if (wr == 0) PG8_BAR;
;     PG8_BAR;
;     __device__ __forceinline__ f32x4 prefetch(const Unit& u, int wr, int wc, int lane) const {
;         const float* ptr;
;         if (lane < 32) { const int arr = lane >> 3, j = lane & 7;
;             if (MODE == 0) ptr = (arr < 3 ? cw + arr * C : cb) + u.pn * 128 + wc * 32 + 4 * j;
;             else ptr = cw + (arr < 3 ? arr : 0) * C + u.pn * 64 + wc * 16 + 4 * (j & 3); }
;         else { const int k = lane - 32; ptr = ssq + u.pm * BM + (k >> 4) * HALF + wr * 64 + 4 * (k & 15); }
;         f32x4 v; asm volatile("global_load_dwordx4 %0, %1, off" : "=&v"(v) : "v"(ptr) : "memory"); return v;
.LBB0_998:
	s_or_b64 exec, exec, s[24:25]
	s_mov_b64 s[16:17], -1
	s_and_b64 vcc, exec, s[12:13]
	s_cbranch_vccz .LBB0_979
	s_lshl_b32 s12, s56, 8
	s_lshl_b32 s13, s52, 7
	v_mov_b32_e32 v0, s12
	v_mov_b32_e32 v1, s13
	v_cndmask_b32_e64 v0, v0, v1, s[4:5]
	v_ashrrev_i32_e32 v1, 31, v0
	v_lshl_add_u64 v[0:1], v[0:1], 2, v[168:169]
	v_lshl_add_u64 v[0:1], v[0:1], 0, v[160:161]
	global_load_dwordx4 v[72:75], v[0:1], off
	s_mov_b64 s[16:17], 0
	s_branch .LBB0_979
.Lkzero_984:
	v_mov_b32_e32 v155, 0
	v_mov_b32_e32 v154, v155
	v_mov_b32_e32 v153, v155
	v_mov_b32_e32 v152, v155
	v_mov_b32_e32 v147, v155
	v_mov_b32_e32 v146, v155
	v_mov_b32_e32 v145, v155
	v_mov_b32_e32 v144, v155
	v_mov_b32_e32 v127, v155
	v_mov_b32_e32 v126, v155
	v_mov_b32_e32 v125, v155
	v_mov_b32_e32 v124, v155
	v_mov_b32_e32 v123, v155
	v_mov_b32_e32 v122, v155
	v_mov_b32_e32 v121, v155
	v_mov_b32_e32 v120, v155
	v_mov_b32_e32 v111, v155
	v_mov_b32_e32 v110, v155
	v_mov_b32_e32 v109, v155
	v_mov_b32_e32 v108, v155
	v_mov_b32_e32 v107, v155
	v_mov_b32_e32 v106, v155
	v_mov_b32_e32 v105, v155
	v_mov_b32_e32 v104, v155
	v_mov_b32_e32 v87, v155
	v_mov_b32_e32 v86, v155
	v_mov_b32_e32 v85, v155
	v_mov_b32_e32 v84, v155
	v_mov_b32_e32 v83, v155
	v_mov_b32_e32 v82, v155
	v_mov_b32_e32 v81, v155
	v_mov_b32_e32 v80, v155
	v_mov_b32_e32 v159, v155
	v_mov_b32_e32 v158, v155
	v_mov_b32_e32 v157, v155
	v_mov_b32_e32 v156, v155
	v_mov_b32_e32 v151, v155
	v_mov_b32_e32 v150, v155
	v_mov_b32_e32 v149, v155
	v_mov_b32_e32 v148, v155
	v_mov_b32_e32 v119, v155
	v_mov_b32_e32 v118, v155
	v_mov_b32_e32 v117, v155
	v_mov_b32_e32 v116, v155
	v_mov_b32_e32 v115, v155
	v_mov_b32_e32 v114, v155
	v_mov_b32_e32 v113, v155
	v_mov_b32_e32 v112, v155
	v_mov_b32_e32 v103, v155
	v_mov_b32_e32 v102, v155
	v_mov_b32_e32 v101, v155
	v_mov_b32_e32 v100, v155
	v_mov_b32_e32 v99, v155
	v_mov_b32_e32 v98, v155
	v_mov_b32_e32 v97, v155
	v_mov_b32_e32 v96, v155
	v_mov_b32_e32 v71, v155
	v_mov_b32_e32 v70, v155
	v_mov_b32_e32 v69, v155
	v_mov_b32_e32 v68, v155
	v_mov_b32_e32 v67, v155
	v_mov_b32_e32 v66, v155
	v_mov_b32_e32 v65, v155
	v_mov_b32_e32 v64, v155
	v_mov_b32_e32 v63, v155
	v_mov_b32_e32 v62, v155
	v_mov_b32_e32 v61, v155
	v_mov_b32_e32 v60, v155
	v_mov_b32_e32 v55, v155
	v_mov_b32_e32 v54, v155
	v_mov_b32_e32 v53, v155
	v_mov_b32_e32 v52, v155
	v_mov_b32_e32 v47, v155
	v_mov_b32_e32 v46, v155
	v_mov_b32_e32 v45, v155
	v_mov_b32_e32 v44, v155
	v_mov_b32_e32 v43, v155
	v_mov_b32_e32 v42, v155
	v_mov_b32_e32 v41, v155
	v_mov_b32_e32 v40, v155
	v_mov_b32_e32 v31, v155
	v_mov_b32_e32 v30, v155
	v_mov_b32_e32 v29, v155
	v_mov_b32_e32 v28, v155
	v_mov_b32_e32 v27, v155
	v_mov_b32_e32 v26, v155
	v_mov_b32_e32 v25, v155
	v_mov_b32_e32 v24, v155
	v_mov_b32_e32 v15, v155
	v_mov_b32_e32 v14, v155
	v_mov_b32_e32 v13, v155
	v_mov_b32_e32 v12, v155
	v_mov_b32_e32 v11, v155
	v_mov_b32_e32 v10, v155
	v_mov_b32_e32 v9, v155
	v_mov_b32_e32 v8, v155
	v_mov_b32_e32 v59, v155
	v_mov_b32_e32 v58, v155
	v_mov_b32_e32 v57, v155
	v_mov_b32_e32 v56, v155
	v_mov_b32_e32 v51, v155
	v_mov_b32_e32 v50, v155
	v_mov_b32_e32 v49, v155
	v_mov_b32_e32 v48, v155
	v_mov_b32_e32 v39, v155
	v_mov_b32_e32 v38, v155
	v_mov_b32_e32 v37, v155
	v_mov_b32_e32 v36, v155
	v_mov_b32_e32 v35, v155
	v_mov_b32_e32 v34, v155
	v_mov_b32_e32 v33, v155
	v_mov_b32_e32 v32, v155
	v_mov_b32_e32 v23, v155
	v_mov_b32_e32 v22, v155
	v_mov_b32_e32 v21, v155
	v_mov_b32_e32 v20, v155
	v_mov_b32_e32 v19, v155
	v_mov_b32_e32 v18, v155
	v_mov_b32_e32 v17, v155
	v_mov_b32_e32 v16, v155
	v_mov_b32_e32 v7, v155
	v_mov_b32_e32 v6, v155
	v_mov_b32_e32 v5, v155
	v_mov_b32_e32 v4, v155
	v_mov_b32_e32 v3, v155
	v_mov_b32_e32 v2, v155
	v_mov_b32_e32 v1, v155
	v_mov_b32_e32 v0, v155
	s_branch .LBB0_986
.LBB0_1000:
	s_waitcnt vmcnt(0)
	s_cmpk_gt_u32 s68, 0xff
	s_cbranch_scc1 .LBB0_1002
	s_barrier

; #define PG8_STAGE(bufoff, gbase, voff) do { const __amdgpu_buffer_rsrc_t _r = __builtin_amdgcn_make_buffer_rsrc((void*)(gbase), (short)0, 0x7fffffff, 0x00020000); _Pragma("unroll") for (int _i = 0; _i < 2; ++_i) \
;         __builtin_amdgcn_raw_ptr_buffer_load_lds(_r, (LAS unsigned*)(lds + (bufoff) + ldsw + _i * 8192), 16, (int)(voff)[_i], 0, 0, 0); } while (0)
; #define PG8_LDA(dst, b, h) do { _Pragma("unroll") for (int m = 0; m < 4; ++m) _Pragma("unroll") for (int k = 0; k < 2; ++k) dst[m][k] = *(const LAS bf16x8*)(lds + PG8_SA(b, h) + aoff + m * 2048 + k * 1024); } while (0)
; #define PG8_LDB(dst, b, h) do { _Pragma("unroll") for (int n = 0; n < 2; ++n) _Pragma("unroll") for (int k = 0; k < 2; ++k) dst[n][k] = *(const LAS bf16x8*)(lds + PG8_SB(b, h) + boff + n * 2048 + k * 1024); } while (0)
; #define PG8_MMA(ai, bj, At, Bt) do { __builtin_amdgcn_s_setprio(1); _Pragma("unroll") for (int k = 0; k < 2; ++k) _Pragma("unroll") for (int m = 0; m < 4; ++m) _Pragma("unroll") for (int n = 0; n < ((bj) == 1 ? NB1 : 2); ++n) \
;         acc[ai][bj][m][n] = __builtin_amdgcn_mfma_f32_16x16x32_bf16(Bt[n][k], At[m][k], acc[ai][bj][m][n], 0, 0, 0); __builtin_amdgcn_s_setprio(0); } while (0)
; #define PG8_WAIT_V(n) asm volatile("s_waitcnt vmcnt(" #n ")" ::: "memory")
; #define PG8_WAIT_L(n) asm volatile("s_waitcnt lgkmcnt(" #n ")" ::: "memory")
; #define PG8_BAR __builtin_amdgcn_s_barrier()
;     ...
;         for (int t = 0; t < nt; t += 2) {
;             const bool last = (t == nt - 2);
;             const char* a1 = cA + (size_t)(t + 1) * kstep;
;             const char* a2 = last ? nA : cA + (size_t)(t + 2) * kstep; const char* b2 = last ? nB : cB + (size_t)(t + 2) * kstep;
;             const char* a3 = a2 + kstep; const char* b3 = b2 + kstep;
;             PG8_LDB(B0, 0, 0); PG8_SCHED; PG8_LDA(At, 0, 0); PG8_STAGE(PG8_SA(1, 1), a1 + hstepA, voffA);
;             PG8_WAIT_L(8); PG8_BAR; PG8_WAIT_L(0); PG8_MMA(0, 0, At, B0); PG8_BAR; PG8_SCHED;
;             PG8_LDB(B1, 0, 1); PG8_STAGE(PG8_SB(0, 0), b2, voffB);
;             PG8_BAR; PG8_WAIT_L(0); PG8_MMA(0, 1, At, B1); PG8_BAR;
;             PG8_LDA(At, 0, 1); PG8_STAGE(PG8_SA(0, 0), a2, voffA);
;             PG8_BAR; PG8_WAIT_L(0); PG8_MMA(1, 0, At, B0); PG8_BAR; PG8_SCHED;
;             PG8_STAGE(PG8_SB(0, 1), b2 + hstepB, voffB);
;             PG8_WAIT_V(6); PG8_BAR; PG8_MMA(1, 1, At, B1); PG8_BAR;
.LBB0_1064:
	s_andn2_b64 vcc, exec, s[42:43]
	s_waitcnt lgkmcnt(0)
	s_cbranch_vccnz .Lkzero_1066
	s_add_u32 s79, s18, 0x100
	s_addc_u32 s80, s19, 0
	s_add_u32 s81, s16, 0x100
	s_addc_u32 s82, s17, 0
	s_mov_b32 s8, 0
	ds_read_b128 v[128:131], v227
	ds_read_b128 v[132:135], v227 offset:1024
	ds_read_b128 v[136:139], v227 offset:2048
	ds_read_b128 v[140:143], v227 offset:3072
	s_add_i32 s22, s8, 2
	s_cmp_eq_u32 s71, s8
	s_cselect_b32 s28, s0, s79
	s_cselect_b32 s19, s1, s80
	s_cselect_b32 s18, s45, s82
	s_cselect_b32 s24, s44, s81
	s_add_u32 s16, s28, 0x80
	s_addc_u32 s17, s19, 0
	s_add_u32 s8, s79, s36
	s_addc_u32 s9, s80, s37
	s_add_u32 s8, s8, 0xffffff80
	s_addc_u32 s9, s9, -1
	s_and_b32 s9, s9, 0xffff
	s_mov_b32 m0, s72
	ds_read_b128 v[144:147], v228
	ds_read_b128 v[148:151], v228 offset:1024
	ds_read_b128 v[152:155], v228 offset:2048
	ds_read_b128 v[156:159], v228 offset:3072
	ds_read_b128 v[160:163], v228 offset:4096
	ds_read_b128 v[164:167], v228 offset:5120
	ds_read_b128 v[168:171], v228 offset:6144
	ds_read_b128 v[172:175], v228 offset:7168
	buffer_load_dwordx4 v222, s[8:11], 0 offen lds
	s_mov_b32 m0, s73
	s_nop 0
	buffer_load_dwordx4 v224, s[8:11], 0 offen lds
	s_waitcnt lgkmcnt(8)
	s_barrier
	s_waitcnt lgkmcnt(0)
	s_setprio 1
	s_waitcnt lgkmcnt(7)
	v_mfma_f32_16x16x32_bf16 v[120:123], v[128:131], v[144:147], 0
	v_mfma_f32_16x16x32_bf16 v[124:127], v[136:139], v[144:147], 0
	s_waitcnt lgkmcnt(5)
	v_mfma_f32_16x16x32_bf16 v[108:111], v[128:131], v[152:155], 0
	v_mfma_f32_16x16x32_bf16 v[104:107], v[136:139], v[152:155], 0
	s_waitcnt lgkmcnt(3)
	v_mfma_f32_16x16x32_bf16 v[92:95], v[128:131], v[160:163], 0
	v_mfma_f32_16x16x32_bf16 v[88:91], v[136:139], v[160:163], 0
	s_waitcnt lgkmcnt(1)
	v_mfma_f32_16x16x32_bf16 v[76:79], v[128:131], v[168:171], 0
	v_mfma_f32_16x16x32_bf16 v[72:75], v[136:139], v[168:171], 0
	v_mfma_f32_16x16x32_bf16 v[120:123], v[132:135], v[148:151], v[120:123]
	v_mfma_f32_16x16x32_bf16 v[124:127], v[140:143], v[148:151], v[124:127]
	v_mfma_f32_16x16x32_bf16 v[108:111], v[132:135], v[156:159], v[108:111]
	v_mfma_f32_16x16x32_bf16 v[104:107], v[140:143], v[156:159], v[104:107]
	v_mfma_f32_16x16x32_bf16 v[92:95], v[132:135], v[164:167], v[92:95]
	v_mfma_f32_16x16x32_bf16 v[88:91], v[140:143], v[164:167], v[88:91]
	s_waitcnt lgkmcnt(0)
	v_mfma_f32_16x16x32_bf16 v[76:79], v[132:135], v[172:175], v[76:79]
	v_mfma_f32_16x16x32_bf16 v[72:75], v[140:143], v[172:175], v[72:75]
	s_setprio 0
	s_barrier
	s_and_b32 s25, s18, 0xffff
	s_mov_b32 s26, s10
	s_mov_b32 s27, s11
	s_mov_b32 m0, s50
	ds_read_b128 v[176:179], v229
	ds_read_b128 v[180:183], v229 offset:1024
	ds_read_b128 v[192:195], v229 offset:2048
	ds_read_b128 v[196:199], v229 offset:3072
	buffer_load_dwordx4 v223, s[24:27], 0 offen lds
	s_mov_b32 m0, s51
	s_nop 0
	buffer_load_dwordx4 v225, s[24:27], 0 offen lds
	s_barrier
	s_waitcnt lgkmcnt(0)
	s_setprio 1
	s_waitcnt lgkmcnt(3)
	v_mfma_f32_16x16x32_bf16 v[116:119], v[176:179], v[144:147], 0
	s_waitcnt lgkmcnt(1)
	v_mfma_f32_16x16x32_bf16 v[112:115], v[192:195], v[144:147], 0
	v_mfma_f32_16x16x32_bf16 v[100:103], v[176:179], v[152:155], 0
	v_mfma_f32_16x16x32_bf16 v[96:99], v[192:195], v[152:155], 0
	v_mfma_f32_16x16x32_bf16 v[84:87], v[176:179], v[160:163], 0
	v_mfma_f32_16x16x32_bf16 v[80:83], v[192:195], v[160:163], 0
	v_mfma_f32_16x16x32_bf16 v[68:71], v[176:179], v[168:171], 0
	v_mfma_f32_16x16x32_bf16 v[64:67], v[192:195], v[168:171], 0
	v_mfma_f32_16x16x32_bf16 v[116:119], v[180:183], v[148:151], v[116:119]
	s_waitcnt lgkmcnt(0)
	v_mfma_f32_16x16x32_bf16 v[112:115], v[196:199], v[148:151], v[112:115]
	v_mfma_f32_16x16x32_bf16 v[100:103], v[180:183], v[156:159], v[100:103]
	v_mfma_f32_16x16x32_bf16 v[96:99], v[196:199], v[156:159], v[96:99]
	v_mfma_f32_16x16x32_bf16 v[84:87], v[180:183], v[164:167], v[84:87]
	v_mfma_f32_16x16x32_bf16 v[80:83], v[196:199], v[164:167], v[80:83]
	v_mfma_f32_16x16x32_bf16 v[68:71], v[180:183], v[172:175], v[68:71]
	v_mfma_f32_16x16x32_bf16 v[64:67], v[196:199], v[172:175], v[64:67]
	s_setprio 0
	s_and_b32 s29, s19, 0xffff
	s_mov_b32 s30, s10
	s_mov_b32 s31, s11
	s_mov_b32 m0, s49
	s_barrier
; #define PG8_STAGE(bufoff, gbase, voff) do { const __amdgpu_buffer_rsrc_t _r = __builtin_amdgcn_make_buffer_rsrc((void*)(gbase), (short)0, 0x7fffffff, 0x00020000); _Pragma("unroll") for (int _i = 0; _i < 2; ++_i) \
;         __builtin_amdgcn_raw_ptr_buffer_load_lds(_r, (LAS unsigned*)(lds + (bufoff) + ldsw + _i * 8192), 16, (int)(voff)[_i], 0, 0, 0); } while (0)
; #define PG8_LDA(dst, b, h) do { _Pragma("unroll") for (int m = 0; m < 4; ++m) _Pragma("unroll") for (int k = 0; k < 2; ++k) dst[m][k] = *(const LAS bf16x8*)(lds + PG8_SA(b, h) + aoff + m * 2048 + k * 1024); } while (0)
; #define PG8_LDB(dst, b, h) do { _Pragma("unroll") for (int n = 0; n < 2; ++n) _Pragma("unroll") for (int k = 0; k < 2; ++k) dst[n][k] = *(const LAS bf16x8*)(lds + PG8_SB(b, h) + boff + n * 2048 + k * 1024); } while (0)
; #define PG8_MMA(ai, bj, At, Bt) do { __builtin_amdgcn_s_setprio(1); _Pragma("unroll") for (int k = 0; k < 2; ++k) _Pragma("unroll") for (int m = 0; m < 4; ++m) _Pragma("unroll") for (int n = 0; n < ((bj) == 1 ? NB1 : 2); ++n) \
;         acc[ai][bj][m][n] = __builtin_amdgcn_mfma_f32_16x16x32_bf16(Bt[n][k], At[m][k], acc[ai][bj][m][n], 0, 0, 0); __builtin_amdgcn_s_setprio(0); } while (0)
; #define PG8_WAIT_V(n) asm volatile("s_waitcnt vmcnt(" #n ")" ::: "memory")
; #define PG8_WAIT_L(n) asm volatile("s_waitcnt lgkmcnt(" #n ")" ::: "memory")
; #define PG8_BAR __builtin_amdgcn_s_barrier()
; #define PG8_SCHED __builtin_amdgcn_sched_barrier(0)
;     ...
;             PG8_WAIT_V(6); PG8_BAR; PG8_MMA(1, 1, At, B1); PG8_BAR;
;             PG8_LDB(B0, 1, 0); PG8_SCHED; PG8_LDA(At, 1, 0); PG8_STAGE(PG8_SA(0, 1), a2 + hstepA, voffA);
;             PG8_WAIT_L(8); PG8_BAR; PG8_WAIT_L(0); PG8_MMA(0, 0, At, B0); PG8_BAR; PG8_SCHED;
;             PG8_LDB(B1, 1, 1); PG8_STAGE(PG8_SB(1, 0), b3, voffB);
;             PG8_BAR; PG8_WAIT_L(0); PG8_MMA(0, 1, At, B1); PG8_BAR;
;             PG8_LDA(At, 1, 1); PG8_STAGE(PG8_SA(1, 0), a3, voffA);
;             PG8_BAR; PG8_WAIT_L(0); PG8_MMA(1, 0, At, B0); PG8_BAR; PG8_SCHED;
;             PG8_STAGE(PG8_SB(1, 1), b3 + hstepB, voffB);
;             PG8_WAIT_V(6); PG8_BAR; PG8_MMA(1, 1, At, B1); PG8_BAR;
	ds_read_b128 v[144:147], v228 offset:16384
	ds_read_b128 v[148:151], v228 offset:17408
	ds_read_b128 v[152:155], v228 offset:18432
	ds_read_b128 v[156:159], v228 offset:19456
	ds_read_b128 v[160:163], v228 offset:20480
	ds_read_b128 v[164:167], v228 offset:21504
	ds_read_b128 v[168:171], v228 offset:22528
	ds_read_b128 v[172:175], v228 offset:23552
	buffer_load_dwordx4 v222, s[28:31], 0 offen lds
	s_mov_b32 m0, s52
	s_nop 0
	buffer_load_dwordx4 v224, s[28:31], 0 offen lds
	s_barrier
	s_waitcnt lgkmcnt(0)
	s_setprio 1
	s_waitcnt lgkmcnt(7)
	v_mfma_f32_16x16x32_bf16 v[60:63], v[128:131], v[144:147], 0
	v_mfma_f32_16x16x32_bf16 v[56:59], v[136:139], v[144:147], 0
	s_waitcnt lgkmcnt(5)
	v_mfma_f32_16x16x32_bf16 v[44:47], v[128:131], v[152:155], 0
	v_mfma_f32_16x16x32_bf16 v[40:43], v[136:139], v[152:155], 0
	s_waitcnt lgkmcnt(3)
	v_mfma_f32_16x16x32_bf16 v[28:31], v[128:131], v[160:163], 0
	v_mfma_f32_16x16x32_bf16 v[24:27], v[136:139], v[160:163], 0
	s_waitcnt lgkmcnt(1)
	v_mfma_f32_16x16x32_bf16 v[12:15], v[128:131], v[168:171], 0
	v_mfma_f32_16x16x32_bf16 v[8:11], v[136:139], v[168:171], 0
	v_mfma_f32_16x16x32_bf16 v[60:63], v[132:135], v[148:151], v[60:63]
	v_mfma_f32_16x16x32_bf16 v[56:59], v[140:143], v[148:151], v[56:59]
	v_mfma_f32_16x16x32_bf16 v[44:47], v[132:135], v[156:159], v[44:47]
	v_mfma_f32_16x16x32_bf16 v[40:43], v[140:143], v[156:159], v[40:43]
	v_mfma_f32_16x16x32_bf16 v[28:31], v[132:135], v[164:167], v[28:31]
	v_mfma_f32_16x16x32_bf16 v[24:27], v[140:143], v[164:167], v[24:27]
	s_waitcnt lgkmcnt(0)
	v_mfma_f32_16x16x32_bf16 v[12:15], v[132:135], v[172:175], v[12:15]
	v_mfma_f32_16x16x32_bf16 v[8:11], v[140:143], v[172:175], v[8:11]
	s_setprio 0
	s_barrier
	s_add_u32 s8, s24, s38
	s_addc_u32 s23, s18, s39
	s_and_b32 s9, s23, 0xffff
	s_mov_b32 m0, s53
	s_nop 0
	buffer_load_dwordx4 v223, s[8:11], 0 offen lds
	s_mov_b32 m0, s54
	s_nop 0
	buffer_load_dwordx4 v225, s[8:11], 0 offen lds
	s_waitcnt vmcnt(6)
	s_barrier
	s_setprio 1
	v_mfma_f32_16x16x32_bf16 v[52:55], v[176:179], v[144:147], 0
	v_mfma_f32_16x16x32_bf16 v[48:51], v[192:195], v[144:147], 0
	v_mfma_f32_16x16x32_bf16 v[36:39], v[176:179], v[152:155], 0
	v_mfma_f32_16x16x32_bf16 v[32:35], v[192:195], v[152:155], 0
	v_mfma_f32_16x16x32_bf16 v[20:23], v[176:179], v[160:163], 0
	v_mfma_f32_16x16x32_bf16 v[16:19], v[192:195], v[160:163], 0
	v_mfma_f32_16x16x32_bf16 v[4:7], v[176:179], v[168:171], 0
	v_mfma_f32_16x16x32_bf16 v[0:3], v[192:195], v[168:171], 0
	v_mfma_f32_16x16x32_bf16 v[52:55], v[180:183], v[148:151], v[52:55]
	v_mfma_f32_16x16x32_bf16 v[48:51], v[196:199], v[148:151], v[48:51]
	v_mfma_f32_16x16x32_bf16 v[36:39], v[180:183], v[156:159], v[36:39]
	v_mfma_f32_16x16x32_bf16 v[32:35], v[196:199], v[156:159], v[32:35]
	v_mfma_f32_16x16x32_bf16 v[20:23], v[180:183], v[164:167], v[20:23]
	v_mfma_f32_16x16x32_bf16 v[16:19], v[196:199], v[164:167], v[16:19]
	v_mfma_f32_16x16x32_bf16 v[4:7], v[180:183], v[172:175], v[4:7]
	v_mfma_f32_16x16x32_bf16 v[0:3], v[196:199], v[172:175], v[0:3]
	s_setprio 0
	s_barrier
	s_branch .Lkmid_1066
	.p2align 6
	s_nop 0
	s_nop 0

;     ...
; #pragma unroll
;         for (int a = 0; a < 2; ++a)
; #pragma unroll
;             for (int b = 0; b < 2; ++b)
; #pragma unroll
;                 for (int m = 0; m < 4; ++m)
; #pragma unroll
;                     for (int n = 0; n < 2; ++n) acc[a][b][m][n] = (f32x4){0.f, 0.f, 0.f, 0.f};
.LBB0_1118:
	s_endpgm
.Lkzero_1066:
	v_mov_b32_e32 v123, 0
	v_mov_b32_e32 v122, v123
	v_mov_b32_e32 v121, v123
	v_mov_b32_e32 v120, v123
	v_mov_b32_e32 v127, v123
	v_mov_b32_e32 v126, v123
	v_mov_b32_e32 v125, v123
	v_mov_b32_e32 v124, v123
	v_mov_b32_e32 v111, v123
	v_mov_b32_e32 v110, v123
	v_mov_b32_e32 v109, v123
	v_mov_b32_e32 v108, v123
	v_mov_b32_e32 v107, v123
	v_mov_b32_e32 v106, v123
	v_mov_b32_e32 v105, v123
	v_mov_b32_e32 v104, v123
	v_mov_b32_e32 v95, v123
	v_mov_b32_e32 v94, v123
	v_mov_b32_e32 v93, v123
	v_mov_b32_e32 v92, v123
	v_mov_b32_e32 v91, v123
	v_mov_b32_e32 v90, v123
	v_mov_b32_e32 v89, v123
	v_mov_b32_e32 v88, v123
	v_mov_b32_e32 v79, v123
	v_mov_b32_e32 v78, v123
	v_mov_b32_e32 v77, v123
	v_mov_b32_e32 v76, v123
	v_mov_b32_e32 v75, v123
	v_mov_b32_e32 v74, v123
	v_mov_b32_e32 v73, v123
	v_mov_b32_e32 v72, v123
	v_mov_b32_e32 v119, v123
	v_mov_b32_e32 v118, v123
	v_mov_b32_e32 v117, v123
	v_mov_b32_e32 v116, v123
	v_mov_b32_e32 v115, v123
	v_mov_b32_e32 v114, v123
	v_mov_b32_e32 v113, v123
	v_mov_b32_e32 v112, v123
	v_mov_b32_e32 v103, v123
	v_mov_b32_e32 v102, v123
	v_mov_b32_e32 v101, v123
	v_mov_b32_e32 v100, v123
	v_mov_b32_e32 v99, v123
	v_mov_b32_e32 v98, v123
	v_mov_b32_e32 v97, v123
	v_mov_b32_e32 v96, v123
	v_mov_b32_e32 v87, v123
	v_mov_b32_e32 v86, v123
	v_mov_b32_e32 v85, v123
	v_mov_b32_e32 v84, v123
	v_mov_b32_e32 v83, v123
	v_mov_b32_e32 v82, v123
	v_mov_b32_e32 v81, v123
	v_mov_b32_e32 v80, v123
	v_mov_b32_e32 v71, v123
	v_mov_b32_e32 v70, v123
	v_mov_b32_e32 v69, v123
	v_mov_b32_e32 v68, v123
	v_mov_b32_e32 v67, v123
	v_mov_b32_e32 v66, v123
	v_mov_b32_e32 v65, v123
	v_mov_b32_e32 v64, v123
	v_mov_b32_e32 v63, v123
	v_mov_b32_e32 v62, v123
	v_mov_b32_e32 v61, v123
	v_mov_b32_e32 v60, v123
	v_mov_b32_e32 v59, v123
	v_mov_b32_e32 v58, v123
	v_mov_b32_e32 v57, v123
	v_mov_b32_e32 v56, v123
	v_mov_b32_e32 v47, v123
	v_mov_b32_e32 v46, v123
	v_mov_b32_e32 v45, v123
	v_mov_b32_e32 v44, v123
	v_mov_b32_e32 v43, v123
	v_mov_b32_e32 v42, v123
	v_mov_b32_e32 v41, v123
	v_mov_b32_e32 v40, v123
	v_mov_b32_e32 v31, v123
	v_mov_b32_e32 v30, v123
	v_mov_b32_e32 v29, v123
	v_mov_b32_e32 v28, v123
	v_mov_b32_e32 v27, v123
	v_mov_b32_e32 v26, v123
	v_mov_b32_e32 v25, v123
	v_mov_b32_e32 v24, v123
	v_mov_b32_e32 v15, v123
	v_mov_b32_e32 v14, v123
	v_mov_b32_e32 v13, v123
	v_mov_b32_e32 v12, v123
	v_mov_b32_e32 v11, v123
	v_mov_b32_e32 v10, v123
	v_mov_b32_e32 v9, v123
	v_mov_b32_e32 v8, v123
	v_mov_b32_e32 v55, v123
	v_mov_b32_e32 v54, v123
	v_mov_b32_e32 v53, v123
	v_mov_b32_e32 v52, v123
	v_mov_b32_e32 v51, v123
	v_mov_b32_e32 v50, v123
	v_mov_b32_e32 v49, v123
	v_mov_b32_e32 v48, v123
	v_mov_b32_e32 v39, v123
	v_mov_b32_e32 v38, v123
	v_mov_b32_e32 v37, v123
	v_mov_b32_e32 v36, v123
	v_mov_b32_e32 v35, v123
	v_mov_b32_e32 v34, v123
	v_mov_b32_e32 v33, v123
	v_mov_b32_e32 v32, v123
	v_mov_b32_e32 v23, v123
	v_mov_b32_e32 v22, v123
	v_mov_b32_e32 v21, v123
	v_mov_b32_e32 v20, v123
	v_mov_b32_e32 v19, v123
	v_mov_b32_e32 v18, v123
	v_mov_b32_e32 v17, v123
	v_mov_b32_e32 v16, v123
	v_mov_b32_e32 v7, v123
	v_mov_b32_e32 v6, v123
	v_mov_b32_e32 v5, v123
	v_mov_b32_e32 v4, v123
	v_mov_b32_e32 v3, v123
	v_mov_b32_e32 v2, v123
	v_mov_b32_e32 v1, v123
	v_mov_b32_e32 v0, v123
	s_branch .LBB0_1067
